# operand bank alignment test on v102: the eight activation-fragment quads (MFMA srcB) moved from v214.. (start reg = 2 mod 4) to v212.. (0 mod 4), weight quad v210 moved to v244; accumulators and other
# speedup vs baseline: 1.0113x; 1.0009x over previous
; #define PG8_STAGE(bufoff, gbase, voff) do { _Pragma("unroll") for (int _i = 0; _i < 2; ++_i) \
;         __builtin_amdgcn_global_load_lds((const unsigned*)((const char*)(gbase) + (voff)[_i]), (PG8_LAS unsigned*)(lds + (bufoff) + ldsw + _i * 8192), 16, 0, 0); } while (0)
; #define PG8_LDA(dst, b, h) do { _Pragma("unroll") for (int m = 0; m < 4; ++m) _Pragma("unroll") for (int k = 0; k < 2; ++k) dst[m][k] = *(const PG8_LAS bf16x8*)(lds + PG8_SA(b, h) + aoff + m * 2048 + k * 1024); } while (0)
; #define PG8_LDB(dst, b, h) do { _Pragma("unroll") for (int n = 0; n < 2; ++n) _Pragma("unroll") for (int k = 0; k < 2; ++k) dst[n][k] = *(const PG8_LAS bf16x8*)(lds + PG8_SB(b, h) + boff + n * 2048 + k * 1024); } while (0)
; #define PG8_MMA(ai, bj, At, Bt) do { __builtin_amdgcn_s_setprio(1); _Pragma("unroll") for (int m = 0; m < 4; ++m) _Pragma("unroll") for (int n = 0; n < 2; ++n) _Pragma("unroll") for (int k = 0; k < 2; ++k) \
;         acc[ai][bj][m][n] = __builtin_amdgcn_mfma_f32_16x16x32_bf16(Bt[n][k], At[m][k], acc[ai][bj][m][n], 0, 0, 0); __builtin_amdgcn_s_setprio(0); } while (0)
; #define PG8_WAIT_V(n) asm volatile("s_waitcnt vmcnt(" #n ")" ::: "memory")
; #define PG8_WAIT_L(n) asm volatile("s_waitcnt lgkmcnt(" #n ")" ::: "memory")
; template <class Epi, class Sched, bool ALIGN_EPI = false, bool SP2 = false>
; __device__ __forceinline__ void gemm_phase(PG8_LAS unsigned char* lds, const Gemm g, const Sched& S, const Epi& E) {
;     ...
;             const bool last = (t == nt - 2);
;             const char* a1 = cA + (size_t)(t + 1) * kstep;
;             const char* a2 = last ? nA : cA + (size_t)(t + 2) * kstep; const char* b2 = last ? nB : cB + (size_t)(t + 2) * kstep;
;             const char* a3 = a2 + kstep; const char* b3 = b2 + kstep;
;             if (last && has_next) S.a_ready(nxt);
;             if constexpr (SP2) {
;             PG8_LDB(B0, 0, 0); PG8_LDB(B1, 0, 1); PG8_SCHED; PG8_LDA(At, 0, 0); PG8_STAGE(PG8_SA(1, 1), a1 + hstep, voffA);
;             PG8_WAIT_V(8); PG8_WAIT_L(0); PG8_BAR; PG8_MMA(0, 0, At, B0); PG8_MMA(0, 1, At, B1); PG8_BAR; PG8_SCHED;
;             PG8_LDA(At, 0, 1); PG8_STAGE(PG8_SB(0, 0), b2, voffB); PG8_STAGE(PG8_SB(0, 1), b2 + hstep, voffB); PG8_STAGE(PG8_SA(0, 0), a2, voffA);
;             PG8_WAIT_V(8); PG8_WAIT_L(0); PG8_BAR; PG8_MMA(1, 0, At, B0); PG8_MMA(1, 1, At, B1); PG8_BAR; PG8_SCHED;
.Labo_peel:
	ds_read_b128 v[68:71], v254
	ds_read_b128 v[72:75], v254 offset:1024
	ds_read_b128 v[76:79], v254 offset:2048
	ds_read_b128 v[80:83], v254 offset:3072
	ds_read_b128 v[174:177], v254 offset:16384
	ds_read_b128 v[182:185], v254 offset:17408
	ds_read_b128 v[186:189], v254 offset:18432
	ds_read_b128 v[244:247], v254 offset:19456
	s_add_u32 s2, s0, 0xfffc0080
	s_addc_u32 s3, s1, -1
	s_cmp_eq_u32 s56, 12
	s_cselect_b32 s5, s27, s3
	s_cselect_b32 s4, s52, s2
	s_cselect_b32 s3, s25, s55
	s_cselect_b32 s2, s53, s54
	s_add_i32 m0, s29, 0xc000
	ds_read_b128 v[212:215], v179
	ds_read_b128 v[216:219], v179 offset:1024
	ds_read_b128 v[220:223], v179 offset:2048
	ds_read_b128 v[224:227], v179 offset:3072
	ds_read_b128 v[228:231], v179 offset:4096
	ds_read_b128 v[232:235], v179 offset:5120
	ds_read_b128 v[236:239], v179 offset:6144
	ds_read_b128 v[240:243], v179 offset:7168
	global_load_lds_dwordx4 v170, s[0:1]
	s_add_i32 m0, s29, 0xe000
	s_nop 0
	global_load_lds_dwordx4 v172, s[0:1]
	s_waitcnt vmcnt(8)
	s_waitcnt lgkmcnt(0)
	s_barrier
	s_setprio 1
	v_mfma_f32_16x16x32_bf16 v[140:143], v[68:71], v[212:215], 0
	v_mfma_f32_16x16x32_bf16 v[140:143], v[72:75], v[216:219], v[140:143]
	v_mfma_f32_16x16x32_bf16 v[124:127], v[68:71], v[220:223], 0
	v_mfma_f32_16x16x32_bf16 v[124:127], v[72:75], v[224:227], v[124:127]
	v_mfma_f32_16x16x32_bf16 v[108:111], v[68:71], v[228:231], 0
	v_mfma_f32_16x16x32_bf16 v[108:111], v[72:75], v[232:235], v[108:111]
	v_mfma_f32_16x16x32_bf16 v[92:95], v[68:71], v[236:239], 0
	v_mfma_f32_16x16x32_bf16 v[92:95], v[72:75], v[240:243], v[92:95]
	v_mfma_f32_16x16x32_bf16 v[136:139], v[76:79], v[212:215], 0
	v_mfma_f32_16x16x32_bf16 v[136:139], v[80:83], v[216:219], v[136:139]
	v_mfma_f32_16x16x32_bf16 v[120:123], v[76:79], v[220:223], 0
	v_mfma_f32_16x16x32_bf16 v[120:123], v[80:83], v[224:227], v[120:123]
	v_mfma_f32_16x16x32_bf16 v[104:107], v[76:79], v[228:231], 0
	v_mfma_f32_16x16x32_bf16 v[104:107], v[80:83], v[232:235], v[104:107]
	v_mfma_f32_16x16x32_bf16 v[88:91], v[76:79], v[236:239], 0
	v_mfma_f32_16x16x32_bf16 v[88:91], v[80:83], v[240:243], v[88:91]
	v_mfma_f32_16x16x32_bf16 v[132:135], v[174:177], v[212:215], 0
	v_mfma_f32_16x16x32_bf16 v[132:135], v[182:185], v[216:219], v[132:135]
	v_mfma_f32_16x16x32_bf16 v[116:119], v[174:177], v[220:223], 0
	v_mfma_f32_16x16x32_bf16 v[116:119], v[182:185], v[224:227], v[116:119]
	v_mfma_f32_16x16x32_bf16 v[100:103], v[174:177], v[228:231], 0
	v_mfma_f32_16x16x32_bf16 v[100:103], v[182:185], v[232:235], v[100:103]
	v_mfma_f32_16x16x32_bf16 v[84:87], v[174:177], v[236:239], 0
	v_mfma_f32_16x16x32_bf16 v[84:87], v[182:185], v[240:243], v[84:87]
	v_mfma_f32_16x16x32_bf16 v[128:131], v[186:189], v[212:215], 0
	v_mfma_f32_16x16x32_bf16 v[128:131], v[244:247], v[216:219], v[128:131]
	v_mfma_f32_16x16x32_bf16 v[112:115], v[186:189], v[220:223], 0
	v_mfma_f32_16x16x32_bf16 v[112:115], v[244:247], v[224:227], v[112:115]
	v_mfma_f32_16x16x32_bf16 v[96:99], v[186:189], v[228:231], 0
	v_mfma_f32_16x16x32_bf16 v[96:99], v[244:247], v[232:235], v[96:99]
	v_mfma_f32_16x16x32_bf16 v[64:67], v[186:189], v[236:239], 0
	v_mfma_f32_16x16x32_bf16 v[64:67], v[244:247], v[240:243], v[64:67]
	s_setprio 0
	s_barrier
	s_mov_b32 m0, s30
	s_add_u32 s58, s2, 0x40000
	s_addc_u32 s59, s3, 0
	ds_read_b128 v[212:215], v179 offset:16384
	ds_read_b128 v[216:219], v179 offset:17408
	ds_read_b128 v[220:223], v179 offset:18432
	ds_read_b128 v[224:227], v179 offset:19456
	ds_read_b128 v[228:231], v179 offset:20480
	ds_read_b128 v[232:235], v179 offset:21504
	ds_read_b128 v[236:239], v179 offset:22528
	ds_read_b128 v[240:243], v179 offset:23552
	global_load_lds_dwordx4 v166, s[2:3]
	s_mov_b32 m0, s31
	s_nop 0
	global_load_lds_dwordx4 v162, s[2:3]
	s_mov_b32 m0, s33
	s_nop 0
	global_load_lds_dwordx4 v166, s[58:59]
	s_mov_b32 m0, s34
	s_nop 0
	global_load_lds_dwordx4 v162, s[58:59]
	s_mov_b32 m0, s29
	s_nop 0
	global_load_lds_dwordx4 v168, s[4:5]
	s_mov_b32 m0, s35
	s_nop 0
	global_load_lds_dwordx4 v164, s[4:5]
	s_waitcnt vmcnt(8)
	s_waitcnt lgkmcnt(0)
	s_barrier
	s_setprio 1
	v_mfma_f32_16x16x32_bf16 v[60:63], v[68:71], v[212:215], 0
	v_mfma_f32_16x16x32_bf16 v[60:63], v[72:75], v[216:219], v[60:63]
	v_mfma_f32_16x16x32_bf16 v[44:47], v[68:71], v[220:223], 0
	v_mfma_f32_16x16x32_bf16 v[44:47], v[72:75], v[224:227], v[44:47]
	v_mfma_f32_16x16x32_bf16 v[28:31], v[68:71], v[228:231], 0
	v_mfma_f32_16x16x32_bf16 v[28:31], v[72:75], v[232:235], v[28:31]
	v_mfma_f32_16x16x32_bf16 v[12:15], v[68:71], v[236:239], 0
	v_mfma_f32_16x16x32_bf16 v[12:15], v[72:75], v[240:243], v[12:15]
	v_mfma_f32_16x16x32_bf16 v[56:59], v[76:79], v[212:215], 0
	v_mfma_f32_16x16x32_bf16 v[56:59], v[80:83], v[216:219], v[56:59]
	v_mfma_f32_16x16x32_bf16 v[40:43], v[76:79], v[220:223], 0
	v_mfma_f32_16x16x32_bf16 v[40:43], v[80:83], v[224:227], v[40:43]
	v_mfma_f32_16x16x32_bf16 v[24:27], v[76:79], v[228:231], 0
	v_mfma_f32_16x16x32_bf16 v[24:27], v[80:83], v[232:235], v[24:27]
	v_mfma_f32_16x16x32_bf16 v[8:11], v[76:79], v[236:239], 0
	v_mfma_f32_16x16x32_bf16 v[8:11], v[80:83], v[240:243], v[8:11]
	v_mfma_f32_16x16x32_bf16 v[52:55], v[174:177], v[212:215], 0
	v_mfma_f32_16x16x32_bf16 v[52:55], v[182:185], v[216:219], v[52:55]
	v_mfma_f32_16x16x32_bf16 v[36:39], v[174:177], v[220:223], 0
	v_mfma_f32_16x16x32_bf16 v[36:39], v[182:185], v[224:227], v[36:39]
	v_mfma_f32_16x16x32_bf16 v[20:23], v[174:177], v[228:231], 0
	v_mfma_f32_16x16x32_bf16 v[20:23], v[182:185], v[232:235], v[20:23]
	v_mfma_f32_16x16x32_bf16 v[4:7], v[174:177], v[236:239], 0
	v_mfma_f32_16x16x32_bf16 v[4:7], v[182:185], v[240:243], v[4:7]
	v_mfma_f32_16x16x32_bf16 v[48:51], v[186:189], v[212:215], 0
	v_mfma_f32_16x16x32_bf16 v[48:51], v[244:247], v[216:219], v[48:51]
	v_mfma_f32_16x16x32_bf16 v[32:35], v[186:189], v[220:223], 0
	v_mfma_f32_16x16x32_bf16 v[32:35], v[244:247], v[224:227], v[32:35]
	v_mfma_f32_16x16x32_bf16 v[16:19], v[186:189], v[228:231], 0
	v_mfma_f32_16x16x32_bf16 v[16:19], v[244:247], v[232:235], v[16:19]
	v_mfma_f32_16x16x32_bf16 v[0:3], v[186:189], v[236:239], 0
	v_mfma_f32_16x16x32_bf16 v[0:3], v[244:247], v[240:243], v[0:3]
	s_setprio 0
	s_barrier
; #define PG8_STAGE(bufoff, gbase, voff) do { _Pragma("unroll") for (int _i = 0; _i < 2; ++_i) \
;         __builtin_amdgcn_global_load_lds((const unsigned*)((const char*)(gbase) + (voff)[_i]), (PG8_LAS unsigned*)(lds + (bufoff) + ldsw + _i * 8192), 16, 0, 0); } while (0)
; #define PG8_LDA(dst, b, h) do { _Pragma("unroll") for (int m = 0; m < 4; ++m) _Pragma("unroll") for (int k = 0; k < 2; ++k) dst[m][k] = *(const PG8_LAS bf16x8*)(lds + PG8_SA(b, h) + aoff + m * 2048 + k * 1024); } while (0)
; #define PG8_LDB(dst, b, h) do { _Pragma("unroll") for (int n = 0; n < 2; ++n) _Pragma("unroll") for (int k = 0; k < 2; ++k) dst[n][k] = *(const PG8_LAS bf16x8*)(lds + PG8_SB(b, h) + boff + n * 2048 + k * 1024); } while (0)
; #define PG8_MMA(ai, bj, At, Bt) do { __builtin_amdgcn_s_setprio(1); _Pragma("unroll") for (int m = 0; m < 4; ++m) _Pragma("unroll") for (int n = 0; n < 2; ++n) _Pragma("unroll") for (int k = 0; k < 2; ++k) \
;         acc[ai][bj][m][n] = __builtin_amdgcn_mfma_f32_16x16x32_bf16(Bt[n][k], At[m][k], acc[ai][bj][m][n], 0, 0, 0); __builtin_amdgcn_s_setprio(0); } while (0)
; #define PG8_WAIT_V(n) asm volatile("s_waitcnt vmcnt(" #n ")" ::: "memory")
; #define PG8_WAIT_L(n) asm volatile("s_waitcnt lgkmcnt(" #n ")" ::: "memory")
; #define PG8_BAR __builtin_amdgcn_s_barrier()
; #define PG8_SCHED __builtin_amdgcn_sched_barrier(0)
; template <class Epi, class Sched, bool ALIGN_EPI = false, bool SP2 = false>
; __device__ __forceinline__ void gemm_phase(PG8_LAS unsigned char* lds, const Gemm g, const Sched& S, const Epi& E) {
;     ...
;             PG8_LDB(B0, 1, 0); PG8_LDB(B1, 1, 1); PG8_SCHED; PG8_LDA(At, 1, 0); PG8_STAGE(PG8_SA(0, 1), a2 + hstep, voffA);
;             PG8_WAIT_V(8); PG8_WAIT_L(0); PG8_BAR; PG8_MMA(0, 0, At, B0); PG8_MMA(0, 1, At, B1); PG8_BAR; PG8_SCHED;
;             PG8_LDA(At, 1, 1); PG8_STAGE(PG8_SB(1, 0), b3, voffB); PG8_STAGE(PG8_SB(1, 1), b3 + hstep, voffB); PG8_STAGE(PG8_SA(1, 0), a3, voffA);
;             PG8_WAIT_V(8); PG8_WAIT_L(0); PG8_BAR; PG8_MMA(1, 0, At, B0); PG8_MMA(1, 1, At, B1); PG8_BAR; PG8_SCHED;
	ds_read_b128 v[68:71], v254 offset:32768
	ds_read_b128 v[72:75], v254 offset:33792
	ds_read_b128 v[76:79], v254 offset:34816
	ds_read_b128 v[80:83], v254 offset:35840
	ds_read_b128 v[174:177], v254 offset:49152
	ds_read_b128 v[182:185], v254 offset:50176
	ds_read_b128 v[186:189], v254 offset:51200
	ds_read_b128 v[244:247], v254 offset:52224
	s_add_u32 s4, s4, 0x40000
	s_addc_u32 s5, s5, 0
	s_mov_b32 m0, s40
	ds_read_b128 v[212:215], v179 offset:32768
	ds_read_b128 v[216:219], v179 offset:33792
	ds_read_b128 v[220:223], v179 offset:34816
	ds_read_b128 v[224:227], v179 offset:35840
	ds_read_b128 v[228:231], v179 offset:36864
	ds_read_b128 v[232:235], v179 offset:37888
	ds_read_b128 v[236:239], v179 offset:38912
	ds_read_b128 v[240:243], v179 offset:39936
	global_load_lds_dwordx4 v168, s[4:5]
	s_mov_b32 m0, s41
	s_nop 0
	global_load_lds_dwordx4 v164, s[4:5]
	s_waitcnt vmcnt(8)
	s_waitcnt lgkmcnt(0)
	s_barrier
	s_setprio 1
	v_mfma_f32_16x16x32_bf16 v[140:143], v[68:71], v[212:215], v[140:143]
	v_mfma_f32_16x16x32_bf16 v[140:143], v[72:75], v[216:219], v[140:143]
	v_mfma_f32_16x16x32_bf16 v[124:127], v[68:71], v[220:223], v[124:127]
	v_mfma_f32_16x16x32_bf16 v[124:127], v[72:75], v[224:227], v[124:127]
	v_mfma_f32_16x16x32_bf16 v[108:111], v[68:71], v[228:231], v[108:111]
	v_mfma_f32_16x16x32_bf16 v[108:111], v[72:75], v[232:235], v[108:111]
	v_mfma_f32_16x16x32_bf16 v[92:95], v[68:71], v[236:239], v[92:95]
	v_mfma_f32_16x16x32_bf16 v[92:95], v[72:75], v[240:243], v[92:95]
	v_mfma_f32_16x16x32_bf16 v[136:139], v[76:79], v[212:215], v[136:139]
	v_mfma_f32_16x16x32_bf16 v[136:139], v[80:83], v[216:219], v[136:139]
	v_mfma_f32_16x16x32_bf16 v[120:123], v[76:79], v[220:223], v[120:123]
	v_mfma_f32_16x16x32_bf16 v[120:123], v[80:83], v[224:227], v[120:123]
	v_mfma_f32_16x16x32_bf16 v[104:107], v[76:79], v[228:231], v[104:107]
	v_mfma_f32_16x16x32_bf16 v[104:107], v[80:83], v[232:235], v[104:107]
	v_mfma_f32_16x16x32_bf16 v[88:91], v[76:79], v[236:239], v[88:91]
	v_mfma_f32_16x16x32_bf16 v[88:91], v[80:83], v[240:243], v[88:91]
	v_mfma_f32_16x16x32_bf16 v[132:135], v[174:177], v[212:215], v[132:135]
	v_mfma_f32_16x16x32_bf16 v[132:135], v[182:185], v[216:219], v[132:135]
	v_mfma_f32_16x16x32_bf16 v[116:119], v[174:177], v[220:223], v[116:119]
	v_mfma_f32_16x16x32_bf16 v[116:119], v[182:185], v[224:227], v[116:119]
	v_mfma_f32_16x16x32_bf16 v[100:103], v[174:177], v[228:231], v[100:103]
	v_mfma_f32_16x16x32_bf16 v[100:103], v[182:185], v[232:235], v[100:103]
	v_mfma_f32_16x16x32_bf16 v[84:87], v[174:177], v[236:239], v[84:87]
	v_mfma_f32_16x16x32_bf16 v[84:87], v[182:185], v[240:243], v[84:87]
	v_mfma_f32_16x16x32_bf16 v[128:131], v[186:189], v[212:215], v[128:131]
	v_mfma_f32_16x16x32_bf16 v[128:131], v[244:247], v[216:219], v[128:131]
	v_mfma_f32_16x16x32_bf16 v[112:115], v[186:189], v[220:223], v[112:115]
	v_mfma_f32_16x16x32_bf16 v[112:115], v[244:247], v[224:227], v[112:115]
	v_mfma_f32_16x16x32_bf16 v[96:99], v[186:189], v[228:231], v[96:99]
	v_mfma_f32_16x16x32_bf16 v[96:99], v[244:247], v[232:235], v[96:99]
	v_mfma_f32_16x16x32_bf16 v[64:67], v[186:189], v[236:239], v[64:67]
	v_mfma_f32_16x16x32_bf16 v[64:67], v[244:247], v[240:243], v[64:67]
	s_setprio 0
	s_barrier
	s_mov_b32 m0, s45
	s_add_u32 s2, s2, 0x40080
	s_addc_u32 s3, s3, 0
	ds_read_b128 v[212:215], v179 offset:49152
	ds_read_b128 v[216:219], v179 offset:50176
	ds_read_b128 v[220:223], v179 offset:51200
	ds_read_b128 v[224:227], v179 offset:52224
	ds_read_b128 v[228:231], v179 offset:53248
	ds_read_b128 v[232:235], v179 offset:54272
	ds_read_b128 v[236:239], v179 offset:55296
	ds_read_b128 v[240:243], v179 offset:56320
	s_add_u32 s98, s2, 0xfffc0000
	s_addc_u32 s99, s3, -1
	global_load_lds_dwordx4 v166, s[98:99]
	s_mov_b32 m0, s46
	s_nop 0
	global_load_lds_dwordx4 v162, s[98:99]
	s_mov_b32 m0, s49
	s_nop 0
	global_load_lds_dwordx4 v166, s[2:3]
	s_mov_b32 m0, s50
	s_nop 0
	global_load_lds_dwordx4 v162, s[2:3]
	s_mov_b32 m0, s47
	s_nop 0
	s_add_u32 s100, s4, 0xfffc0080
	s_addc_u32 s101, s5, -1
	global_load_lds_dwordx4 v168, s[100:101]
	s_mov_b32 m0, s48
	s_nop 0
	global_load_lds_dwordx4 v164, s[100:101]
	s_waitcnt vmcnt(8)
	s_waitcnt lgkmcnt(0)
	s_barrier
	s_setprio 1
	v_mfma_f32_16x16x32_bf16 v[60:63], v[68:71], v[212:215], v[60:63]
	v_mfma_f32_16x16x32_bf16 v[60:63], v[72:75], v[216:219], v[60:63]
	v_mfma_f32_16x16x32_bf16 v[44:47], v[68:71], v[220:223], v[44:47]
	v_mfma_f32_16x16x32_bf16 v[44:47], v[72:75], v[224:227], v[44:47]
	v_mfma_f32_16x16x32_bf16 v[28:31], v[68:71], v[228:231], v[28:31]
	v_mfma_f32_16x16x32_bf16 v[28:31], v[72:75], v[232:235], v[28:31]
	v_mfma_f32_16x16x32_bf16 v[12:15], v[68:71], v[236:239], v[12:15]
	v_mfma_f32_16x16x32_bf16 v[12:15], v[72:75], v[240:243], v[12:15]
	v_mfma_f32_16x16x32_bf16 v[56:59], v[76:79], v[212:215], v[56:59]
	v_mfma_f32_16x16x32_bf16 v[56:59], v[80:83], v[216:219], v[56:59]
	v_mfma_f32_16x16x32_bf16 v[40:43], v[76:79], v[220:223], v[40:43]
	v_mfma_f32_16x16x32_bf16 v[40:43], v[80:83], v[224:227], v[40:43]
	v_mfma_f32_16x16x32_bf16 v[24:27], v[76:79], v[228:231], v[24:27]
	v_mfma_f32_16x16x32_bf16 v[24:27], v[80:83], v[232:235], v[24:27]
	v_mfma_f32_16x16x32_bf16 v[8:11], v[76:79], v[236:239], v[8:11]
	v_mfma_f32_16x16x32_bf16 v[8:11], v[80:83], v[240:243], v[8:11]
	v_mfma_f32_16x16x32_bf16 v[52:55], v[174:177], v[212:215], v[52:55]
	v_mfma_f32_16x16x32_bf16 v[52:55], v[182:185], v[216:219], v[52:55]
	v_mfma_f32_16x16x32_bf16 v[36:39], v[174:177], v[220:223], v[36:39]
	v_mfma_f32_16x16x32_bf16 v[36:39], v[182:185], v[224:227], v[36:39]
	v_mfma_f32_16x16x32_bf16 v[20:23], v[174:177], v[228:231], v[20:23]
	v_mfma_f32_16x16x32_bf16 v[20:23], v[182:185], v[232:235], v[20:23]
	v_mfma_f32_16x16x32_bf16 v[4:7], v[174:177], v[236:239], v[4:7]
	v_mfma_f32_16x16x32_bf16 v[4:7], v[182:185], v[240:243], v[4:7]
	v_mfma_f32_16x16x32_bf16 v[48:51], v[186:189], v[212:215], v[48:51]
	v_mfma_f32_16x16x32_bf16 v[48:51], v[244:247], v[216:219], v[48:51]
	v_mfma_f32_16x16x32_bf16 v[32:35], v[186:189], v[220:223], v[32:35]
	v_mfma_f32_16x16x32_bf16 v[32:35], v[244:247], v[224:227], v[32:35]
	v_mfma_f32_16x16x32_bf16 v[16:19], v[186:189], v[228:231], v[16:19]
	v_mfma_f32_16x16x32_bf16 v[16:19], v[244:247], v[232:235], v[16:19]
	v_mfma_f32_16x16x32_bf16 v[0:3], v[186:189], v[236:239], v[0:3]
	v_mfma_f32_16x16x32_bf16 v[0:3], v[244:247], v[240:243], v[0:3]
	s_setprio 0
	s_barrier
	s_add_i32 s56, s56, 2
	s_add_u32 s0, s0, 0x100
	s_addc_u32 s1, s1, 0
	s_add_u32 s54, s54, 0x100
	s_addc_u32 s55, s55, 0
	s_cmp_gt_u32 s56, 13
; #define PG8_STAGE(bufoff, gbase, voff) do { _Pragma("unroll") for (int _i = 0; _i < 2; ++_i) \
;         __builtin_amdgcn_global_load_lds((const unsigned*)((const char*)(gbase) + (voff)[_i]), (PG8_LAS unsigned*)(lds + (bufoff) + ldsw + _i * 8192), 16, 0, 0); } while (0)
; #define PG8_LDA(dst, b, h) do { _Pragma("unroll") for (int m = 0; m < 4; ++m) _Pragma("unroll") for (int k = 0; k < 2; ++k) dst[m][k] = *(const PG8_LAS bf16x8*)(lds + PG8_SA(b, h) + aoff + m * 2048 + k * 1024); } while (0)
; #define PG8_LDB(dst, b, h) do { _Pragma("unroll") for (int n = 0; n < 2; ++n) _Pragma("unroll") for (int k = 0; k < 2; ++k) dst[n][k] = *(const PG8_LAS bf16x8*)(lds + PG8_SB(b, h) + boff + n * 2048 + k * 1024); } while (0)
; #define PG8_MMA(ai, bj, At, Bt) do { __builtin_amdgcn_s_setprio(1); _Pragma("unroll") for (int m = 0; m < 4; ++m) _Pragma("unroll") for (int n = 0; n < 2; ++n) _Pragma("unroll") for (int k = 0; k < 2; ++k) \
;         acc[ai][bj][m][n] = __builtin_amdgcn_mfma_f32_16x16x32_bf16(Bt[n][k], At[m][k], acc[ai][bj][m][n], 0, 0, 0); __builtin_amdgcn_s_setprio(0); } while (0)
; #define PG8_WAIT_V(n) asm volatile("s_waitcnt vmcnt(" #n ")" ::: "memory")
; #define PG8_WAIT_L(n) asm volatile("s_waitcnt lgkmcnt(" #n ")" ::: "memory")
; #define PG8_BAR __builtin_amdgcn_s_barrier()
; #define PG8_SCHED __builtin_amdgcn_sched_barrier(0)
; template <class Epi, class Sched, bool ALIGN_EPI = false, bool SP2 = false>
; __device__ __forceinline__ void gemm_phase(PG8_LAS unsigned char* lds, const Gemm g, const Sched& S, const Epi& E) {
;     ...
;             PG8_LDB(B0, 0, 0); PG8_LDB(B1, 0, 1); PG8_SCHED; PG8_LDA(At, 0, 0); PG8_STAGE(PG8_SA(1, 1), a1 + hstep, voffA);
;             PG8_WAIT_V(8); PG8_WAIT_L(0); PG8_BAR; PG8_MMA(0, 0, At, B0); PG8_MMA(0, 1, At, B1); PG8_BAR; PG8_SCHED;
;             PG8_LDA(At, 0, 1); PG8_STAGE(PG8_SB(0, 0), b2, voffB); PG8_STAGE(PG8_SB(0, 1), b2 + hstep, voffB); PG8_STAGE(PG8_SA(0, 0), a2, voffA);
;             PG8_WAIT_V(8); PG8_WAIT_L(0); PG8_BAR; PG8_MMA(1, 0, At, B0); PG8_MMA(1, 1, At, B1); PG8_BAR; PG8_SCHED;
.LBB0_327:
	ds_read_b128 v[68:71], v254
	ds_read_b128 v[72:75], v254 offset:1024
	ds_read_b128 v[76:79], v254 offset:2048
	ds_read_b128 v[80:83], v254 offset:3072
	ds_read_b128 v[174:177], v254 offset:16384
	ds_read_b128 v[182:185], v254 offset:17408
	ds_read_b128 v[186:189], v254 offset:18432
	ds_read_b128 v[244:247], v254 offset:19456
	s_add_u32 s2, s0, 0xfffc0080
	s_addc_u32 s3, s1, -1
	s_cmp_eq_u32 s56, 12
	s_cselect_b32 s5, s27, s3
	s_cselect_b32 s4, s52, s2
	s_cselect_b32 s3, s25, s55
	s_cselect_b32 s2, s53, s54
	s_add_i32 m0, s29, 0xc000
	ds_read_b128 v[212:215], v179
	ds_read_b128 v[216:219], v179 offset:1024
	ds_read_b128 v[220:223], v179 offset:2048
	ds_read_b128 v[224:227], v179 offset:3072
	ds_read_b128 v[228:231], v179 offset:4096
	ds_read_b128 v[232:235], v179 offset:5120
	ds_read_b128 v[236:239], v179 offset:6144
	ds_read_b128 v[240:243], v179 offset:7168
	global_load_lds_dwordx4 v170, s[0:1]
	s_add_i32 m0, s29, 0xe000
	s_nop 0
	global_load_lds_dwordx4 v172, s[0:1]
	s_waitcnt vmcnt(8)
	s_waitcnt lgkmcnt(0)
	s_barrier
	s_setprio 1
	v_mfma_f32_16x16x32_bf16 v[140:143], v[68:71], v[212:215], v[140:143]
	v_mfma_f32_16x16x32_bf16 v[140:143], v[72:75], v[216:219], v[140:143]
	v_mfma_f32_16x16x32_bf16 v[124:127], v[68:71], v[220:223], v[124:127]
	v_mfma_f32_16x16x32_bf16 v[124:127], v[72:75], v[224:227], v[124:127]
	v_mfma_f32_16x16x32_bf16 v[108:111], v[68:71], v[228:231], v[108:111]
	v_mfma_f32_16x16x32_bf16 v[108:111], v[72:75], v[232:235], v[108:111]
	v_mfma_f32_16x16x32_bf16 v[92:95], v[68:71], v[236:239], v[92:95]
	v_mfma_f32_16x16x32_bf16 v[92:95], v[72:75], v[240:243], v[92:95]
	v_mfma_f32_16x16x32_bf16 v[136:139], v[76:79], v[212:215], v[136:139]
	v_mfma_f32_16x16x32_bf16 v[136:139], v[80:83], v[216:219], v[136:139]
	v_mfma_f32_16x16x32_bf16 v[120:123], v[76:79], v[220:223], v[120:123]
	v_mfma_f32_16x16x32_bf16 v[120:123], v[80:83], v[224:227], v[120:123]
	v_mfma_f32_16x16x32_bf16 v[104:107], v[76:79], v[228:231], v[104:107]
	v_mfma_f32_16x16x32_bf16 v[104:107], v[80:83], v[232:235], v[104:107]
	v_mfma_f32_16x16x32_bf16 v[88:91], v[76:79], v[236:239], v[88:91]
	v_mfma_f32_16x16x32_bf16 v[88:91], v[80:83], v[240:243], v[88:91]
	v_mfma_f32_16x16x32_bf16 v[132:135], v[174:177], v[212:215], v[132:135]
	v_mfma_f32_16x16x32_bf16 v[132:135], v[182:185], v[216:219], v[132:135]
	v_mfma_f32_16x16x32_bf16 v[116:119], v[174:177], v[220:223], v[116:119]
	v_mfma_f32_16x16x32_bf16 v[116:119], v[182:185], v[224:227], v[116:119]
	v_mfma_f32_16x16x32_bf16 v[100:103], v[174:177], v[228:231], v[100:103]
	v_mfma_f32_16x16x32_bf16 v[100:103], v[182:185], v[232:235], v[100:103]
	v_mfma_f32_16x16x32_bf16 v[84:87], v[174:177], v[236:239], v[84:87]
	v_mfma_f32_16x16x32_bf16 v[84:87], v[182:185], v[240:243], v[84:87]
	v_mfma_f32_16x16x32_bf16 v[128:131], v[186:189], v[212:215], v[128:131]
	v_mfma_f32_16x16x32_bf16 v[128:131], v[244:247], v[216:219], v[128:131]
	v_mfma_f32_16x16x32_bf16 v[112:115], v[186:189], v[220:223], v[112:115]
	v_mfma_f32_16x16x32_bf16 v[112:115], v[244:247], v[224:227], v[112:115]
	v_mfma_f32_16x16x32_bf16 v[96:99], v[186:189], v[228:231], v[96:99]
	v_mfma_f32_16x16x32_bf16 v[96:99], v[244:247], v[232:235], v[96:99]
	v_mfma_f32_16x16x32_bf16 v[64:67], v[186:189], v[236:239], v[64:67]
	v_mfma_f32_16x16x32_bf16 v[64:67], v[244:247], v[240:243], v[64:67]
	s_setprio 0
	s_barrier
	s_mov_b32 m0, s30
	s_add_u32 s58, s2, 0x40000
	s_addc_u32 s59, s3, 0
	ds_read_b128 v[212:215], v179 offset:16384
	ds_read_b128 v[216:219], v179 offset:17408
	ds_read_b128 v[220:223], v179 offset:18432
	ds_read_b128 v[224:227], v179 offset:19456
	ds_read_b128 v[228:231], v179 offset:20480
	ds_read_b128 v[232:235], v179 offset:21504
	ds_read_b128 v[236:239], v179 offset:22528
	ds_read_b128 v[240:243], v179 offset:23552
	global_load_lds_dwordx4 v166, s[2:3]
	s_mov_b32 m0, s31
	s_nop 0
	global_load_lds_dwordx4 v162, s[2:3]
	s_mov_b32 m0, s33
	s_nop 0
	global_load_lds_dwordx4 v166, s[58:59]
	s_mov_b32 m0, s34
	s_nop 0
	global_load_lds_dwordx4 v162, s[58:59]
	s_mov_b32 m0, s29
	s_nop 0
	global_load_lds_dwordx4 v168, s[4:5]
	s_mov_b32 m0, s35
	s_nop 0
	global_load_lds_dwordx4 v164, s[4:5]
	s_waitcnt vmcnt(8)
	s_waitcnt lgkmcnt(0)
	s_barrier
	s_setprio 1
	v_mfma_f32_16x16x32_bf16 v[60:63], v[68:71], v[212:215], v[60:63]
	v_mfma_f32_16x16x32_bf16 v[60:63], v[72:75], v[216:219], v[60:63]
	v_mfma_f32_16x16x32_bf16 v[44:47], v[68:71], v[220:223], v[44:47]
	v_mfma_f32_16x16x32_bf16 v[44:47], v[72:75], v[224:227], v[44:47]
	v_mfma_f32_16x16x32_bf16 v[28:31], v[68:71], v[228:231], v[28:31]
	v_mfma_f32_16x16x32_bf16 v[28:31], v[72:75], v[232:235], v[28:31]
	v_mfma_f32_16x16x32_bf16 v[12:15], v[68:71], v[236:239], v[12:15]
	v_mfma_f32_16x16x32_bf16 v[12:15], v[72:75], v[240:243], v[12:15]
	v_mfma_f32_16x16x32_bf16 v[56:59], v[76:79], v[212:215], v[56:59]
	v_mfma_f32_16x16x32_bf16 v[56:59], v[80:83], v[216:219], v[56:59]
	v_mfma_f32_16x16x32_bf16 v[40:43], v[76:79], v[220:223], v[40:43]
	v_mfma_f32_16x16x32_bf16 v[40:43], v[80:83], v[224:227], v[40:43]
	v_mfma_f32_16x16x32_bf16 v[24:27], v[76:79], v[228:231], v[24:27]
	v_mfma_f32_16x16x32_bf16 v[24:27], v[80:83], v[232:235], v[24:27]
	v_mfma_f32_16x16x32_bf16 v[8:11], v[76:79], v[236:239], v[8:11]
	v_mfma_f32_16x16x32_bf16 v[8:11], v[80:83], v[240:243], v[8:11]
	v_mfma_f32_16x16x32_bf16 v[52:55], v[174:177], v[212:215], v[52:55]
	v_mfma_f32_16x16x32_bf16 v[52:55], v[182:185], v[216:219], v[52:55]
	v_mfma_f32_16x16x32_bf16 v[36:39], v[174:177], v[220:223], v[36:39]
	v_mfma_f32_16x16x32_bf16 v[36:39], v[182:185], v[224:227], v[36:39]
	v_mfma_f32_16x16x32_bf16 v[20:23], v[174:177], v[228:231], v[20:23]
	v_mfma_f32_16x16x32_bf16 v[20:23], v[182:185], v[232:235], v[20:23]
	v_mfma_f32_16x16x32_bf16 v[4:7], v[174:177], v[236:239], v[4:7]
	v_mfma_f32_16x16x32_bf16 v[4:7], v[182:185], v[240:243], v[4:7]
	v_mfma_f32_16x16x32_bf16 v[48:51], v[186:189], v[212:215], v[48:51]
	v_mfma_f32_16x16x32_bf16 v[48:51], v[244:247], v[216:219], v[48:51]
	v_mfma_f32_16x16x32_bf16 v[32:35], v[186:189], v[220:223], v[32:35]
	v_mfma_f32_16x16x32_bf16 v[32:35], v[244:247], v[224:227], v[32:35]
	v_mfma_f32_16x16x32_bf16 v[16:19], v[186:189], v[228:231], v[16:19]
	v_mfma_f32_16x16x32_bf16 v[16:19], v[244:247], v[232:235], v[16:19]
	v_mfma_f32_16x16x32_bf16 v[0:3], v[186:189], v[236:239], v[0:3]
	v_mfma_f32_16x16x32_bf16 v[0:3], v[244:247], v[240:243], v[0:3]
	s_setprio 0
	s_barrier
; #define PG8_STAGE(bufoff, gbase, voff) do { _Pragma("unroll") for (int _i = 0; _i < 2; ++_i) \
;         __builtin_amdgcn_global_load_lds((const unsigned*)((const char*)(gbase) + (voff)[_i]), (PG8_LAS unsigned*)(lds + (bufoff) + ldsw + _i * 8192), 16, 0, 0); } while (0)
; #define PG8_LDA(dst, b, h) do { _Pragma("unroll") for (int m = 0; m < 4; ++m) _Pragma("unroll") for (int k = 0; k < 2; ++k) dst[m][k] = *(const PG8_LAS bf16x8*)(lds + PG8_SA(b, h) + aoff + m * 2048 + k * 1024); } while (0)
; #define PG8_LDB(dst, b, h) do { _Pragma("unroll") for (int n = 0; n < 2; ++n) _Pragma("unroll") for (int k = 0; k < 2; ++k) dst[n][k] = *(const PG8_LAS bf16x8*)(lds + PG8_SB(b, h) + boff + n * 2048 + k * 1024); } while (0)
; #define PG8_MMA(ai, bj, At, Bt) do { __builtin_amdgcn_s_setprio(1); _Pragma("unroll") for (int m = 0; m < 4; ++m) _Pragma("unroll") for (int n = 0; n < 2; ++n) _Pragma("unroll") for (int k = 0; k < 2; ++k) \
;         acc[ai][bj][m][n] = __builtin_amdgcn_mfma_f32_16x16x32_bf16(Bt[n][k], At[m][k], acc[ai][bj][m][n], 0, 0, 0); __builtin_amdgcn_s_setprio(0); } while (0)
; #define PG8_WAIT_V(n) asm volatile("s_waitcnt vmcnt(" #n ")" ::: "memory")
; #define PG8_WAIT_L(n) asm volatile("s_waitcnt lgkmcnt(" #n ")" ::: "memory")
; template <class Epi, class Sched, bool ALIGN_EPI = false, bool SP2 = false>
; __device__ __forceinline__ void gemm_phase(PG8_LAS unsigned char* lds, const Gemm g, const Sched& S, const Epi& E) {
;     ...
;         for (int t = 0; t < nt; t += 2) {
;             const bool last = (t == nt - 2);
;             const char* a1 = cA + (size_t)(t + 1) * kstep;
;             const char* a2 = last ? nA : cA + (size_t)(t + 2) * kstep; const char* b2 = last ? nB : cB + (size_t)(t + 2) * kstep;
;             const char* a3 = a2 + kstep; const char* b3 = b2 + kstep;
;             if (last && has_next) S.a_ready(nxt);
;     ...
;             PG8_LDB(B0, 1, 0); PG8_LDB(B1, 1, 1); PG8_SCHED; PG8_LDA(At, 1, 0); PG8_STAGE(PG8_SA(0, 1), a2 + hstep, voffA);
;             PG8_WAIT_V(8); PG8_WAIT_L(0); PG8_BAR; PG8_MMA(0, 0, At, B0); PG8_MMA(0, 1, At, B1); PG8_BAR; PG8_SCHED;
;             PG8_LDA(At, 1, 1); PG8_STAGE(PG8_SB(1, 0), b3, voffB); PG8_STAGE(PG8_SB(1, 1), b3 + hstep, voffB); PG8_STAGE(PG8_SA(1, 0), a3, voffA);
;             PG8_WAIT_V(8); PG8_WAIT_L(0); PG8_BAR; PG8_MMA(1, 0, At, B0); PG8_MMA(1, 1, At, B1); PG8_BAR; PG8_SCHED;
	ds_read_b128 v[68:71], v254 offset:32768
	ds_read_b128 v[72:75], v254 offset:33792
	ds_read_b128 v[76:79], v254 offset:34816
	ds_read_b128 v[80:83], v254 offset:35840
	ds_read_b128 v[174:177], v254 offset:49152
	ds_read_b128 v[182:185], v254 offset:50176
	ds_read_b128 v[186:189], v254 offset:51200
	ds_read_b128 v[244:247], v254 offset:52224
	s_add_u32 s4, s4, 0x40000
	s_addc_u32 s5, s5, 0
	s_mov_b32 m0, s40
	ds_read_b128 v[212:215], v179 offset:32768
	ds_read_b128 v[216:219], v179 offset:33792
	ds_read_b128 v[220:223], v179 offset:34816
	ds_read_b128 v[224:227], v179 offset:35840
	ds_read_b128 v[228:231], v179 offset:36864
	ds_read_b128 v[232:235], v179 offset:37888
	ds_read_b128 v[236:239], v179 offset:38912
	ds_read_b128 v[240:243], v179 offset:39936
	global_load_lds_dwordx4 v168, s[4:5]
	s_mov_b32 m0, s41
	s_nop 0
	global_load_lds_dwordx4 v164, s[4:5]
	s_waitcnt vmcnt(8)
	s_waitcnt lgkmcnt(0)
	s_barrier
	s_setprio 1
	v_mfma_f32_16x16x32_bf16 v[140:143], v[68:71], v[212:215], v[140:143]
	v_mfma_f32_16x16x32_bf16 v[140:143], v[72:75], v[216:219], v[140:143]
	v_mfma_f32_16x16x32_bf16 v[124:127], v[68:71], v[220:223], v[124:127]
	v_mfma_f32_16x16x32_bf16 v[124:127], v[72:75], v[224:227], v[124:127]
	v_mfma_f32_16x16x32_bf16 v[108:111], v[68:71], v[228:231], v[108:111]
	v_mfma_f32_16x16x32_bf16 v[108:111], v[72:75], v[232:235], v[108:111]
	v_mfma_f32_16x16x32_bf16 v[92:95], v[68:71], v[236:239], v[92:95]
	v_mfma_f32_16x16x32_bf16 v[92:95], v[72:75], v[240:243], v[92:95]
	v_mfma_f32_16x16x32_bf16 v[136:139], v[76:79], v[212:215], v[136:139]
	v_mfma_f32_16x16x32_bf16 v[136:139], v[80:83], v[216:219], v[136:139]
	v_mfma_f32_16x16x32_bf16 v[120:123], v[76:79], v[220:223], v[120:123]
	v_mfma_f32_16x16x32_bf16 v[120:123], v[80:83], v[224:227], v[120:123]
	v_mfma_f32_16x16x32_bf16 v[104:107], v[76:79], v[228:231], v[104:107]
	v_mfma_f32_16x16x32_bf16 v[104:107], v[80:83], v[232:235], v[104:107]
	v_mfma_f32_16x16x32_bf16 v[88:91], v[76:79], v[236:239], v[88:91]
	v_mfma_f32_16x16x32_bf16 v[88:91], v[80:83], v[240:243], v[88:91]
	v_mfma_f32_16x16x32_bf16 v[132:135], v[174:177], v[212:215], v[132:135]
	v_mfma_f32_16x16x32_bf16 v[132:135], v[182:185], v[216:219], v[132:135]
	v_mfma_f32_16x16x32_bf16 v[116:119], v[174:177], v[220:223], v[116:119]
	v_mfma_f32_16x16x32_bf16 v[116:119], v[182:185], v[224:227], v[116:119]
	v_mfma_f32_16x16x32_bf16 v[100:103], v[174:177], v[228:231], v[100:103]
	v_mfma_f32_16x16x32_bf16 v[100:103], v[182:185], v[232:235], v[100:103]
	v_mfma_f32_16x16x32_bf16 v[84:87], v[174:177], v[236:239], v[84:87]
	v_mfma_f32_16x16x32_bf16 v[84:87], v[182:185], v[240:243], v[84:87]
	v_mfma_f32_16x16x32_bf16 v[128:131], v[186:189], v[212:215], v[128:131]
	v_mfma_f32_16x16x32_bf16 v[128:131], v[244:247], v[216:219], v[128:131]
	v_mfma_f32_16x16x32_bf16 v[112:115], v[186:189], v[220:223], v[112:115]
	v_mfma_f32_16x16x32_bf16 v[112:115], v[244:247], v[224:227], v[112:115]
	v_mfma_f32_16x16x32_bf16 v[96:99], v[186:189], v[228:231], v[96:99]
	v_mfma_f32_16x16x32_bf16 v[96:99], v[244:247], v[232:235], v[96:99]
	v_mfma_f32_16x16x32_bf16 v[64:67], v[186:189], v[236:239], v[64:67]
	v_mfma_f32_16x16x32_bf16 v[64:67], v[244:247], v[240:243], v[64:67]
	s_setprio 0
	s_barrier
	s_mov_b32 m0, s45
	s_add_u32 s2, s2, 0x40080
	s_addc_u32 s3, s3, 0
	ds_read_b128 v[212:215], v179 offset:49152
	ds_read_b128 v[216:219], v179 offset:50176
	ds_read_b128 v[220:223], v179 offset:51200
	ds_read_b128 v[224:227], v179 offset:52224
	ds_read_b128 v[228:231], v179 offset:53248
	ds_read_b128 v[232:235], v179 offset:54272
	ds_read_b128 v[236:239], v179 offset:55296
	ds_read_b128 v[240:243], v179 offset:56320
	s_add_u32 s98, s2, 0xfffc0000
	s_addc_u32 s99, s3, -1
	global_load_lds_dwordx4 v166, s[98:99]
	s_mov_b32 m0, s46
	s_nop 0
	global_load_lds_dwordx4 v162, s[98:99]
	s_mov_b32 m0, s49
	s_nop 0
	global_load_lds_dwordx4 v166, s[2:3]
	s_mov_b32 m0, s50
	s_nop 0
	global_load_lds_dwordx4 v162, s[2:3]
	s_mov_b32 m0, s47
	s_nop 0
	s_add_u32 s100, s4, 0xfffc0080
	s_addc_u32 s101, s5, -1
	global_load_lds_dwordx4 v168, s[100:101]
	s_mov_b32 m0, s48
	s_nop 0
	global_load_lds_dwordx4 v164, s[100:101]
	s_waitcnt vmcnt(8)
	s_waitcnt lgkmcnt(0)
	s_barrier
	s_setprio 1
	v_mfma_f32_16x16x32_bf16 v[60:63], v[68:71], v[212:215], v[60:63]
	v_mfma_f32_16x16x32_bf16 v[60:63], v[72:75], v[216:219], v[60:63]
	v_mfma_f32_16x16x32_bf16 v[44:47], v[68:71], v[220:223], v[44:47]
	v_mfma_f32_16x16x32_bf16 v[44:47], v[72:75], v[224:227], v[44:47]
	v_mfma_f32_16x16x32_bf16 v[28:31], v[68:71], v[228:231], v[28:31]
	v_mfma_f32_16x16x32_bf16 v[28:31], v[72:75], v[232:235], v[28:31]
	v_mfma_f32_16x16x32_bf16 v[12:15], v[68:71], v[236:239], v[12:15]
	v_mfma_f32_16x16x32_bf16 v[12:15], v[72:75], v[240:243], v[12:15]
	v_mfma_f32_16x16x32_bf16 v[56:59], v[76:79], v[212:215], v[56:59]
	v_mfma_f32_16x16x32_bf16 v[56:59], v[80:83], v[216:219], v[56:59]
	v_mfma_f32_16x16x32_bf16 v[40:43], v[76:79], v[220:223], v[40:43]
	v_mfma_f32_16x16x32_bf16 v[40:43], v[80:83], v[224:227], v[40:43]
	v_mfma_f32_16x16x32_bf16 v[24:27], v[76:79], v[228:231], v[24:27]
	v_mfma_f32_16x16x32_bf16 v[24:27], v[80:83], v[232:235], v[24:27]
	v_mfma_f32_16x16x32_bf16 v[8:11], v[76:79], v[236:239], v[8:11]
	v_mfma_f32_16x16x32_bf16 v[8:11], v[80:83], v[240:243], v[8:11]
	v_mfma_f32_16x16x32_bf16 v[52:55], v[174:177], v[212:215], v[52:55]
	v_mfma_f32_16x16x32_bf16 v[52:55], v[182:185], v[216:219], v[52:55]
	v_mfma_f32_16x16x32_bf16 v[36:39], v[174:177], v[220:223], v[36:39]
	v_mfma_f32_16x16x32_bf16 v[36:39], v[182:185], v[224:227], v[36:39]
	v_mfma_f32_16x16x32_bf16 v[20:23], v[174:177], v[228:231], v[20:23]
	v_mfma_f32_16x16x32_bf16 v[20:23], v[182:185], v[232:235], v[20:23]
	v_mfma_f32_16x16x32_bf16 v[4:7], v[174:177], v[236:239], v[4:7]
	v_mfma_f32_16x16x32_bf16 v[4:7], v[182:185], v[240:243], v[4:7]
	v_mfma_f32_16x16x32_bf16 v[48:51], v[186:189], v[212:215], v[48:51]
	v_mfma_f32_16x16x32_bf16 v[48:51], v[244:247], v[216:219], v[48:51]
	v_mfma_f32_16x16x32_bf16 v[32:35], v[186:189], v[220:223], v[32:35]
	v_mfma_f32_16x16x32_bf16 v[32:35], v[244:247], v[224:227], v[32:35]
	v_mfma_f32_16x16x32_bf16 v[16:19], v[186:189], v[228:231], v[16:19]
	v_mfma_f32_16x16x32_bf16 v[16:19], v[244:247], v[232:235], v[16:19]
	v_mfma_f32_16x16x32_bf16 v[0:3], v[186:189], v[236:239], v[0:3]
	v_mfma_f32_16x16x32_bf16 v[0:3], v[244:247], v[240:243], v[0:3]
	s_setprio 0
	s_barrier
	s_add_i32 s56, s56, 2
	s_add_u32 s0, s0, 0x100
	s_addc_u32 s1, s1, 0
	s_add_u32 s54, s54, 0x100
	s_addc_u32 s55, s55, 0
	s_cmp_gt_u32 s56, 13
	s_cbranch_scc0 .LBB0_327
	s_and_b64 vcc, exec, s[22:23]
	s_cbranch_vccz .LBB0_330
	s_barrier

; #define PG8_STAGE(bufoff, gbase, voff) do { _Pragma("unroll") for (int _i = 0; _i < 2; ++_i) \
;         __builtin_amdgcn_global_load_lds((const unsigned*)((const char*)(gbase) + (voff)[_i]), (PG8_LAS unsigned*)(lds + (bufoff) + ldsw + _i * 8192), 16, 0, 0); } while (0)
; #define PG8_LDA(dst, b, h) do { _Pragma("unroll") for (int m = 0; m < 4; ++m) _Pragma("unroll") for (int k = 0; k < 2; ++k) dst[m][k] = *(const PG8_LAS bf16x8*)(lds + PG8_SA(b, h) + aoff + m * 2048 + k * 1024); } while (0)
; #define PG8_LDB(dst, b, h) do { _Pragma("unroll") for (int n = 0; n < 2; ++n) _Pragma("unroll") for (int k = 0; k < 2; ++k) dst[n][k] = *(const PG8_LAS bf16x8*)(lds + PG8_SB(b, h) + boff + n * 2048 + k * 1024); } while (0)
; #define PG8_MMA(ai, bj, At, Bt) do { __builtin_amdgcn_s_setprio(1); _Pragma("unroll") for (int m = 0; m < 4; ++m) _Pragma("unroll") for (int n = 0; n < 2; ++n) _Pragma("unroll") for (int k = 0; k < 2; ++k) \
;         acc[ai][bj][m][n] = __builtin_amdgcn_mfma_f32_16x16x32_bf16(Bt[n][k], At[m][k], acc[ai][bj][m][n], 0, 0, 0); __builtin_amdgcn_s_setprio(0); } while (0)
; #define PG8_WAIT_V(n) asm volatile("s_waitcnt vmcnt(" #n ")" ::: "memory")
; #define PG8_WAIT_L(n) asm volatile("s_waitcnt lgkmcnt(" #n ")" ::: "memory")
; #define PG8_BAR __builtin_amdgcn_s_barrier()
; #define PG8_SCHED __builtin_amdgcn_sched_barrier(0)
; template <class Epi, class Sched, bool ALIGN_EPI = false, bool SP2 = false>
; __device__ __forceinline__ void gemm_phase(PG8_LAS unsigned char* lds, const Gemm g, const Sched& S, const Epi& E) {
;     ...
;             PG8_LDB(B0, 0, 0); PG8_LDB(B1, 0, 1); PG8_SCHED; PG8_LDA(At, 0, 0); PG8_STAGE(PG8_SA(1, 1), a1 + hstep, voffA);
;             PG8_WAIT_V(8); PG8_WAIT_L(0); PG8_BAR; PG8_MMA(0, 0, At, B0); PG8_MMA(0, 1, At, B1); PG8_BAR; PG8_SCHED;
;             PG8_LDA(At, 0, 1); PG8_STAGE(PG8_SB(0, 0), b2, voffB); PG8_STAGE(PG8_SB(0, 1), b2 + hstep, voffB); PG8_STAGE(PG8_SA(0, 0), a2, voffA);
;             PG8_WAIT_V(8); PG8_WAIT_L(0); PG8_BAR; PG8_MMA(1, 0, At, B0); PG8_MMA(1, 1, At, B1); PG8_BAR; PG8_SCHED;
;     ...
; #pragma unroll
;         for (int a = 0; a < 2; ++a)
; #pragma unroll
;             for (int b = 0; b < 2; ++b)
; #pragma unroll
;                 for (int m = 0; m < 4; ++m)
; #pragma unroll
;                     for (int n = 0; n < 2; ++n) acc[a][b][m][n] = (f32x4){0.f, 0.f, 0.f, 0.f};
.Lup_peel:
	ds_read_b128 v[140:143], v254
	ds_read_b128 v[168:171], v254 offset:1024
	ds_read_b128 v[172:175], v254 offset:2048
	ds_read_b128 v[176:179], v254 offset:3072
	ds_read_b128 v[180:183], v254 offset:16384
	ds_read_b128 v[184:187], v254 offset:17408
	ds_read_b128 v[188:191], v254 offset:18432
	ds_read_b128 v[244:247], v254 offset:19456
	s_add_u32 s16, s14, 0xfffc0080
	s_addc_u32 s17, s15, -1
	s_cmp_eq_u32 s53, 12
	s_cselect_b32 s19, s7, s17
	s_cselect_b32 s18, s49, s16
	s_cselect_b32 s17, s5, s52
	s_cselect_b32 s16, s50, s51
	s_mov_b32 m0, s43
	ds_read_b128 v[212:215], v165
	ds_read_b128 v[216:219], v165 offset:1024
	ds_read_b128 v[220:223], v165 offset:2048
	ds_read_b128 v[224:227], v165 offset:3072
	ds_read_b128 v[228:231], v165 offset:4096
	ds_read_b128 v[232:235], v165 offset:5120
	ds_read_b128 v[236:239], v165 offset:6144
	ds_read_b128 v[240:243], v165 offset:7168
	global_load_lds_dwordx4 v136, s[14:15]
	s_mov_b32 m0, s44
	s_nop 0
	global_load_lds_dwordx4 v138, s[14:15]
	s_waitcnt vmcnt(8)
	s_waitcnt lgkmcnt(0)
	s_barrier
	s_setprio 1
	v_mfma_f32_16x16x32_bf16 v[124:127], v[140:143], v[212:215], 0
	v_mfma_f32_16x16x32_bf16 v[124:127], v[168:171], v[216:219], v[124:127]
	v_mfma_f32_16x16x32_bf16 v[108:111], v[140:143], v[220:223], 0
	v_mfma_f32_16x16x32_bf16 v[108:111], v[168:171], v[224:227], v[108:111]
	v_mfma_f32_16x16x32_bf16 v[92:95], v[140:143], v[228:231], 0
	v_mfma_f32_16x16x32_bf16 v[92:95], v[168:171], v[232:235], v[92:95]
	v_mfma_f32_16x16x32_bf16 v[76:79], v[140:143], v[236:239], 0
	v_mfma_f32_16x16x32_bf16 v[76:79], v[168:171], v[240:243], v[76:79]
	v_mfma_f32_16x16x32_bf16 v[116:119], v[172:175], v[212:215], 0
	v_mfma_f32_16x16x32_bf16 v[116:119], v[176:179], v[216:219], v[116:119]
	v_mfma_f32_16x16x32_bf16 v[100:103], v[172:175], v[220:223], 0
	v_mfma_f32_16x16x32_bf16 v[100:103], v[176:179], v[224:227], v[100:103]
	v_mfma_f32_16x16x32_bf16 v[84:87], v[172:175], v[228:231], 0
	v_mfma_f32_16x16x32_bf16 v[84:87], v[176:179], v[232:235], v[84:87]
	v_mfma_f32_16x16x32_bf16 v[68:71], v[172:175], v[236:239], 0
	v_mfma_f32_16x16x32_bf16 v[68:71], v[176:179], v[240:243], v[68:71]
	v_mfma_f32_16x16x32_bf16 v[120:123], v[180:183], v[212:215], 0
	v_mfma_f32_16x16x32_bf16 v[120:123], v[184:187], v[216:219], v[120:123]
	v_mfma_f32_16x16x32_bf16 v[104:107], v[180:183], v[220:223], 0
	v_mfma_f32_16x16x32_bf16 v[104:107], v[184:187], v[224:227], v[104:107]
	v_mfma_f32_16x16x32_bf16 v[88:91], v[180:183], v[228:231], 0
	v_mfma_f32_16x16x32_bf16 v[88:91], v[184:187], v[232:235], v[88:91]
	v_mfma_f32_16x16x32_bf16 v[72:75], v[180:183], v[236:239], 0
	v_mfma_f32_16x16x32_bf16 v[72:75], v[184:187], v[240:243], v[72:75]
	v_mfma_f32_16x16x32_bf16 v[112:115], v[188:191], v[212:215], 0
	v_mfma_f32_16x16x32_bf16 v[112:115], v[244:247], v[216:219], v[112:115]
	v_mfma_f32_16x16x32_bf16 v[96:99], v[188:191], v[220:223], 0
	v_mfma_f32_16x16x32_bf16 v[96:99], v[244:247], v[224:227], v[96:99]
	v_mfma_f32_16x16x32_bf16 v[80:83], v[188:191], v[228:231], 0
	v_mfma_f32_16x16x32_bf16 v[80:83], v[244:247], v[232:235], v[80:83]
	v_mfma_f32_16x16x32_bf16 v[64:67], v[188:191], v[236:239], 0
	v_mfma_f32_16x16x32_bf16 v[64:67], v[244:247], v[240:243], v[64:67]
	s_setprio 0
	s_barrier
	s_mov_b32 m0, s27
	s_add_u32 s54, s16, 0x40000
	s_addc_u32 s55, s17, 0
	ds_read_b128 v[212:215], v165 offset:16384
	ds_read_b128 v[216:219], v165 offset:17408
	ds_read_b128 v[220:223], v165 offset:18432
	ds_read_b128 v[224:227], v165 offset:19456
	ds_read_b128 v[228:231], v165 offset:20480
	ds_read_b128 v[232:235], v165 offset:21504
	ds_read_b128 v[236:239], v165 offset:22528
	ds_read_b128 v[240:243], v165 offset:23552
	global_load_lds_dwordx4 v132, s[16:17]
	s_mov_b32 m0, s28
	s_nop 0
	global_load_lds_dwordx4 v128, s[16:17]
	s_mov_b32 m0, s29
	s_nop 0
	global_load_lds_dwordx4 v132, s[54:55]
	s_mov_b32 m0, s30
	s_nop 0
	global_load_lds_dwordx4 v128, s[54:55]
	s_mov_b32 m0, s22
	s_nop 0
	global_load_lds_dwordx4 v134, s[18:19]
	s_mov_b32 m0, s31
	s_nop 0
	global_load_lds_dwordx4 v130, s[18:19]
	s_waitcnt vmcnt(8)
	s_waitcnt lgkmcnt(0)
	s_barrier
	s_setprio 1
	v_mfma_f32_16x16x32_bf16 v[60:63], v[140:143], v[212:215], 0
	v_mfma_f32_16x16x32_bf16 v[60:63], v[168:171], v[216:219], v[60:63]
	v_mfma_f32_16x16x32_bf16 v[44:47], v[140:143], v[220:223], 0
	v_mfma_f32_16x16x32_bf16 v[44:47], v[168:171], v[224:227], v[44:47]
	v_mfma_f32_16x16x32_bf16 v[28:31], v[140:143], v[228:231], 0
	v_mfma_f32_16x16x32_bf16 v[28:31], v[168:171], v[232:235], v[28:31]
	v_mfma_f32_16x16x32_bf16 v[12:15], v[140:143], v[236:239], 0
	v_mfma_f32_16x16x32_bf16 v[12:15], v[168:171], v[240:243], v[12:15]
	v_mfma_f32_16x16x32_bf16 v[52:55], v[172:175], v[212:215], 0
	v_mfma_f32_16x16x32_bf16 v[52:55], v[176:179], v[216:219], v[52:55]
	v_mfma_f32_16x16x32_bf16 v[36:39], v[172:175], v[220:223], 0
	v_mfma_f32_16x16x32_bf16 v[36:39], v[176:179], v[224:227], v[36:39]
	v_mfma_f32_16x16x32_bf16 v[20:23], v[172:175], v[228:231], 0
	v_mfma_f32_16x16x32_bf16 v[20:23], v[176:179], v[232:235], v[20:23]
	v_mfma_f32_16x16x32_bf16 v[4:7], v[172:175], v[236:239], 0
	v_mfma_f32_16x16x32_bf16 v[4:7], v[176:179], v[240:243], v[4:7]
	v_mfma_f32_16x16x32_bf16 v[56:59], v[180:183], v[212:215], 0
	v_mfma_f32_16x16x32_bf16 v[56:59], v[184:187], v[216:219], v[56:59]
	v_mfma_f32_16x16x32_bf16 v[40:43], v[180:183], v[220:223], 0
	v_mfma_f32_16x16x32_bf16 v[40:43], v[184:187], v[224:227], v[40:43]
	v_mfma_f32_16x16x32_bf16 v[24:27], v[180:183], v[228:231], 0
	v_mfma_f32_16x16x32_bf16 v[24:27], v[184:187], v[232:235], v[24:27]
	v_mfma_f32_16x16x32_bf16 v[8:11], v[180:183], v[236:239], 0
	v_mfma_f32_16x16x32_bf16 v[8:11], v[184:187], v[240:243], v[8:11]
	v_mfma_f32_16x16x32_bf16 v[48:51], v[188:191], v[212:215], 0
	v_mfma_f32_16x16x32_bf16 v[48:51], v[244:247], v[216:219], v[48:51]
	v_mfma_f32_16x16x32_bf16 v[32:35], v[188:191], v[220:223], 0
	v_mfma_f32_16x16x32_bf16 v[32:35], v[244:247], v[224:227], v[32:35]
	v_mfma_f32_16x16x32_bf16 v[16:19], v[188:191], v[228:231], 0
	v_mfma_f32_16x16x32_bf16 v[16:19], v[244:247], v[232:235], v[16:19]
	v_mfma_f32_16x16x32_bf16 v[0:3], v[188:191], v[236:239], 0
	v_mfma_f32_16x16x32_bf16 v[0:3], v[244:247], v[240:243], v[0:3]
	s_setprio 0
	s_barrier
; #define PG8_STAGE(bufoff, gbase, voff) do { _Pragma("unroll") for (int _i = 0; _i < 2; ++_i) \
;         __builtin_amdgcn_global_load_lds((const unsigned*)((const char*)(gbase) + (voff)[_i]), (PG8_LAS unsigned*)(lds + (bufoff) + ldsw + _i * 8192), 16, 0, 0); } while (0)
; #define PG8_LDA(dst, b, h) do { _Pragma("unroll") for (int m = 0; m < 4; ++m) _Pragma("unroll") for (int k = 0; k < 2; ++k) dst[m][k] = *(const PG8_LAS bf16x8*)(lds + PG8_SA(b, h) + aoff + m * 2048 + k * 1024); } while (0)
; #define PG8_LDB(dst, b, h) do { _Pragma("unroll") for (int n = 0; n < 2; ++n) _Pragma("unroll") for (int k = 0; k < 2; ++k) dst[n][k] = *(const PG8_LAS bf16x8*)(lds + PG8_SB(b, h) + boff + n * 2048 + k * 1024); } while (0)
; #define PG8_MMA(ai, bj, At, Bt) do { __builtin_amdgcn_s_setprio(1); _Pragma("unroll") for (int m = 0; m < 4; ++m) _Pragma("unroll") for (int n = 0; n < 2; ++n) _Pragma("unroll") for (int k = 0; k < 2; ++k) \
;         acc[ai][bj][m][n] = __builtin_amdgcn_mfma_f32_16x16x32_bf16(Bt[n][k], At[m][k], acc[ai][bj][m][n], 0, 0, 0); __builtin_amdgcn_s_setprio(0); } while (0)
; #define PG8_WAIT_V(n) asm volatile("s_waitcnt vmcnt(" #n ")" ::: "memory")
; #define PG8_WAIT_L(n) asm volatile("s_waitcnt lgkmcnt(" #n ")" ::: "memory")
; #define PG8_BAR __builtin_amdgcn_s_barrier()
; #define PG8_SCHED __builtin_amdgcn_sched_barrier(0)
; template <class Epi, class Sched, bool ALIGN_EPI = false, bool SP2 = false>
; __device__ __forceinline__ void gemm_phase(PG8_LAS unsigned char* lds, const Gemm g, const Sched& S, const Epi& E) {
;     ...
;             PG8_LDB(B0, 1, 0); PG8_LDB(B1, 1, 1); PG8_SCHED; PG8_LDA(At, 1, 0); PG8_STAGE(PG8_SA(0, 1), a2 + hstep, voffA);
;             PG8_WAIT_V(8); PG8_WAIT_L(0); PG8_BAR; PG8_MMA(0, 0, At, B0); PG8_MMA(0, 1, At, B1); PG8_BAR; PG8_SCHED;
;             PG8_LDA(At, 1, 1); PG8_STAGE(PG8_SB(1, 0), b3, voffB); PG8_STAGE(PG8_SB(1, 1), b3 + hstep, voffB); PG8_STAGE(PG8_SA(1, 0), a3, voffA);
;             PG8_WAIT_V(8); PG8_WAIT_L(0); PG8_BAR; PG8_MMA(1, 0, At, B0); PG8_MMA(1, 1, At, B1); PG8_BAR; PG8_SCHED;
	ds_read_b128 v[140:143], v254 offset:32768
	ds_read_b128 v[168:171], v254 offset:33792
	ds_read_b128 v[172:175], v254 offset:34816
	ds_read_b128 v[176:179], v254 offset:35840
	ds_read_b128 v[180:183], v254 offset:49152
	ds_read_b128 v[184:187], v254 offset:50176
	ds_read_b128 v[188:191], v254 offset:51200
	ds_read_b128 v[244:247], v254 offset:52224
	s_add_u32 s18, s18, 0x40000
	s_addc_u32 s19, s19, 0
	s_mov_b32 m0, s33
	ds_read_b128 v[212:215], v165 offset:32768
	ds_read_b128 v[216:219], v165 offset:33792
	ds_read_b128 v[220:223], v165 offset:34816
	ds_read_b128 v[224:227], v165 offset:35840
	ds_read_b128 v[228:231], v165 offset:36864
	ds_read_b128 v[232:235], v165 offset:37888
	ds_read_b128 v[236:239], v165 offset:38912
	ds_read_b128 v[240:243], v165 offset:39936
	global_load_lds_dwordx4 v134, s[18:19]
	s_mov_b32 m0, s34
	s_nop 0
	global_load_lds_dwordx4 v130, s[18:19]
	s_waitcnt vmcnt(8)
	s_waitcnt lgkmcnt(0)
	s_barrier
	s_setprio 1
	v_mfma_f32_16x16x32_bf16 v[124:127], v[140:143], v[212:215], v[124:127]
	v_mfma_f32_16x16x32_bf16 v[124:127], v[168:171], v[216:219], v[124:127]
	v_mfma_f32_16x16x32_bf16 v[108:111], v[140:143], v[220:223], v[108:111]
	v_mfma_f32_16x16x32_bf16 v[108:111], v[168:171], v[224:227], v[108:111]
	v_mfma_f32_16x16x32_bf16 v[92:95], v[140:143], v[228:231], v[92:95]
	v_mfma_f32_16x16x32_bf16 v[92:95], v[168:171], v[232:235], v[92:95]
	v_mfma_f32_16x16x32_bf16 v[76:79], v[140:143], v[236:239], v[76:79]
	v_mfma_f32_16x16x32_bf16 v[76:79], v[168:171], v[240:243], v[76:79]
	v_mfma_f32_16x16x32_bf16 v[116:119], v[172:175], v[212:215], v[116:119]
	v_mfma_f32_16x16x32_bf16 v[116:119], v[176:179], v[216:219], v[116:119]
	v_mfma_f32_16x16x32_bf16 v[100:103], v[172:175], v[220:223], v[100:103]
	v_mfma_f32_16x16x32_bf16 v[100:103], v[176:179], v[224:227], v[100:103]
	v_mfma_f32_16x16x32_bf16 v[84:87], v[172:175], v[228:231], v[84:87]
	v_mfma_f32_16x16x32_bf16 v[84:87], v[176:179], v[232:235], v[84:87]
	v_mfma_f32_16x16x32_bf16 v[68:71], v[172:175], v[236:239], v[68:71]
	v_mfma_f32_16x16x32_bf16 v[68:71], v[176:179], v[240:243], v[68:71]
	v_mfma_f32_16x16x32_bf16 v[120:123], v[180:183], v[212:215], v[120:123]
	v_mfma_f32_16x16x32_bf16 v[120:123], v[184:187], v[216:219], v[120:123]
	v_mfma_f32_16x16x32_bf16 v[104:107], v[180:183], v[220:223], v[104:107]
	v_mfma_f32_16x16x32_bf16 v[104:107], v[184:187], v[224:227], v[104:107]
	v_mfma_f32_16x16x32_bf16 v[88:91], v[180:183], v[228:231], v[88:91]
	v_mfma_f32_16x16x32_bf16 v[88:91], v[184:187], v[232:235], v[88:91]
	v_mfma_f32_16x16x32_bf16 v[72:75], v[180:183], v[236:239], v[72:75]
	v_mfma_f32_16x16x32_bf16 v[72:75], v[184:187], v[240:243], v[72:75]
	v_mfma_f32_16x16x32_bf16 v[112:115], v[188:191], v[212:215], v[112:115]
	v_mfma_f32_16x16x32_bf16 v[112:115], v[244:247], v[216:219], v[112:115]
	v_mfma_f32_16x16x32_bf16 v[96:99], v[188:191], v[220:223], v[96:99]
	v_mfma_f32_16x16x32_bf16 v[96:99], v[244:247], v[224:227], v[96:99]
	v_mfma_f32_16x16x32_bf16 v[80:83], v[188:191], v[228:231], v[80:83]
	v_mfma_f32_16x16x32_bf16 v[80:83], v[244:247], v[232:235], v[80:83]
	v_mfma_f32_16x16x32_bf16 v[64:67], v[188:191], v[236:239], v[64:67]
	v_mfma_f32_16x16x32_bf16 v[64:67], v[244:247], v[240:243], v[64:67]
	s_setprio 0
	s_barrier
	s_mov_b32 m0, s37
	s_add_u32 s16, s16, 0x40080
	s_addc_u32 s17, s17, 0
	ds_read_b128 v[212:215], v165 offset:49152
	ds_read_b128 v[216:219], v165 offset:50176
	ds_read_b128 v[220:223], v165 offset:51200
	ds_read_b128 v[224:227], v165 offset:52224
	ds_read_b128 v[228:231], v165 offset:53248
	ds_read_b128 v[232:235], v165 offset:54272
	ds_read_b128 v[236:239], v165 offset:55296
	ds_read_b128 v[240:243], v165 offset:56320
	s_add_u32 s98, s16, 0xfffc0000
	s_addc_u32 s99, s17, -1
	global_load_lds_dwordx4 v132, s[98:99]
	s_mov_b32 m0, s38
	s_nop 0
	global_load_lds_dwordx4 v128, s[98:99]
	s_mov_b32 m0, s41
	s_nop 0
	global_load_lds_dwordx4 v132, s[16:17]
	s_mov_b32 m0, s42
	s_nop 0
	global_load_lds_dwordx4 v128, s[16:17]
	s_mov_b32 m0, s39
	s_nop 0
	s_add_u32 s100, s18, 0xfffc0080
	s_addc_u32 s101, s19, -1
	global_load_lds_dwordx4 v134, s[100:101]
	s_mov_b32 m0, s40
	s_nop 0
	global_load_lds_dwordx4 v130, s[100:101]
	s_waitcnt vmcnt(8)
	s_waitcnt lgkmcnt(0)
	s_barrier
	s_setprio 1
	v_mfma_f32_16x16x32_bf16 v[60:63], v[140:143], v[212:215], v[60:63]
	v_mfma_f32_16x16x32_bf16 v[60:63], v[168:171], v[216:219], v[60:63]
	v_mfma_f32_16x16x32_bf16 v[44:47], v[140:143], v[220:223], v[44:47]
	v_mfma_f32_16x16x32_bf16 v[44:47], v[168:171], v[224:227], v[44:47]
	v_mfma_f32_16x16x32_bf16 v[28:31], v[140:143], v[228:231], v[28:31]
	v_mfma_f32_16x16x32_bf16 v[28:31], v[168:171], v[232:235], v[28:31]
	v_mfma_f32_16x16x32_bf16 v[12:15], v[140:143], v[236:239], v[12:15]
	v_mfma_f32_16x16x32_bf16 v[12:15], v[168:171], v[240:243], v[12:15]
	v_mfma_f32_16x16x32_bf16 v[52:55], v[172:175], v[212:215], v[52:55]
	v_mfma_f32_16x16x32_bf16 v[52:55], v[176:179], v[216:219], v[52:55]
	v_mfma_f32_16x16x32_bf16 v[36:39], v[172:175], v[220:223], v[36:39]
	v_mfma_f32_16x16x32_bf16 v[36:39], v[176:179], v[224:227], v[36:39]
	v_mfma_f32_16x16x32_bf16 v[20:23], v[172:175], v[228:231], v[20:23]
	v_mfma_f32_16x16x32_bf16 v[20:23], v[176:179], v[232:235], v[20:23]
	v_mfma_f32_16x16x32_bf16 v[4:7], v[172:175], v[236:239], v[4:7]
	v_mfma_f32_16x16x32_bf16 v[4:7], v[176:179], v[240:243], v[4:7]
	v_mfma_f32_16x16x32_bf16 v[56:59], v[180:183], v[212:215], v[56:59]
	v_mfma_f32_16x16x32_bf16 v[56:59], v[184:187], v[216:219], v[56:59]
	v_mfma_f32_16x16x32_bf16 v[40:43], v[180:183], v[220:223], v[40:43]
	v_mfma_f32_16x16x32_bf16 v[40:43], v[184:187], v[224:227], v[40:43]
	v_mfma_f32_16x16x32_bf16 v[24:27], v[180:183], v[228:231], v[24:27]
	v_mfma_f32_16x16x32_bf16 v[24:27], v[184:187], v[232:235], v[24:27]
	v_mfma_f32_16x16x32_bf16 v[8:11], v[180:183], v[236:239], v[8:11]
	v_mfma_f32_16x16x32_bf16 v[8:11], v[184:187], v[240:243], v[8:11]
	v_mfma_f32_16x16x32_bf16 v[48:51], v[188:191], v[212:215], v[48:51]
	v_mfma_f32_16x16x32_bf16 v[48:51], v[244:247], v[216:219], v[48:51]
	v_mfma_f32_16x16x32_bf16 v[32:35], v[188:191], v[220:223], v[32:35]
	v_mfma_f32_16x16x32_bf16 v[32:35], v[244:247], v[224:227], v[32:35]
	v_mfma_f32_16x16x32_bf16 v[16:19], v[188:191], v[228:231], v[16:19]
	v_mfma_f32_16x16x32_bf16 v[16:19], v[244:247], v[232:235], v[16:19]
	v_mfma_f32_16x16x32_bf16 v[0:3], v[188:191], v[236:239], v[0:3]
	v_mfma_f32_16x16x32_bf16 v[0:3], v[244:247], v[240:243], v[0:3]
	s_setprio 0
	s_barrier
	s_add_i32 s53, s53, 2
	s_add_u32 s14, s14, 0x100
	s_addc_u32 s15, s15, 0
	s_add_u32 s51, s51, 0x100
	s_addc_u32 s52, s52, 0
	s_cmp_gt_u32 s53, 13
; #define PG8_STAGE(bufoff, gbase, voff) do { _Pragma("unroll") for (int _i = 0; _i < 2; ++_i) \
;         __builtin_amdgcn_global_load_lds((const unsigned*)((const char*)(gbase) + (voff)[_i]), (PG8_LAS unsigned*)(lds + (bufoff) + ldsw + _i * 8192), 16, 0, 0); } while (0)
; #define PG8_LDA(dst, b, h) do { _Pragma("unroll") for (int m = 0; m < 4; ++m) _Pragma("unroll") for (int k = 0; k < 2; ++k) dst[m][k] = *(const PG8_LAS bf16x8*)(lds + PG8_SA(b, h) + aoff + m * 2048 + k * 1024); } while (0)
; #define PG8_LDB(dst, b, h) do { _Pragma("unroll") for (int n = 0; n < 2; ++n) _Pragma("unroll") for (int k = 0; k < 2; ++k) dst[n][k] = *(const PG8_LAS bf16x8*)(lds + PG8_SB(b, h) + boff + n * 2048 + k * 1024); } while (0)
; #define PG8_MMA(ai, bj, At, Bt) do { __builtin_amdgcn_s_setprio(1); _Pragma("unroll") for (int m = 0; m < 4; ++m) _Pragma("unroll") for (int n = 0; n < 2; ++n) _Pragma("unroll") for (int k = 0; k < 2; ++k) \
;         acc[ai][bj][m][n] = __builtin_amdgcn_mfma_f32_16x16x32_bf16(Bt[n][k], At[m][k], acc[ai][bj][m][n], 0, 0, 0); __builtin_amdgcn_s_setprio(0); } while (0)
; #define PG8_WAIT_V(n) asm volatile("s_waitcnt vmcnt(" #n ")" ::: "memory")
; #define PG8_WAIT_L(n) asm volatile("s_waitcnt lgkmcnt(" #n ")" ::: "memory")
; #define PG8_BAR __builtin_amdgcn_s_barrier()
; #define PG8_SCHED __builtin_amdgcn_sched_barrier(0)
; template <class Epi, class Sched, bool ALIGN_EPI = false, bool SP2 = false>
; __device__ __forceinline__ void gemm_phase(PG8_LAS unsigned char* lds, const Gemm g, const Sched& S, const Epi& E) {
;     ...
;             PG8_LDB(B0, 0, 0); PG8_LDB(B1, 0, 1); PG8_SCHED; PG8_LDA(At, 0, 0); PG8_STAGE(PG8_SA(1, 1), a1 + hstep, voffA);
;             PG8_WAIT_V(8); PG8_WAIT_L(0); PG8_BAR; PG8_MMA(0, 0, At, B0); PG8_MMA(0, 1, At, B1); PG8_BAR; PG8_SCHED;
;             PG8_LDA(At, 0, 1); PG8_STAGE(PG8_SB(0, 0), b2, voffB); PG8_STAGE(PG8_SB(0, 1), b2 + hstep, voffB); PG8_STAGE(PG8_SA(0, 0), a2, voffA);
;             PG8_WAIT_V(8); PG8_WAIT_L(0); PG8_BAR; PG8_MMA(1, 0, At, B0); PG8_MMA(1, 1, At, B1); PG8_BAR; PG8_SCHED;
.LBB0_446:
	ds_read_b128 v[140:143], v254
	ds_read_b128 v[168:171], v254 offset:1024
	ds_read_b128 v[172:175], v254 offset:2048
	ds_read_b128 v[176:179], v254 offset:3072
	ds_read_b128 v[180:183], v254 offset:16384
	ds_read_b128 v[184:187], v254 offset:17408
	ds_read_b128 v[188:191], v254 offset:18432
	ds_read_b128 v[244:247], v254 offset:19456
	s_add_u32 s16, s14, 0xfffc0080
	s_addc_u32 s17, s15, -1
	s_cmp_eq_u32 s53, 12
	s_cselect_b32 s19, s7, s17
	s_cselect_b32 s18, s49, s16
	s_cselect_b32 s17, s5, s52
	s_cselect_b32 s16, s50, s51
	s_mov_b32 m0, s43
	ds_read_b128 v[212:215], v165
	ds_read_b128 v[216:219], v165 offset:1024
	ds_read_b128 v[220:223], v165 offset:2048
	ds_read_b128 v[224:227], v165 offset:3072
	ds_read_b128 v[228:231], v165 offset:4096
	ds_read_b128 v[232:235], v165 offset:5120
	ds_read_b128 v[236:239], v165 offset:6144
	ds_read_b128 v[240:243], v165 offset:7168
	global_load_lds_dwordx4 v136, s[14:15]
	s_mov_b32 m0, s44
	s_nop 0
	global_load_lds_dwordx4 v138, s[14:15]
	s_waitcnt vmcnt(8)
	s_waitcnt lgkmcnt(0)
	s_barrier
	s_setprio 1
	v_mfma_f32_16x16x32_bf16 v[124:127], v[140:143], v[212:215], v[124:127]
	v_mfma_f32_16x16x32_bf16 v[124:127], v[168:171], v[216:219], v[124:127]
	v_mfma_f32_16x16x32_bf16 v[108:111], v[140:143], v[220:223], v[108:111]
	v_mfma_f32_16x16x32_bf16 v[108:111], v[168:171], v[224:227], v[108:111]
	v_mfma_f32_16x16x32_bf16 v[92:95], v[140:143], v[228:231], v[92:95]
	v_mfma_f32_16x16x32_bf16 v[92:95], v[168:171], v[232:235], v[92:95]
	v_mfma_f32_16x16x32_bf16 v[76:79], v[140:143], v[236:239], v[76:79]
	v_mfma_f32_16x16x32_bf16 v[76:79], v[168:171], v[240:243], v[76:79]
	v_mfma_f32_16x16x32_bf16 v[116:119], v[172:175], v[212:215], v[116:119]
	v_mfma_f32_16x16x32_bf16 v[116:119], v[176:179], v[216:219], v[116:119]
	v_mfma_f32_16x16x32_bf16 v[100:103], v[172:175], v[220:223], v[100:103]
	v_mfma_f32_16x16x32_bf16 v[100:103], v[176:179], v[224:227], v[100:103]
	v_mfma_f32_16x16x32_bf16 v[84:87], v[172:175], v[228:231], v[84:87]
	v_mfma_f32_16x16x32_bf16 v[84:87], v[176:179], v[232:235], v[84:87]
	v_mfma_f32_16x16x32_bf16 v[68:71], v[172:175], v[236:239], v[68:71]
	v_mfma_f32_16x16x32_bf16 v[68:71], v[176:179], v[240:243], v[68:71]
	v_mfma_f32_16x16x32_bf16 v[120:123], v[180:183], v[212:215], v[120:123]
	v_mfma_f32_16x16x32_bf16 v[120:123], v[184:187], v[216:219], v[120:123]
	v_mfma_f32_16x16x32_bf16 v[104:107], v[180:183], v[220:223], v[104:107]
	v_mfma_f32_16x16x32_bf16 v[104:107], v[184:187], v[224:227], v[104:107]
	v_mfma_f32_16x16x32_bf16 v[88:91], v[180:183], v[228:231], v[88:91]
	v_mfma_f32_16x16x32_bf16 v[88:91], v[184:187], v[232:235], v[88:91]
	v_mfma_f32_16x16x32_bf16 v[72:75], v[180:183], v[236:239], v[72:75]
	v_mfma_f32_16x16x32_bf16 v[72:75], v[184:187], v[240:243], v[72:75]
	v_mfma_f32_16x16x32_bf16 v[112:115], v[188:191], v[212:215], v[112:115]
	v_mfma_f32_16x16x32_bf16 v[112:115], v[244:247], v[216:219], v[112:115]
	v_mfma_f32_16x16x32_bf16 v[96:99], v[188:191], v[220:223], v[96:99]
	v_mfma_f32_16x16x32_bf16 v[96:99], v[244:247], v[224:227], v[96:99]
	v_mfma_f32_16x16x32_bf16 v[80:83], v[188:191], v[228:231], v[80:83]
	v_mfma_f32_16x16x32_bf16 v[80:83], v[244:247], v[232:235], v[80:83]
	v_mfma_f32_16x16x32_bf16 v[64:67], v[188:191], v[236:239], v[64:67]
	v_mfma_f32_16x16x32_bf16 v[64:67], v[244:247], v[240:243], v[64:67]
	s_setprio 0
	s_barrier
	s_mov_b32 m0, s27
	s_add_u32 s54, s16, 0x40000
	s_addc_u32 s55, s17, 0
	ds_read_b128 v[212:215], v165 offset:16384
	ds_read_b128 v[216:219], v165 offset:17408
	ds_read_b128 v[220:223], v165 offset:18432
	ds_read_b128 v[224:227], v165 offset:19456
	ds_read_b128 v[228:231], v165 offset:20480
	ds_read_b128 v[232:235], v165 offset:21504
	ds_read_b128 v[236:239], v165 offset:22528
	ds_read_b128 v[240:243], v165 offset:23552
	global_load_lds_dwordx4 v132, s[16:17]
	s_mov_b32 m0, s28
	s_nop 0
	global_load_lds_dwordx4 v128, s[16:17]
	s_mov_b32 m0, s29
	s_nop 0
	global_load_lds_dwordx4 v132, s[54:55]
	s_mov_b32 m0, s30
	s_nop 0
	global_load_lds_dwordx4 v128, s[54:55]
	s_mov_b32 m0, s22
	s_nop 0
	global_load_lds_dwordx4 v134, s[18:19]
	s_mov_b32 m0, s31
	s_nop 0
	global_load_lds_dwordx4 v130, s[18:19]
	s_waitcnt vmcnt(8)
	s_waitcnt lgkmcnt(0)
	s_barrier
	s_setprio 1
	v_mfma_f32_16x16x32_bf16 v[60:63], v[140:143], v[212:215], v[60:63]
	v_mfma_f32_16x16x32_bf16 v[60:63], v[168:171], v[216:219], v[60:63]
	v_mfma_f32_16x16x32_bf16 v[44:47], v[140:143], v[220:223], v[44:47]
	v_mfma_f32_16x16x32_bf16 v[44:47], v[168:171], v[224:227], v[44:47]
	v_mfma_f32_16x16x32_bf16 v[28:31], v[140:143], v[228:231], v[28:31]
	v_mfma_f32_16x16x32_bf16 v[28:31], v[168:171], v[232:235], v[28:31]
	v_mfma_f32_16x16x32_bf16 v[12:15], v[140:143], v[236:239], v[12:15]
	v_mfma_f32_16x16x32_bf16 v[12:15], v[168:171], v[240:243], v[12:15]
	v_mfma_f32_16x16x32_bf16 v[52:55], v[172:175], v[212:215], v[52:55]
	v_mfma_f32_16x16x32_bf16 v[52:55], v[176:179], v[216:219], v[52:55]
	v_mfma_f32_16x16x32_bf16 v[36:39], v[172:175], v[220:223], v[36:39]
	v_mfma_f32_16x16x32_bf16 v[36:39], v[176:179], v[224:227], v[36:39]
	v_mfma_f32_16x16x32_bf16 v[20:23], v[172:175], v[228:231], v[20:23]
	v_mfma_f32_16x16x32_bf16 v[20:23], v[176:179], v[232:235], v[20:23]
	v_mfma_f32_16x16x32_bf16 v[4:7], v[172:175], v[236:239], v[4:7]
	v_mfma_f32_16x16x32_bf16 v[4:7], v[176:179], v[240:243], v[4:7]
	v_mfma_f32_16x16x32_bf16 v[56:59], v[180:183], v[212:215], v[56:59]
	v_mfma_f32_16x16x32_bf16 v[56:59], v[184:187], v[216:219], v[56:59]
	v_mfma_f32_16x16x32_bf16 v[40:43], v[180:183], v[220:223], v[40:43]
	v_mfma_f32_16x16x32_bf16 v[40:43], v[184:187], v[224:227], v[40:43]
	v_mfma_f32_16x16x32_bf16 v[24:27], v[180:183], v[228:231], v[24:27]
	v_mfma_f32_16x16x32_bf16 v[24:27], v[184:187], v[232:235], v[24:27]
	v_mfma_f32_16x16x32_bf16 v[8:11], v[180:183], v[236:239], v[8:11]
	v_mfma_f32_16x16x32_bf16 v[8:11], v[184:187], v[240:243], v[8:11]
	v_mfma_f32_16x16x32_bf16 v[48:51], v[188:191], v[212:215], v[48:51]
	v_mfma_f32_16x16x32_bf16 v[48:51], v[244:247], v[216:219], v[48:51]
	v_mfma_f32_16x16x32_bf16 v[32:35], v[188:191], v[220:223], v[32:35]
	v_mfma_f32_16x16x32_bf16 v[32:35], v[244:247], v[224:227], v[32:35]
	v_mfma_f32_16x16x32_bf16 v[16:19], v[188:191], v[228:231], v[16:19]
	v_mfma_f32_16x16x32_bf16 v[16:19], v[244:247], v[232:235], v[16:19]
	v_mfma_f32_16x16x32_bf16 v[0:3], v[188:191], v[236:239], v[0:3]
	v_mfma_f32_16x16x32_bf16 v[0:3], v[244:247], v[240:243], v[0:3]
	s_setprio 0
	s_barrier
; #define PG8_STAGE(bufoff, gbase, voff) do { _Pragma("unroll") for (int _i = 0; _i < 2; ++_i) \
;         __builtin_amdgcn_global_load_lds((const unsigned*)((const char*)(gbase) + (voff)[_i]), (PG8_LAS unsigned*)(lds + (bufoff) + ldsw + _i * 8192), 16, 0, 0); } while (0)
; #define PG8_LDA(dst, b, h) do { _Pragma("unroll") for (int m = 0; m < 4; ++m) _Pragma("unroll") for (int k = 0; k < 2; ++k) dst[m][k] = *(const PG8_LAS bf16x8*)(lds + PG8_SA(b, h) + aoff + m * 2048 + k * 1024); } while (0)
; #define PG8_LDB(dst, b, h) do { _Pragma("unroll") for (int n = 0; n < 2; ++n) _Pragma("unroll") for (int k = 0; k < 2; ++k) dst[n][k] = *(const PG8_LAS bf16x8*)(lds + PG8_SB(b, h) + boff + n * 2048 + k * 1024); } while (0)
; #define PG8_MMA(ai, bj, At, Bt) do { __builtin_amdgcn_s_setprio(1); _Pragma("unroll") for (int m = 0; m < 4; ++m) _Pragma("unroll") for (int n = 0; n < 2; ++n) _Pragma("unroll") for (int k = 0; k < 2; ++k) \
;         acc[ai][bj][m][n] = __builtin_amdgcn_mfma_f32_16x16x32_bf16(Bt[n][k], At[m][k], acc[ai][bj][m][n], 0, 0, 0); __builtin_amdgcn_s_setprio(0); } while (0)
; #define PG8_WAIT_V(n) asm volatile("s_waitcnt vmcnt(" #n ")" ::: "memory")
; #define PG8_WAIT_L(n) asm volatile("s_waitcnt lgkmcnt(" #n ")" ::: "memory")
; template <class Epi, class Sched, bool ALIGN_EPI = false, bool SP2 = false>
; __device__ __forceinline__ void gemm_phase(PG8_LAS unsigned char* lds, const Gemm g, const Sched& S, const Epi& E) {
;     ...
;         for (int t = 0; t < nt; t += 2) {
;             const bool last = (t == nt - 2);
;             const char* a1 = cA + (size_t)(t + 1) * kstep;
;             const char* a2 = last ? nA : cA + (size_t)(t + 2) * kstep; const char* b2 = last ? nB : cB + (size_t)(t + 2) * kstep;
;             const char* a3 = a2 + kstep; const char* b3 = b2 + kstep;
;             if (last && has_next) S.a_ready(nxt);
;     ...
;             PG8_LDB(B0, 1, 0); PG8_LDB(B1, 1, 1); PG8_SCHED; PG8_LDA(At, 1, 0); PG8_STAGE(PG8_SA(0, 1), a2 + hstep, voffA);
;             PG8_WAIT_V(8); PG8_WAIT_L(0); PG8_BAR; PG8_MMA(0, 0, At, B0); PG8_MMA(0, 1, At, B1); PG8_BAR; PG8_SCHED;
;             PG8_LDA(At, 1, 1); PG8_STAGE(PG8_SB(1, 0), b3, voffB); PG8_STAGE(PG8_SB(1, 1), b3 + hstep, voffB); PG8_STAGE(PG8_SA(1, 0), a3, voffA);
;             PG8_WAIT_V(8); PG8_WAIT_L(0); PG8_BAR; PG8_MMA(1, 0, At, B0); PG8_MMA(1, 1, At, B1); PG8_BAR; PG8_SCHED;
	ds_read_b128 v[140:143], v254 offset:32768
	ds_read_b128 v[168:171], v254 offset:33792
	ds_read_b128 v[172:175], v254 offset:34816
	ds_read_b128 v[176:179], v254 offset:35840
	ds_read_b128 v[180:183], v254 offset:49152
	ds_read_b128 v[184:187], v254 offset:50176
	ds_read_b128 v[188:191], v254 offset:51200
	ds_read_b128 v[244:247], v254 offset:52224
	s_add_u32 s18, s18, 0x40000
	s_addc_u32 s19, s19, 0
	s_mov_b32 m0, s33
	ds_read_b128 v[212:215], v165 offset:32768
	ds_read_b128 v[216:219], v165 offset:33792
	ds_read_b128 v[220:223], v165 offset:34816
	ds_read_b128 v[224:227], v165 offset:35840
	ds_read_b128 v[228:231], v165 offset:36864
	ds_read_b128 v[232:235], v165 offset:37888
	ds_read_b128 v[236:239], v165 offset:38912
	ds_read_b128 v[240:243], v165 offset:39936
	global_load_lds_dwordx4 v134, s[18:19]
	s_mov_b32 m0, s34
	s_nop 0
	global_load_lds_dwordx4 v130, s[18:19]
	s_waitcnt vmcnt(8)
	s_waitcnt lgkmcnt(0)
	s_barrier
	s_setprio 1
	v_mfma_f32_16x16x32_bf16 v[124:127], v[140:143], v[212:215], v[124:127]
	v_mfma_f32_16x16x32_bf16 v[124:127], v[168:171], v[216:219], v[124:127]
	v_mfma_f32_16x16x32_bf16 v[108:111], v[140:143], v[220:223], v[108:111]
	v_mfma_f32_16x16x32_bf16 v[108:111], v[168:171], v[224:227], v[108:111]
	v_mfma_f32_16x16x32_bf16 v[92:95], v[140:143], v[228:231], v[92:95]
	v_mfma_f32_16x16x32_bf16 v[92:95], v[168:171], v[232:235], v[92:95]
	v_mfma_f32_16x16x32_bf16 v[76:79], v[140:143], v[236:239], v[76:79]
	v_mfma_f32_16x16x32_bf16 v[76:79], v[168:171], v[240:243], v[76:79]
	v_mfma_f32_16x16x32_bf16 v[116:119], v[172:175], v[212:215], v[116:119]
	v_mfma_f32_16x16x32_bf16 v[116:119], v[176:179], v[216:219], v[116:119]
	v_mfma_f32_16x16x32_bf16 v[100:103], v[172:175], v[220:223], v[100:103]
	v_mfma_f32_16x16x32_bf16 v[100:103], v[176:179], v[224:227], v[100:103]
	v_mfma_f32_16x16x32_bf16 v[84:87], v[172:175], v[228:231], v[84:87]
	v_mfma_f32_16x16x32_bf16 v[84:87], v[176:179], v[232:235], v[84:87]
	v_mfma_f32_16x16x32_bf16 v[68:71], v[172:175], v[236:239], v[68:71]
	v_mfma_f32_16x16x32_bf16 v[68:71], v[176:179], v[240:243], v[68:71]
	v_mfma_f32_16x16x32_bf16 v[120:123], v[180:183], v[212:215], v[120:123]
	v_mfma_f32_16x16x32_bf16 v[120:123], v[184:187], v[216:219], v[120:123]
	v_mfma_f32_16x16x32_bf16 v[104:107], v[180:183], v[220:223], v[104:107]
	v_mfma_f32_16x16x32_bf16 v[104:107], v[184:187], v[224:227], v[104:107]
	v_mfma_f32_16x16x32_bf16 v[88:91], v[180:183], v[228:231], v[88:91]
	v_mfma_f32_16x16x32_bf16 v[88:91], v[184:187], v[232:235], v[88:91]
	v_mfma_f32_16x16x32_bf16 v[72:75], v[180:183], v[236:239], v[72:75]
	v_mfma_f32_16x16x32_bf16 v[72:75], v[184:187], v[240:243], v[72:75]
	v_mfma_f32_16x16x32_bf16 v[112:115], v[188:191], v[212:215], v[112:115]
	v_mfma_f32_16x16x32_bf16 v[112:115], v[244:247], v[216:219], v[112:115]
	v_mfma_f32_16x16x32_bf16 v[96:99], v[188:191], v[220:223], v[96:99]
	v_mfma_f32_16x16x32_bf16 v[96:99], v[244:247], v[224:227], v[96:99]
	v_mfma_f32_16x16x32_bf16 v[80:83], v[188:191], v[228:231], v[80:83]
	v_mfma_f32_16x16x32_bf16 v[80:83], v[244:247], v[232:235], v[80:83]
	v_mfma_f32_16x16x32_bf16 v[64:67], v[188:191], v[236:239], v[64:67]
	v_mfma_f32_16x16x32_bf16 v[64:67], v[244:247], v[240:243], v[64:67]
	s_setprio 0
	s_barrier
	s_mov_b32 m0, s37
	s_add_u32 s16, s16, 0x40080
	s_addc_u32 s17, s17, 0
	ds_read_b128 v[212:215], v165 offset:49152
	ds_read_b128 v[216:219], v165 offset:50176
	ds_read_b128 v[220:223], v165 offset:51200
	ds_read_b128 v[224:227], v165 offset:52224
	ds_read_b128 v[228:231], v165 offset:53248
	ds_read_b128 v[232:235], v165 offset:54272
	ds_read_b128 v[236:239], v165 offset:55296
	ds_read_b128 v[240:243], v165 offset:56320
	s_add_u32 s98, s16, 0xfffc0000
	s_addc_u32 s99, s17, -1
	global_load_lds_dwordx4 v132, s[98:99]
	s_mov_b32 m0, s38
	s_nop 0
	global_load_lds_dwordx4 v128, s[98:99]
	s_mov_b32 m0, s41
	s_nop 0
	global_load_lds_dwordx4 v132, s[16:17]
	s_mov_b32 m0, s42
	s_nop 0
	global_load_lds_dwordx4 v128, s[16:17]
	s_mov_b32 m0, s39
	s_nop 0
	s_add_u32 s100, s18, 0xfffc0080
	s_addc_u32 s101, s19, -1
	global_load_lds_dwordx4 v134, s[100:101]
	s_mov_b32 m0, s40
	s_nop 0
	global_load_lds_dwordx4 v130, s[100:101]
	s_waitcnt vmcnt(8)
	s_waitcnt lgkmcnt(0)
	s_barrier
	s_setprio 1
	v_mfma_f32_16x16x32_bf16 v[60:63], v[140:143], v[212:215], v[60:63]
	v_mfma_f32_16x16x32_bf16 v[60:63], v[168:171], v[216:219], v[60:63]
	v_mfma_f32_16x16x32_bf16 v[44:47], v[140:143], v[220:223], v[44:47]
	v_mfma_f32_16x16x32_bf16 v[44:47], v[168:171], v[224:227], v[44:47]
	v_mfma_f32_16x16x32_bf16 v[28:31], v[140:143], v[228:231], v[28:31]
	v_mfma_f32_16x16x32_bf16 v[28:31], v[168:171], v[232:235], v[28:31]
	v_mfma_f32_16x16x32_bf16 v[12:15], v[140:143], v[236:239], v[12:15]
	v_mfma_f32_16x16x32_bf16 v[12:15], v[168:171], v[240:243], v[12:15]
	v_mfma_f32_16x16x32_bf16 v[52:55], v[172:175], v[212:215], v[52:55]
	v_mfma_f32_16x16x32_bf16 v[52:55], v[176:179], v[216:219], v[52:55]
	v_mfma_f32_16x16x32_bf16 v[36:39], v[172:175], v[220:223], v[36:39]
	v_mfma_f32_16x16x32_bf16 v[36:39], v[176:179], v[224:227], v[36:39]
	v_mfma_f32_16x16x32_bf16 v[20:23], v[172:175], v[228:231], v[20:23]
	v_mfma_f32_16x16x32_bf16 v[20:23], v[176:179], v[232:235], v[20:23]
	v_mfma_f32_16x16x32_bf16 v[4:7], v[172:175], v[236:239], v[4:7]
	v_mfma_f32_16x16x32_bf16 v[4:7], v[176:179], v[240:243], v[4:7]
	v_mfma_f32_16x16x32_bf16 v[56:59], v[180:183], v[212:215], v[56:59]
	v_mfma_f32_16x16x32_bf16 v[56:59], v[184:187], v[216:219], v[56:59]
	v_mfma_f32_16x16x32_bf16 v[40:43], v[180:183], v[220:223], v[40:43]
	v_mfma_f32_16x16x32_bf16 v[40:43], v[184:187], v[224:227], v[40:43]
	v_mfma_f32_16x16x32_bf16 v[24:27], v[180:183], v[228:231], v[24:27]
	v_mfma_f32_16x16x32_bf16 v[24:27], v[184:187], v[232:235], v[24:27]
	v_mfma_f32_16x16x32_bf16 v[8:11], v[180:183], v[236:239], v[8:11]
	v_mfma_f32_16x16x32_bf16 v[8:11], v[184:187], v[240:243], v[8:11]
	v_mfma_f32_16x16x32_bf16 v[48:51], v[188:191], v[212:215], v[48:51]
	v_mfma_f32_16x16x32_bf16 v[48:51], v[244:247], v[216:219], v[48:51]
	v_mfma_f32_16x16x32_bf16 v[32:35], v[188:191], v[220:223], v[32:35]
	v_mfma_f32_16x16x32_bf16 v[32:35], v[244:247], v[224:227], v[32:35]
	v_mfma_f32_16x16x32_bf16 v[16:19], v[188:191], v[228:231], v[16:19]
	v_mfma_f32_16x16x32_bf16 v[16:19], v[244:247], v[232:235], v[16:19]
	v_mfma_f32_16x16x32_bf16 v[0:3], v[188:191], v[236:239], v[0:3]
	v_mfma_f32_16x16x32_bf16 v[0:3], v[244:247], v[240:243], v[0:3]
	s_setprio 0
	s_barrier
	s_add_i32 s53, s53, 2
	s_add_u32 s14, s14, 0x100
	s_addc_u32 s15, s15, 0
	s_add_u32 s51, s51, 0x100
	s_addc_u32 s52, s52, 0
	s_cmp_gt_u32 s53, 13
	s_cbranch_scc0 .LBB0_446
	s_and_b64 vcc, exec, s[2:3]
	s_cbranch_vccz .LBB0_449
	s_barrier

; #define PG8_STAGE(bufoff, gbase, voff) do { _Pragma("unroll") for (int _i = 0; _i < 2; ++_i) \
;         __builtin_amdgcn_global_load_lds((const unsigned*)((const char*)(gbase) + (voff)[_i]), (PG8_LAS unsigned*)(lds + (bufoff) + ldsw + _i * 8192), 16, 0, 0); } while (0)
; #define PG8_LDA(dst, b, h) do { _Pragma("unroll") for (int m = 0; m < 4; ++m) _Pragma("unroll") for (int k = 0; k < 2; ++k) dst[m][k] = *(const PG8_LAS bf16x8*)(lds + PG8_SA(b, h) + aoff + m * 2048 + k * 1024); } while (0)
; #define PG8_LDB(dst, b, h) do { _Pragma("unroll") for (int n = 0; n < 2; ++n) _Pragma("unroll") for (int k = 0; k < 2; ++k) dst[n][k] = *(const PG8_LAS bf16x8*)(lds + PG8_SB(b, h) + boff + n * 2048 + k * 1024); } while (0)
; #define PG8_MMA(ai, bj, At, Bt) do { __builtin_amdgcn_s_setprio(1); _Pragma("unroll") for (int m = 0; m < 4; ++m) _Pragma("unroll") for (int n = 0; n < 2; ++n) _Pragma("unroll") for (int k = 0; k < 2; ++k) \
;         acc[ai][bj][m][n] = __builtin_amdgcn_mfma_f32_16x16x32_bf16(Bt[n][k], At[m][k], acc[ai][bj][m][n], 0, 0, 0); __builtin_amdgcn_s_setprio(0); } while (0)
; #define PG8_WAIT_V(n) asm volatile("s_waitcnt vmcnt(" #n ")" ::: "memory")
; #define PG8_WAIT_L(n) asm volatile("s_waitcnt lgkmcnt(" #n ")" ::: "memory")
; #define PG8_BAR __builtin_amdgcn_s_barrier()
; #define PG8_SCHED __builtin_amdgcn_sched_barrier(0)
; template <class Epi, class Sched, bool ALIGN_EPI = false, bool SP2 = false>
; __device__ __forceinline__ void gemm_phase(PG8_LAS unsigned char* lds, const Gemm g, const Sched& S, const Epi& E) {
;     ...
;             PG8_LDB(B0, 0, 0); PG8_LDB(B1, 0, 1); PG8_SCHED; PG8_LDA(At, 0, 0); PG8_STAGE(PG8_SA(1, 1), a1 + hstep, voffA);
;             PG8_WAIT_V(8); PG8_WAIT_L(0); PG8_BAR; PG8_MMA(0, 0, At, B0); PG8_MMA(0, 1, At, B1); PG8_BAR; PG8_SCHED;
;             PG8_LDA(At, 0, 1); PG8_STAGE(PG8_SB(0, 0), b2, voffB); PG8_STAGE(PG8_SB(0, 1), b2 + hstep, voffB); PG8_STAGE(PG8_SA(0, 0), a2, voffA);
;             PG8_WAIT_V(8); PG8_WAIT_L(0); PG8_BAR; PG8_MMA(1, 0, At, B0); PG8_MMA(1, 1, At, B1); PG8_BAR; PG8_SCHED;
;     ...
; #pragma unroll
;         for (int a = 0; a < 2; ++a)
; #pragma unroll
;             for (int b = 0; b < 2; ++b)
; #pragma unroll
;                 for (int m = 0; m < 4; ++m)
; #pragma unroll
;                     for (int n = 0; n < 2; ++n) acc[a][b][m][n] = (f32x4){0.f, 0.f, 0.f, 0.f};
.Ldn_peel:
	ds_read_b128 v[128:131], v254
	ds_read_b128 v[132:135], v254 offset:1024
	ds_read_b128 v[136:139], v254 offset:2048
	ds_read_b128 v[140:143], v254 offset:3072
	ds_read_b128 v[174:177], v254 offset:16384
	ds_read_b128 v[184:187], v254 offset:17408
	ds_read_b128 v[188:191], v254 offset:18432
	ds_read_b128 v[244:247], v254 offset:19456
	s_add_u32 s2, s0, 0x100
	s_addc_u32 s3, s1, 0
	s_cmp_eq_u32 s13, 40
	s_cselect_b32 s7, s27, s3
	s_cselect_b32 s6, s26, s2
	s_cselect_b32 s5, s37, s11
	s_cselect_b32 s4, s36, s10
	s_add_i32 m0, s29, 0xc000
	ds_read_b128 v[212:215], v181
	ds_read_b128 v[216:219], v181 offset:1024
	ds_read_b128 v[220:223], v181 offset:2048
	ds_read_b128 v[224:227], v181 offset:3072
	ds_read_b128 v[228:231], v181 offset:4096
	ds_read_b128 v[232:235], v181 offset:5120
	ds_read_b128 v[236:239], v181 offset:6144
	ds_read_b128 v[240:243], v181 offset:7168
	global_load_lds_dwordx4 v170, s[0:1]
	s_add_i32 m0, s29, 0xe000
	s_nop 0
	global_load_lds_dwordx4 v172, s[0:1]
	s_waitcnt vmcnt(8)
	s_waitcnt lgkmcnt(0)
	s_barrier
	s_setprio 1
	v_mfma_f32_16x16x32_bf16 v[124:127], v[128:131], v[212:215], 0
	v_mfma_f32_16x16x32_bf16 v[124:127], v[132:135], v[216:219], v[124:127]
	v_mfma_f32_16x16x32_bf16 v[108:111], v[128:131], v[220:223], 0
	v_mfma_f32_16x16x32_bf16 v[108:111], v[132:135], v[224:227], v[108:111]
	v_mfma_f32_16x16x32_bf16 v[92:95], v[128:131], v[228:231], 0
	v_mfma_f32_16x16x32_bf16 v[92:95], v[132:135], v[232:235], v[92:95]
	v_mfma_f32_16x16x32_bf16 v[76:79], v[128:131], v[236:239], 0
	v_mfma_f32_16x16x32_bf16 v[76:79], v[132:135], v[240:243], v[76:79]
	v_mfma_f32_16x16x32_bf16 v[120:123], v[136:139], v[212:215], 0
	v_mfma_f32_16x16x32_bf16 v[120:123], v[140:143], v[216:219], v[120:123]
	v_mfma_f32_16x16x32_bf16 v[104:107], v[136:139], v[220:223], 0
	v_mfma_f32_16x16x32_bf16 v[104:107], v[140:143], v[224:227], v[104:107]
	v_mfma_f32_16x16x32_bf16 v[88:91], v[136:139], v[228:231], 0
	v_mfma_f32_16x16x32_bf16 v[88:91], v[140:143], v[232:235], v[88:91]
	v_mfma_f32_16x16x32_bf16 v[72:75], v[136:139], v[236:239], 0
	v_mfma_f32_16x16x32_bf16 v[72:75], v[140:143], v[240:243], v[72:75]
	v_mfma_f32_16x16x32_bf16 v[116:119], v[174:177], v[212:215], 0
	v_mfma_f32_16x16x32_bf16 v[116:119], v[184:187], v[216:219], v[116:119]
	v_mfma_f32_16x16x32_bf16 v[100:103], v[174:177], v[220:223], 0
	v_mfma_f32_16x16x32_bf16 v[100:103], v[184:187], v[224:227], v[100:103]
	v_mfma_f32_16x16x32_bf16 v[84:87], v[174:177], v[228:231], 0
	v_mfma_f32_16x16x32_bf16 v[84:87], v[184:187], v[232:235], v[84:87]
	v_mfma_f32_16x16x32_bf16 v[68:71], v[174:177], v[236:239], 0
	v_mfma_f32_16x16x32_bf16 v[68:71], v[184:187], v[240:243], v[68:71]
	v_mfma_f32_16x16x32_bf16 v[112:115], v[188:191], v[212:215], 0
	v_mfma_f32_16x16x32_bf16 v[112:115], v[244:247], v[216:219], v[112:115]
	v_mfma_f32_16x16x32_bf16 v[96:99], v[188:191], v[220:223], 0
	v_mfma_f32_16x16x32_bf16 v[96:99], v[244:247], v[224:227], v[96:99]
	v_mfma_f32_16x16x32_bf16 v[80:83], v[188:191], v[228:231], 0
	v_mfma_f32_16x16x32_bf16 v[80:83], v[244:247], v[232:235], v[80:83]
	v_mfma_f32_16x16x32_bf16 v[64:67], v[188:191], v[236:239], 0
	v_mfma_f32_16x16x32_bf16 v[64:67], v[244:247], v[240:243], v[64:67]
	s_setprio 0
	s_barrier
	s_mov_b32 m0, s35
	s_add_u32 s0, s4, 0xb0000
	s_addc_u32 s1, s5, 0
	ds_read_b128 v[212:215], v181 offset:16384
	ds_read_b128 v[216:219], v181 offset:17408
	ds_read_b128 v[220:223], v181 offset:18432
	ds_read_b128 v[224:227], v181 offset:19456
	ds_read_b128 v[228:231], v181 offset:20480
	ds_read_b128 v[232:235], v181 offset:21504
	ds_read_b128 v[236:239], v181 offset:22528
	ds_read_b128 v[240:243], v181 offset:23552
	global_load_lds_dwordx4 v166, s[4:5]
	s_mov_b32 m0, s38
	s_nop 0
	global_load_lds_dwordx4 v162, s[4:5]
	s_mov_b32 m0, s39
	s_nop 0
	global_load_lds_dwordx4 v166, s[0:1]
	s_mov_b32 m0, s40
	s_nop 0
	global_load_lds_dwordx4 v162, s[0:1]
	s_mov_b32 m0, s29
	s_nop 0
	global_load_lds_dwordx4 v168, s[6:7]
	s_mov_b32 m0, s41
	s_nop 0
	global_load_lds_dwordx4 v164, s[6:7]
	s_waitcnt vmcnt(8)
	s_waitcnt lgkmcnt(0)
	s_barrier
	s_setprio 1
	v_mfma_f32_16x16x32_bf16 v[60:63], v[128:131], v[212:215], 0
	v_mfma_f32_16x16x32_bf16 v[60:63], v[132:135], v[216:219], v[60:63]
	v_mfma_f32_16x16x32_bf16 v[44:47], v[128:131], v[220:223], 0
	v_mfma_f32_16x16x32_bf16 v[44:47], v[132:135], v[224:227], v[44:47]
	v_mfma_f32_16x16x32_bf16 v[28:31], v[128:131], v[228:231], 0
	v_mfma_f32_16x16x32_bf16 v[28:31], v[132:135], v[232:235], v[28:31]
	v_mfma_f32_16x16x32_bf16 v[12:15], v[128:131], v[236:239], 0
	v_mfma_f32_16x16x32_bf16 v[12:15], v[132:135], v[240:243], v[12:15]
	v_mfma_f32_16x16x32_bf16 v[56:59], v[136:139], v[212:215], 0
	v_mfma_f32_16x16x32_bf16 v[56:59], v[140:143], v[216:219], v[56:59]
	v_mfma_f32_16x16x32_bf16 v[40:43], v[136:139], v[220:223], 0
	v_mfma_f32_16x16x32_bf16 v[40:43], v[140:143], v[224:227], v[40:43]
	v_mfma_f32_16x16x32_bf16 v[24:27], v[136:139], v[228:231], 0
	v_mfma_f32_16x16x32_bf16 v[24:27], v[140:143], v[232:235], v[24:27]
	v_mfma_f32_16x16x32_bf16 v[8:11], v[136:139], v[236:239], 0
	v_mfma_f32_16x16x32_bf16 v[8:11], v[140:143], v[240:243], v[8:11]
	v_mfma_f32_16x16x32_bf16 v[52:55], v[174:177], v[212:215], 0
	v_mfma_f32_16x16x32_bf16 v[52:55], v[184:187], v[216:219], v[52:55]
	v_mfma_f32_16x16x32_bf16 v[36:39], v[174:177], v[220:223], 0
	v_mfma_f32_16x16x32_bf16 v[36:39], v[184:187], v[224:227], v[36:39]
	v_mfma_f32_16x16x32_bf16 v[20:23], v[174:177], v[228:231], 0
	v_mfma_f32_16x16x32_bf16 v[20:23], v[184:187], v[232:235], v[20:23]
	v_mfma_f32_16x16x32_bf16 v[4:7], v[174:177], v[236:239], 0
	v_mfma_f32_16x16x32_bf16 v[4:7], v[184:187], v[240:243], v[4:7]
	v_mfma_f32_16x16x32_bf16 v[48:51], v[188:191], v[212:215], 0
	v_mfma_f32_16x16x32_bf16 v[48:51], v[244:247], v[216:219], v[48:51]
	v_mfma_f32_16x16x32_bf16 v[32:35], v[188:191], v[220:223], 0
	v_mfma_f32_16x16x32_bf16 v[32:35], v[244:247], v[224:227], v[32:35]
	v_mfma_f32_16x16x32_bf16 v[16:19], v[188:191], v[228:231], 0
	v_mfma_f32_16x16x32_bf16 v[16:19], v[244:247], v[232:235], v[16:19]
	v_mfma_f32_16x16x32_bf16 v[0:3], v[188:191], v[236:239], 0
	v_mfma_f32_16x16x32_bf16 v[0:3], v[244:247], v[240:243], v[0:3]
	s_setprio 0
	s_barrier
; #define PG8_STAGE(bufoff, gbase, voff) do { _Pragma("unroll") for (int _i = 0; _i < 2; ++_i) \
;         __builtin_amdgcn_global_load_lds((const unsigned*)((const char*)(gbase) + (voff)[_i]), (PG8_LAS unsigned*)(lds + (bufoff) + ldsw + _i * 8192), 16, 0, 0); } while (0)
; #define PG8_LDA(dst, b, h) do { _Pragma("unroll") for (int m = 0; m < 4; ++m) _Pragma("unroll") for (int k = 0; k < 2; ++k) dst[m][k] = *(const PG8_LAS bf16x8*)(lds + PG8_SA(b, h) + aoff + m * 2048 + k * 1024); } while (0)
; #define PG8_LDB(dst, b, h) do { _Pragma("unroll") for (int n = 0; n < 2; ++n) _Pragma("unroll") for (int k = 0; k < 2; ++k) dst[n][k] = *(const PG8_LAS bf16x8*)(lds + PG8_SB(b, h) + boff + n * 2048 + k * 1024); } while (0)
; #define PG8_MMA(ai, bj, At, Bt) do { __builtin_amdgcn_s_setprio(1); _Pragma("unroll") for (int m = 0; m < 4; ++m) _Pragma("unroll") for (int n = 0; n < 2; ++n) _Pragma("unroll") for (int k = 0; k < 2; ++k) \
;         acc[ai][bj][m][n] = __builtin_amdgcn_mfma_f32_16x16x32_bf16(Bt[n][k], At[m][k], acc[ai][bj][m][n], 0, 0, 0); __builtin_amdgcn_s_setprio(0); } while (0)
; #define PG8_WAIT_V(n) asm volatile("s_waitcnt vmcnt(" #n ")" ::: "memory")
; #define PG8_WAIT_L(n) asm volatile("s_waitcnt lgkmcnt(" #n ")" ::: "memory")
; #define PG8_BAR __builtin_amdgcn_s_barrier()
; #define PG8_SCHED __builtin_amdgcn_sched_barrier(0)
; template <class Epi, class Sched, bool ALIGN_EPI = false, bool SP2 = false>
; __device__ __forceinline__ void gemm_phase(PG8_LAS unsigned char* lds, const Gemm g, const Sched& S, const Epi& E) {
;     ...
;             PG8_LDB(B0, 1, 0); PG8_LDB(B1, 1, 1); PG8_SCHED; PG8_LDA(At, 1, 0); PG8_STAGE(PG8_SA(0, 1), a2 + hstep, voffA);
;             PG8_WAIT_V(8); PG8_WAIT_L(0); PG8_BAR; PG8_MMA(0, 0, At, B0); PG8_MMA(0, 1, At, B1); PG8_BAR; PG8_SCHED;
;             PG8_LDA(At, 1, 1); PG8_STAGE(PG8_SB(1, 0), b3, voffB); PG8_STAGE(PG8_SB(1, 1), b3 + hstep, voffB); PG8_STAGE(PG8_SA(1, 0), a3, voffA);
;             PG8_WAIT_V(8); PG8_WAIT_L(0); PG8_BAR; PG8_MMA(1, 0, At, B0); PG8_MMA(1, 1, At, B1); PG8_BAR; PG8_SCHED;
	ds_read_b128 v[128:131], v254 offset:32768
	ds_read_b128 v[132:135], v254 offset:33792
	ds_read_b128 v[136:139], v254 offset:34816
	ds_read_b128 v[140:143], v254 offset:35840
	ds_read_b128 v[174:177], v254 offset:49152
	ds_read_b128 v[184:187], v254 offset:50176
	ds_read_b128 v[188:191], v254 offset:51200
	ds_read_b128 v[244:247], v254 offset:52224
	s_add_u32 s0, s6, 0xb0000
	s_addc_u32 s1, s7, 0
	s_mov_b32 m0, s42
	ds_read_b128 v[212:215], v181 offset:32768
	ds_read_b128 v[216:219], v181 offset:33792
	ds_read_b128 v[220:223], v181 offset:34816
	ds_read_b128 v[224:227], v181 offset:35840
	ds_read_b128 v[228:231], v181 offset:36864
	ds_read_b128 v[232:235], v181 offset:37888
	ds_read_b128 v[236:239], v181 offset:38912
	ds_read_b128 v[240:243], v181 offset:39936
	global_load_lds_dwordx4 v168, s[0:1]
	s_mov_b32 m0, s43
	s_nop 0
	global_load_lds_dwordx4 v164, s[0:1]
	s_waitcnt vmcnt(8)
	s_waitcnt lgkmcnt(0)
	s_barrier
	s_setprio 1
	v_mfma_f32_16x16x32_bf16 v[124:127], v[128:131], v[212:215], v[124:127]
	v_mfma_f32_16x16x32_bf16 v[124:127], v[132:135], v[216:219], v[124:127]
	v_mfma_f32_16x16x32_bf16 v[108:111], v[128:131], v[220:223], v[108:111]
	v_mfma_f32_16x16x32_bf16 v[108:111], v[132:135], v[224:227], v[108:111]
	v_mfma_f32_16x16x32_bf16 v[92:95], v[128:131], v[228:231], v[92:95]
	v_mfma_f32_16x16x32_bf16 v[92:95], v[132:135], v[232:235], v[92:95]
	v_mfma_f32_16x16x32_bf16 v[76:79], v[128:131], v[236:239], v[76:79]
	v_mfma_f32_16x16x32_bf16 v[76:79], v[132:135], v[240:243], v[76:79]
	v_mfma_f32_16x16x32_bf16 v[120:123], v[136:139], v[212:215], v[120:123]
	v_mfma_f32_16x16x32_bf16 v[120:123], v[140:143], v[216:219], v[120:123]
	v_mfma_f32_16x16x32_bf16 v[104:107], v[136:139], v[220:223], v[104:107]
	v_mfma_f32_16x16x32_bf16 v[104:107], v[140:143], v[224:227], v[104:107]
	v_mfma_f32_16x16x32_bf16 v[88:91], v[136:139], v[228:231], v[88:91]
	v_mfma_f32_16x16x32_bf16 v[88:91], v[140:143], v[232:235], v[88:91]
	v_mfma_f32_16x16x32_bf16 v[72:75], v[136:139], v[236:239], v[72:75]
	v_mfma_f32_16x16x32_bf16 v[72:75], v[140:143], v[240:243], v[72:75]
	v_mfma_f32_16x16x32_bf16 v[116:119], v[174:177], v[212:215], v[116:119]
	v_mfma_f32_16x16x32_bf16 v[116:119], v[184:187], v[216:219], v[116:119]
	v_mfma_f32_16x16x32_bf16 v[100:103], v[174:177], v[220:223], v[100:103]
	v_mfma_f32_16x16x32_bf16 v[100:103], v[184:187], v[224:227], v[100:103]
	v_mfma_f32_16x16x32_bf16 v[84:87], v[174:177], v[228:231], v[84:87]
	v_mfma_f32_16x16x32_bf16 v[84:87], v[184:187], v[232:235], v[84:87]
	v_mfma_f32_16x16x32_bf16 v[68:71], v[174:177], v[236:239], v[68:71]
	v_mfma_f32_16x16x32_bf16 v[68:71], v[184:187], v[240:243], v[68:71]
	v_mfma_f32_16x16x32_bf16 v[112:115], v[188:191], v[212:215], v[112:115]
	v_mfma_f32_16x16x32_bf16 v[112:115], v[244:247], v[216:219], v[112:115]
	v_mfma_f32_16x16x32_bf16 v[96:99], v[188:191], v[220:223], v[96:99]
	v_mfma_f32_16x16x32_bf16 v[96:99], v[244:247], v[224:227], v[96:99]
	v_mfma_f32_16x16x32_bf16 v[80:83], v[188:191], v[228:231], v[80:83]
	v_mfma_f32_16x16x32_bf16 v[80:83], v[244:247], v[232:235], v[80:83]
	v_mfma_f32_16x16x32_bf16 v[64:67], v[188:191], v[236:239], v[64:67]
	v_mfma_f32_16x16x32_bf16 v[64:67], v[244:247], v[240:243], v[64:67]
	s_setprio 0
	s_barrier
	s_mov_b32 m0, s47
	s_add_u32 s0, s4, 0xb0080
	s_addc_u32 s1, s5, 0
	ds_read_b128 v[212:215], v181 offset:49152
	ds_read_b128 v[216:219], v181 offset:50176
	ds_read_b128 v[220:223], v181 offset:51200
	ds_read_b128 v[224:227], v181 offset:52224
	ds_read_b128 v[228:231], v181 offset:53248
	ds_read_b128 v[232:235], v181 offset:54272
	ds_read_b128 v[236:239], v181 offset:55296
	ds_read_b128 v[240:243], v181 offset:56320
	s_add_u32 s98, s4, 0x80
	s_addc_u32 s99, s5, 0
	global_load_lds_dwordx4 v166, s[98:99]
	s_mov_b32 m0, s48
	s_nop 0
	global_load_lds_dwordx4 v162, s[98:99]
	s_mov_b32 m0, s51
	s_nop 0
	global_load_lds_dwordx4 v166, s[0:1]
	s_mov_b32 m0, s52
	s_nop 0
	global_load_lds_dwordx4 v162, s[0:1]
	s_mov_b32 m0, s49
	s_nop 0
	s_add_u32 s100, s6, 0x80
	s_addc_u32 s101, s7, 0
	global_load_lds_dwordx4 v168, s[100:101]
	s_mov_b32 m0, s50
	s_nop 0
	global_load_lds_dwordx4 v164, s[100:101]
	s_waitcnt vmcnt(8)
	s_waitcnt lgkmcnt(0)
	s_barrier
	s_setprio 1
	v_mfma_f32_16x16x32_bf16 v[60:63], v[128:131], v[212:215], v[60:63]
	v_mfma_f32_16x16x32_bf16 v[60:63], v[132:135], v[216:219], v[60:63]
	v_mfma_f32_16x16x32_bf16 v[44:47], v[128:131], v[220:223], v[44:47]
	v_mfma_f32_16x16x32_bf16 v[44:47], v[132:135], v[224:227], v[44:47]
	v_mfma_f32_16x16x32_bf16 v[28:31], v[128:131], v[228:231], v[28:31]
	v_mfma_f32_16x16x32_bf16 v[28:31], v[132:135], v[232:235], v[28:31]
	v_mfma_f32_16x16x32_bf16 v[12:15], v[128:131], v[236:239], v[12:15]
	v_mfma_f32_16x16x32_bf16 v[12:15], v[132:135], v[240:243], v[12:15]
	v_mfma_f32_16x16x32_bf16 v[56:59], v[136:139], v[212:215], v[56:59]
	v_mfma_f32_16x16x32_bf16 v[56:59], v[140:143], v[216:219], v[56:59]
	v_mfma_f32_16x16x32_bf16 v[40:43], v[136:139], v[220:223], v[40:43]
	v_mfma_f32_16x16x32_bf16 v[40:43], v[140:143], v[224:227], v[40:43]
	v_mfma_f32_16x16x32_bf16 v[24:27], v[136:139], v[228:231], v[24:27]
	v_mfma_f32_16x16x32_bf16 v[24:27], v[140:143], v[232:235], v[24:27]
	v_mfma_f32_16x16x32_bf16 v[8:11], v[136:139], v[236:239], v[8:11]
	v_mfma_f32_16x16x32_bf16 v[8:11], v[140:143], v[240:243], v[8:11]
	v_mfma_f32_16x16x32_bf16 v[52:55], v[174:177], v[212:215], v[52:55]
	v_mfma_f32_16x16x32_bf16 v[52:55], v[184:187], v[216:219], v[52:55]
	v_mfma_f32_16x16x32_bf16 v[36:39], v[174:177], v[220:223], v[36:39]
	v_mfma_f32_16x16x32_bf16 v[36:39], v[184:187], v[224:227], v[36:39]
	v_mfma_f32_16x16x32_bf16 v[20:23], v[174:177], v[228:231], v[20:23]
	v_mfma_f32_16x16x32_bf16 v[20:23], v[184:187], v[232:235], v[20:23]
	v_mfma_f32_16x16x32_bf16 v[4:7], v[174:177], v[236:239], v[4:7]
	v_mfma_f32_16x16x32_bf16 v[4:7], v[184:187], v[240:243], v[4:7]
	v_mfma_f32_16x16x32_bf16 v[48:51], v[188:191], v[212:215], v[48:51]
	v_mfma_f32_16x16x32_bf16 v[48:51], v[244:247], v[216:219], v[48:51]
	v_mfma_f32_16x16x32_bf16 v[32:35], v[188:191], v[220:223], v[32:35]
	v_mfma_f32_16x16x32_bf16 v[32:35], v[244:247], v[224:227], v[32:35]
	v_mfma_f32_16x16x32_bf16 v[16:19], v[188:191], v[228:231], v[16:19]
	v_mfma_f32_16x16x32_bf16 v[16:19], v[244:247], v[232:235], v[16:19]
	v_mfma_f32_16x16x32_bf16 v[0:3], v[188:191], v[236:239], v[0:3]
	v_mfma_f32_16x16x32_bf16 v[0:3], v[244:247], v[240:243], v[0:3]
	s_setprio 0
	s_barrier
	s_add_i32 s13, s13, 2
	s_add_u32 s10, s10, 0x100
	s_addc_u32 s11, s11, 0
	s_cmp_gt_u32 s13, 41
	s_mov_b64 s[0:1], s[2:3]
; #define PG8_STAGE(bufoff, gbase, voff) do { _Pragma("unroll") for (int _i = 0; _i < 2; ++_i) \
;         __builtin_amdgcn_global_load_lds((const unsigned*)((const char*)(gbase) + (voff)[_i]), (PG8_LAS unsigned*)(lds + (bufoff) + ldsw + _i * 8192), 16, 0, 0); } while (0)
; #define PG8_LDA(dst, b, h) do { _Pragma("unroll") for (int m = 0; m < 4; ++m) _Pragma("unroll") for (int k = 0; k < 2; ++k) dst[m][k] = *(const PG8_LAS bf16x8*)(lds + PG8_SA(b, h) + aoff + m * 2048 + k * 1024); } while (0)
; #define PG8_LDB(dst, b, h) do { _Pragma("unroll") for (int n = 0; n < 2; ++n) _Pragma("unroll") for (int k = 0; k < 2; ++k) dst[n][k] = *(const PG8_LAS bf16x8*)(lds + PG8_SB(b, h) + boff + n * 2048 + k * 1024); } while (0)
; #define PG8_MMA(ai, bj, At, Bt) do { __builtin_amdgcn_s_setprio(1); _Pragma("unroll") for (int m = 0; m < 4; ++m) _Pragma("unroll") for (int n = 0; n < 2; ++n) _Pragma("unroll") for (int k = 0; k < 2; ++k) \
;         acc[ai][bj][m][n] = __builtin_amdgcn_mfma_f32_16x16x32_bf16(Bt[n][k], At[m][k], acc[ai][bj][m][n], 0, 0, 0); __builtin_amdgcn_s_setprio(0); } while (0)
; #define PG8_WAIT_V(n) asm volatile("s_waitcnt vmcnt(" #n ")" ::: "memory")
; #define PG8_WAIT_L(n) asm volatile("s_waitcnt lgkmcnt(" #n ")" ::: "memory")
; #define PG8_BAR __builtin_amdgcn_s_barrier()
; #define PG8_SCHED __builtin_amdgcn_sched_barrier(0)
; template <class Epi, class Sched, bool ALIGN_EPI = false, bool SP2 = false>
; __device__ __forceinline__ void gemm_phase(PG8_LAS unsigned char* lds, const Gemm g, const Sched& S, const Epi& E) {
;     ...
;             PG8_LDB(B0, 0, 0); PG8_LDB(B1, 0, 1); PG8_SCHED; PG8_LDA(At, 0, 0); PG8_STAGE(PG8_SA(1, 1), a1 + hstep, voffA);
;             PG8_WAIT_V(8); PG8_WAIT_L(0); PG8_BAR; PG8_MMA(0, 0, At, B0); PG8_MMA(0, 1, At, B1); PG8_BAR; PG8_SCHED;
;             PG8_LDA(At, 0, 1); PG8_STAGE(PG8_SB(0, 0), b2, voffB); PG8_STAGE(PG8_SB(0, 1), b2 + hstep, voffB); PG8_STAGE(PG8_SA(0, 0), a2, voffA);
;             PG8_WAIT_V(8); PG8_WAIT_L(0); PG8_BAR; PG8_MMA(1, 0, At, B0); PG8_MMA(1, 1, At, B1); PG8_BAR; PG8_SCHED;
.LBB0_545:
	ds_read_b128 v[128:131], v254
	ds_read_b128 v[132:135], v254 offset:1024
	ds_read_b128 v[136:139], v254 offset:2048
	ds_read_b128 v[140:143], v254 offset:3072
	ds_read_b128 v[174:177], v254 offset:16384
	ds_read_b128 v[184:187], v254 offset:17408
	ds_read_b128 v[188:191], v254 offset:18432
	ds_read_b128 v[244:247], v254 offset:19456
	s_add_u32 s2, s0, 0x100
	s_addc_u32 s3, s1, 0
	s_cmp_eq_u32 s13, 40
	s_cselect_b32 s7, s27, s3
	s_cselect_b32 s6, s26, s2
	s_cselect_b32 s5, s37, s11
	s_cselect_b32 s4, s36, s10
	s_add_i32 m0, s29, 0xc000
	ds_read_b128 v[212:215], v181
	ds_read_b128 v[216:219], v181 offset:1024
	ds_read_b128 v[220:223], v181 offset:2048
	ds_read_b128 v[224:227], v181 offset:3072
	ds_read_b128 v[228:231], v181 offset:4096
	ds_read_b128 v[232:235], v181 offset:5120
	ds_read_b128 v[236:239], v181 offset:6144
	ds_read_b128 v[240:243], v181 offset:7168
	global_load_lds_dwordx4 v170, s[0:1]
	s_add_i32 m0, s29, 0xe000
	s_nop 0
	global_load_lds_dwordx4 v172, s[0:1]
	s_waitcnt vmcnt(8)
	s_waitcnt lgkmcnt(0)
	s_barrier
	s_setprio 1
	v_mfma_f32_16x16x32_bf16 v[124:127], v[128:131], v[212:215], v[124:127]
	v_mfma_f32_16x16x32_bf16 v[124:127], v[132:135], v[216:219], v[124:127]
	v_mfma_f32_16x16x32_bf16 v[108:111], v[128:131], v[220:223], v[108:111]
	v_mfma_f32_16x16x32_bf16 v[108:111], v[132:135], v[224:227], v[108:111]
	v_mfma_f32_16x16x32_bf16 v[92:95], v[128:131], v[228:231], v[92:95]
	v_mfma_f32_16x16x32_bf16 v[92:95], v[132:135], v[232:235], v[92:95]
	v_mfma_f32_16x16x32_bf16 v[76:79], v[128:131], v[236:239], v[76:79]
	v_mfma_f32_16x16x32_bf16 v[76:79], v[132:135], v[240:243], v[76:79]
	v_mfma_f32_16x16x32_bf16 v[120:123], v[136:139], v[212:215], v[120:123]
	v_mfma_f32_16x16x32_bf16 v[120:123], v[140:143], v[216:219], v[120:123]
	v_mfma_f32_16x16x32_bf16 v[104:107], v[136:139], v[220:223], v[104:107]
	v_mfma_f32_16x16x32_bf16 v[104:107], v[140:143], v[224:227], v[104:107]
	v_mfma_f32_16x16x32_bf16 v[88:91], v[136:139], v[228:231], v[88:91]
	v_mfma_f32_16x16x32_bf16 v[88:91], v[140:143], v[232:235], v[88:91]
	v_mfma_f32_16x16x32_bf16 v[72:75], v[136:139], v[236:239], v[72:75]
	v_mfma_f32_16x16x32_bf16 v[72:75], v[140:143], v[240:243], v[72:75]
	v_mfma_f32_16x16x32_bf16 v[116:119], v[174:177], v[212:215], v[116:119]
	v_mfma_f32_16x16x32_bf16 v[116:119], v[184:187], v[216:219], v[116:119]
	v_mfma_f32_16x16x32_bf16 v[100:103], v[174:177], v[220:223], v[100:103]
	v_mfma_f32_16x16x32_bf16 v[100:103], v[184:187], v[224:227], v[100:103]
	v_mfma_f32_16x16x32_bf16 v[84:87], v[174:177], v[228:231], v[84:87]
	v_mfma_f32_16x16x32_bf16 v[84:87], v[184:187], v[232:235], v[84:87]
	v_mfma_f32_16x16x32_bf16 v[68:71], v[174:177], v[236:239], v[68:71]
	v_mfma_f32_16x16x32_bf16 v[68:71], v[184:187], v[240:243], v[68:71]
	v_mfma_f32_16x16x32_bf16 v[112:115], v[188:191], v[212:215], v[112:115]
	v_mfma_f32_16x16x32_bf16 v[112:115], v[244:247], v[216:219], v[112:115]
	v_mfma_f32_16x16x32_bf16 v[96:99], v[188:191], v[220:223], v[96:99]
	v_mfma_f32_16x16x32_bf16 v[96:99], v[244:247], v[224:227], v[96:99]
	v_mfma_f32_16x16x32_bf16 v[80:83], v[188:191], v[228:231], v[80:83]
	v_mfma_f32_16x16x32_bf16 v[80:83], v[244:247], v[232:235], v[80:83]
	v_mfma_f32_16x16x32_bf16 v[64:67], v[188:191], v[236:239], v[64:67]
	v_mfma_f32_16x16x32_bf16 v[64:67], v[244:247], v[240:243], v[64:67]
	s_setprio 0
	s_barrier
	s_mov_b32 m0, s35
	s_add_u32 s0, s4, 0xb0000
	s_addc_u32 s1, s5, 0
	ds_read_b128 v[212:215], v181 offset:16384
	ds_read_b128 v[216:219], v181 offset:17408
	ds_read_b128 v[220:223], v181 offset:18432
	ds_read_b128 v[224:227], v181 offset:19456
	ds_read_b128 v[228:231], v181 offset:20480
	ds_read_b128 v[232:235], v181 offset:21504
	ds_read_b128 v[236:239], v181 offset:22528
	ds_read_b128 v[240:243], v181 offset:23552
	global_load_lds_dwordx4 v166, s[4:5]
	s_mov_b32 m0, s38
	s_nop 0
	global_load_lds_dwordx4 v162, s[4:5]
	s_mov_b32 m0, s39
	s_nop 0
	global_load_lds_dwordx4 v166, s[0:1]
	s_mov_b32 m0, s40
	s_nop 0
	global_load_lds_dwordx4 v162, s[0:1]
	s_mov_b32 m0, s29
	s_nop 0
	global_load_lds_dwordx4 v168, s[6:7]
	s_mov_b32 m0, s41
	s_nop 0
	global_load_lds_dwordx4 v164, s[6:7]
	s_waitcnt vmcnt(8)
	s_waitcnt lgkmcnt(0)
	s_barrier
	s_setprio 1
	v_mfma_f32_16x16x32_bf16 v[60:63], v[128:131], v[212:215], v[60:63]
	v_mfma_f32_16x16x32_bf16 v[60:63], v[132:135], v[216:219], v[60:63]
	v_mfma_f32_16x16x32_bf16 v[44:47], v[128:131], v[220:223], v[44:47]
	v_mfma_f32_16x16x32_bf16 v[44:47], v[132:135], v[224:227], v[44:47]
	v_mfma_f32_16x16x32_bf16 v[28:31], v[128:131], v[228:231], v[28:31]
	v_mfma_f32_16x16x32_bf16 v[28:31], v[132:135], v[232:235], v[28:31]
	v_mfma_f32_16x16x32_bf16 v[12:15], v[128:131], v[236:239], v[12:15]
	v_mfma_f32_16x16x32_bf16 v[12:15], v[132:135], v[240:243], v[12:15]
	v_mfma_f32_16x16x32_bf16 v[56:59], v[136:139], v[212:215], v[56:59]
	v_mfma_f32_16x16x32_bf16 v[56:59], v[140:143], v[216:219], v[56:59]
	v_mfma_f32_16x16x32_bf16 v[40:43], v[136:139], v[220:223], v[40:43]
	v_mfma_f32_16x16x32_bf16 v[40:43], v[140:143], v[224:227], v[40:43]
	v_mfma_f32_16x16x32_bf16 v[24:27], v[136:139], v[228:231], v[24:27]
	v_mfma_f32_16x16x32_bf16 v[24:27], v[140:143], v[232:235], v[24:27]
	v_mfma_f32_16x16x32_bf16 v[8:11], v[136:139], v[236:239], v[8:11]
	v_mfma_f32_16x16x32_bf16 v[8:11], v[140:143], v[240:243], v[8:11]
	v_mfma_f32_16x16x32_bf16 v[52:55], v[174:177], v[212:215], v[52:55]
	v_mfma_f32_16x16x32_bf16 v[52:55], v[184:187], v[216:219], v[52:55]
	v_mfma_f32_16x16x32_bf16 v[36:39], v[174:177], v[220:223], v[36:39]
	v_mfma_f32_16x16x32_bf16 v[36:39], v[184:187], v[224:227], v[36:39]
	v_mfma_f32_16x16x32_bf16 v[20:23], v[174:177], v[228:231], v[20:23]
	v_mfma_f32_16x16x32_bf16 v[20:23], v[184:187], v[232:235], v[20:23]
	v_mfma_f32_16x16x32_bf16 v[4:7], v[174:177], v[236:239], v[4:7]
	v_mfma_f32_16x16x32_bf16 v[4:7], v[184:187], v[240:243], v[4:7]
	v_mfma_f32_16x16x32_bf16 v[48:51], v[188:191], v[212:215], v[48:51]
	v_mfma_f32_16x16x32_bf16 v[48:51], v[244:247], v[216:219], v[48:51]
	v_mfma_f32_16x16x32_bf16 v[32:35], v[188:191], v[220:223], v[32:35]
	v_mfma_f32_16x16x32_bf16 v[32:35], v[244:247], v[224:227], v[32:35]
	v_mfma_f32_16x16x32_bf16 v[16:19], v[188:191], v[228:231], v[16:19]
	v_mfma_f32_16x16x32_bf16 v[16:19], v[244:247], v[232:235], v[16:19]
	v_mfma_f32_16x16x32_bf16 v[0:3], v[188:191], v[236:239], v[0:3]
	v_mfma_f32_16x16x32_bf16 v[0:3], v[244:247], v[240:243], v[0:3]
	s_setprio 0
	s_barrier
; #define PG8_STAGE(bufoff, gbase, voff) do { _Pragma("unroll") for (int _i = 0; _i < 2; ++_i) \
;         __builtin_amdgcn_global_load_lds((const unsigned*)((const char*)(gbase) + (voff)[_i]), (PG8_LAS unsigned*)(lds + (bufoff) + ldsw + _i * 8192), 16, 0, 0); } while (0)
; #define PG8_LDA(dst, b, h) do { _Pragma("unroll") for (int m = 0; m < 4; ++m) _Pragma("unroll") for (int k = 0; k < 2; ++k) dst[m][k] = *(const PG8_LAS bf16x8*)(lds + PG8_SA(b, h) + aoff + m * 2048 + k * 1024); } while (0)
; #define PG8_LDB(dst, b, h) do { _Pragma("unroll") for (int n = 0; n < 2; ++n) _Pragma("unroll") for (int k = 0; k < 2; ++k) dst[n][k] = *(const PG8_LAS bf16x8*)(lds + PG8_SB(b, h) + boff + n * 2048 + k * 1024); } while (0)
; #define PG8_MMA(ai, bj, At, Bt) do { __builtin_amdgcn_s_setprio(1); _Pragma("unroll") for (int m = 0; m < 4; ++m) _Pragma("unroll") for (int n = 0; n < 2; ++n) _Pragma("unroll") for (int k = 0; k < 2; ++k) \
;         acc[ai][bj][m][n] = __builtin_amdgcn_mfma_f32_16x16x32_bf16(Bt[n][k], At[m][k], acc[ai][bj][m][n], 0, 0, 0); __builtin_amdgcn_s_setprio(0); } while (0)
; #define PG8_WAIT_V(n) asm volatile("s_waitcnt vmcnt(" #n ")" ::: "memory")
; #define PG8_WAIT_L(n) asm volatile("s_waitcnt lgkmcnt(" #n ")" ::: "memory")
; #define PG8_BAR __builtin_amdgcn_s_barrier()
; #define PG8_SCHED __builtin_amdgcn_sched_barrier(0)
; template <class Epi, class Sched, bool ALIGN_EPI = false, bool SP2 = false>
; __device__ __forceinline__ void gemm_phase(PG8_LAS unsigned char* lds, const Gemm g, const Sched& S, const Epi& E) {
;     ...
;             PG8_LDB(B0, 1, 0); PG8_LDB(B1, 1, 1); PG8_SCHED; PG8_LDA(At, 1, 0); PG8_STAGE(PG8_SA(0, 1), a2 + hstep, voffA);
;             PG8_WAIT_V(8); PG8_WAIT_L(0); PG8_BAR; PG8_MMA(0, 0, At, B0); PG8_MMA(0, 1, At, B1); PG8_BAR; PG8_SCHED;
;             PG8_LDA(At, 1, 1); PG8_STAGE(PG8_SB(1, 0), b3, voffB); PG8_STAGE(PG8_SB(1, 1), b3 + hstep, voffB); PG8_STAGE(PG8_SA(1, 0), a3, voffA);
;             PG8_WAIT_V(8); PG8_WAIT_L(0); PG8_BAR; PG8_MMA(1, 0, At, B0); PG8_MMA(1, 1, At, B1); PG8_BAR; PG8_SCHED;
	ds_read_b128 v[128:131], v254 offset:32768
	ds_read_b128 v[132:135], v254 offset:33792
	ds_read_b128 v[136:139], v254 offset:34816
	ds_read_b128 v[140:143], v254 offset:35840
	ds_read_b128 v[174:177], v254 offset:49152
	ds_read_b128 v[184:187], v254 offset:50176
	ds_read_b128 v[188:191], v254 offset:51200
	ds_read_b128 v[244:247], v254 offset:52224
	s_add_u32 s0, s6, 0xb0000
	s_addc_u32 s1, s7, 0
	s_mov_b32 m0, s42
	ds_read_b128 v[212:215], v181 offset:32768
	ds_read_b128 v[216:219], v181 offset:33792
	ds_read_b128 v[220:223], v181 offset:34816
	ds_read_b128 v[224:227], v181 offset:35840
	ds_read_b128 v[228:231], v181 offset:36864
	ds_read_b128 v[232:235], v181 offset:37888
	ds_read_b128 v[236:239], v181 offset:38912
	ds_read_b128 v[240:243], v181 offset:39936
	global_load_lds_dwordx4 v168, s[0:1]
	s_mov_b32 m0, s43
	s_nop 0
	global_load_lds_dwordx4 v164, s[0:1]
	s_waitcnt vmcnt(8)
	s_waitcnt lgkmcnt(0)
	s_barrier
	s_setprio 1
	v_mfma_f32_16x16x32_bf16 v[124:127], v[128:131], v[212:215], v[124:127]
	v_mfma_f32_16x16x32_bf16 v[124:127], v[132:135], v[216:219], v[124:127]
	v_mfma_f32_16x16x32_bf16 v[108:111], v[128:131], v[220:223], v[108:111]
	v_mfma_f32_16x16x32_bf16 v[108:111], v[132:135], v[224:227], v[108:111]
	v_mfma_f32_16x16x32_bf16 v[92:95], v[128:131], v[228:231], v[92:95]
	v_mfma_f32_16x16x32_bf16 v[92:95], v[132:135], v[232:235], v[92:95]
	v_mfma_f32_16x16x32_bf16 v[76:79], v[128:131], v[236:239], v[76:79]
	v_mfma_f32_16x16x32_bf16 v[76:79], v[132:135], v[240:243], v[76:79]
	v_mfma_f32_16x16x32_bf16 v[120:123], v[136:139], v[212:215], v[120:123]
	v_mfma_f32_16x16x32_bf16 v[120:123], v[140:143], v[216:219], v[120:123]
	v_mfma_f32_16x16x32_bf16 v[104:107], v[136:139], v[220:223], v[104:107]
	v_mfma_f32_16x16x32_bf16 v[104:107], v[140:143], v[224:227], v[104:107]
	v_mfma_f32_16x16x32_bf16 v[88:91], v[136:139], v[228:231], v[88:91]
	v_mfma_f32_16x16x32_bf16 v[88:91], v[140:143], v[232:235], v[88:91]
	v_mfma_f32_16x16x32_bf16 v[72:75], v[136:139], v[236:239], v[72:75]
	v_mfma_f32_16x16x32_bf16 v[72:75], v[140:143], v[240:243], v[72:75]
	v_mfma_f32_16x16x32_bf16 v[116:119], v[174:177], v[212:215], v[116:119]
	v_mfma_f32_16x16x32_bf16 v[116:119], v[184:187], v[216:219], v[116:119]
	v_mfma_f32_16x16x32_bf16 v[100:103], v[174:177], v[220:223], v[100:103]
	v_mfma_f32_16x16x32_bf16 v[100:103], v[184:187], v[224:227], v[100:103]
	v_mfma_f32_16x16x32_bf16 v[84:87], v[174:177], v[228:231], v[84:87]
	v_mfma_f32_16x16x32_bf16 v[84:87], v[184:187], v[232:235], v[84:87]
	v_mfma_f32_16x16x32_bf16 v[68:71], v[174:177], v[236:239], v[68:71]
	v_mfma_f32_16x16x32_bf16 v[68:71], v[184:187], v[240:243], v[68:71]
	v_mfma_f32_16x16x32_bf16 v[112:115], v[188:191], v[212:215], v[112:115]
	v_mfma_f32_16x16x32_bf16 v[112:115], v[244:247], v[216:219], v[112:115]
	v_mfma_f32_16x16x32_bf16 v[96:99], v[188:191], v[220:223], v[96:99]
	v_mfma_f32_16x16x32_bf16 v[96:99], v[244:247], v[224:227], v[96:99]
	v_mfma_f32_16x16x32_bf16 v[80:83], v[188:191], v[228:231], v[80:83]
	v_mfma_f32_16x16x32_bf16 v[80:83], v[244:247], v[232:235], v[80:83]
	v_mfma_f32_16x16x32_bf16 v[64:67], v[188:191], v[236:239], v[64:67]
	v_mfma_f32_16x16x32_bf16 v[64:67], v[244:247], v[240:243], v[64:67]
	s_setprio 0
	s_barrier
	s_mov_b32 m0, s47
	s_add_u32 s0, s4, 0xb0080
	s_addc_u32 s1, s5, 0
	ds_read_b128 v[212:215], v181 offset:49152
	ds_read_b128 v[216:219], v181 offset:50176
	ds_read_b128 v[220:223], v181 offset:51200
	ds_read_b128 v[224:227], v181 offset:52224
	ds_read_b128 v[228:231], v181 offset:53248
	ds_read_b128 v[232:235], v181 offset:54272
	ds_read_b128 v[236:239], v181 offset:55296
	ds_read_b128 v[240:243], v181 offset:56320
	s_add_u32 s98, s4, 0x80
	s_addc_u32 s99, s5, 0
	global_load_lds_dwordx4 v166, s[98:99]
	s_mov_b32 m0, s48
	s_nop 0
	global_load_lds_dwordx4 v162, s[98:99]
	s_mov_b32 m0, s51
	s_nop 0
	global_load_lds_dwordx4 v166, s[0:1]
	s_mov_b32 m0, s52
	s_nop 0
	global_load_lds_dwordx4 v162, s[0:1]
	s_mov_b32 m0, s49
	s_nop 0
	s_add_u32 s100, s6, 0x80
	s_addc_u32 s101, s7, 0
	global_load_lds_dwordx4 v168, s[100:101]
	s_mov_b32 m0, s50
	s_nop 0
	global_load_lds_dwordx4 v164, s[100:101]
	s_waitcnt vmcnt(8)
	s_waitcnt lgkmcnt(0)
	s_barrier
	s_setprio 1
	v_mfma_f32_16x16x32_bf16 v[60:63], v[128:131], v[212:215], v[60:63]
	v_mfma_f32_16x16x32_bf16 v[60:63], v[132:135], v[216:219], v[60:63]
	v_mfma_f32_16x16x32_bf16 v[44:47], v[128:131], v[220:223], v[44:47]
	v_mfma_f32_16x16x32_bf16 v[44:47], v[132:135], v[224:227], v[44:47]
	v_mfma_f32_16x16x32_bf16 v[28:31], v[128:131], v[228:231], v[28:31]
	v_mfma_f32_16x16x32_bf16 v[28:31], v[132:135], v[232:235], v[28:31]
	v_mfma_f32_16x16x32_bf16 v[12:15], v[128:131], v[236:239], v[12:15]
	v_mfma_f32_16x16x32_bf16 v[12:15], v[132:135], v[240:243], v[12:15]
	v_mfma_f32_16x16x32_bf16 v[56:59], v[136:139], v[212:215], v[56:59]
	v_mfma_f32_16x16x32_bf16 v[56:59], v[140:143], v[216:219], v[56:59]
	v_mfma_f32_16x16x32_bf16 v[40:43], v[136:139], v[220:223], v[40:43]
	v_mfma_f32_16x16x32_bf16 v[40:43], v[140:143], v[224:227], v[40:43]
	v_mfma_f32_16x16x32_bf16 v[24:27], v[136:139], v[228:231], v[24:27]
	v_mfma_f32_16x16x32_bf16 v[24:27], v[140:143], v[232:235], v[24:27]
	v_mfma_f32_16x16x32_bf16 v[8:11], v[136:139], v[236:239], v[8:11]
	v_mfma_f32_16x16x32_bf16 v[8:11], v[140:143], v[240:243], v[8:11]
	v_mfma_f32_16x16x32_bf16 v[52:55], v[174:177], v[212:215], v[52:55]
	v_mfma_f32_16x16x32_bf16 v[52:55], v[184:187], v[216:219], v[52:55]
	v_mfma_f32_16x16x32_bf16 v[36:39], v[174:177], v[220:223], v[36:39]
	v_mfma_f32_16x16x32_bf16 v[36:39], v[184:187], v[224:227], v[36:39]
	v_mfma_f32_16x16x32_bf16 v[20:23], v[174:177], v[228:231], v[20:23]
	v_mfma_f32_16x16x32_bf16 v[20:23], v[184:187], v[232:235], v[20:23]
	v_mfma_f32_16x16x32_bf16 v[4:7], v[174:177], v[236:239], v[4:7]
	v_mfma_f32_16x16x32_bf16 v[4:7], v[184:187], v[240:243], v[4:7]
	v_mfma_f32_16x16x32_bf16 v[48:51], v[188:191], v[212:215], v[48:51]
	v_mfma_f32_16x16x32_bf16 v[48:51], v[244:247], v[216:219], v[48:51]
	v_mfma_f32_16x16x32_bf16 v[32:35], v[188:191], v[220:223], v[32:35]
	v_mfma_f32_16x16x32_bf16 v[32:35], v[244:247], v[224:227], v[32:35]
	v_mfma_f32_16x16x32_bf16 v[16:19], v[188:191], v[228:231], v[16:19]
	v_mfma_f32_16x16x32_bf16 v[16:19], v[244:247], v[232:235], v[16:19]
	v_mfma_f32_16x16x32_bf16 v[0:3], v[188:191], v[236:239], v[0:3]
	v_mfma_f32_16x16x32_bf16 v[0:3], v[244:247], v[240:243], v[0:3]
	s_setprio 0
	s_barrier
	s_add_i32 s13, s13, 2
	s_add_u32 s10, s10, 0x100
	s_addc_u32 s11, s11, 0
	s_cmp_gt_u32 s13, 41
	s_mov_b64 s[0:1], s[2:3]
	s_cbranch_scc0 .LBB0_545
	s_and_b64 vcc, exec, s[22:23]
	s_cbranch_vccz .LBB0_548
	s_barrier

; #define PG8_STAGE(bufoff, gbase, voff) do { _Pragma("unroll") for (int _i = 0; _i < 2; ++_i) \
;         __builtin_amdgcn_global_load_lds((const unsigned*)((const char*)(gbase) + (voff)[_i]), (PG8_LAS unsigned*)(lds + (bufoff) + ldsw + _i * 8192), 16, 0, 0); } while (0)
; #define PG8_LDA(dst, b, h) do { _Pragma("unroll") for (int m = 0; m < 4; ++m) _Pragma("unroll") for (int k = 0; k < 2; ++k) dst[m][k] = *(const PG8_LAS bf16x8*)(lds + PG8_SA(b, h) + aoff + m * 2048 + k * 1024); } while (0)
; #define PG8_LDB(dst, b, h) do { _Pragma("unroll") for (int n = 0; n < 2; ++n) _Pragma("unroll") for (int k = 0; k < 2; ++k) dst[n][k] = *(const PG8_LAS bf16x8*)(lds + PG8_SB(b, h) + boff + n * 2048 + k * 1024); } while (0)
; #define PG8_MMA(ai, bj, At, Bt) do { __builtin_amdgcn_s_setprio(1); _Pragma("unroll") for (int m = 0; m < 4; ++m) _Pragma("unroll") for (int n = 0; n < 2; ++n) _Pragma("unroll") for (int k = 0; k < 2; ++k) \
;         acc[ai][bj][m][n] = __builtin_amdgcn_mfma_f32_16x16x32_bf16(Bt[n][k], At[m][k], acc[ai][bj][m][n], 0, 0, 0); __builtin_amdgcn_s_setprio(0); } while (0)
; #define PG8_WAIT_V(n) asm volatile("s_waitcnt vmcnt(" #n ")" ::: "memory")
; #define PG8_WAIT_L(n) asm volatile("s_waitcnt lgkmcnt(" #n ")" ::: "memory")
; #define PG8_BAR __builtin_amdgcn_s_barrier()
; #define PG8_SCHED __builtin_amdgcn_sched_barrier(0)
; template <class Epi, class Sched, bool ALIGN_EPI = false, bool SP2 = false>
; __device__ __forceinline__ void gemm_phase(PG8_LAS unsigned char* lds, const Gemm g, const Sched& S, const Epi& E) {
;     ...
;             PG8_LDB(B0, 0, 0); PG8_LDB(B1, 0, 1); PG8_SCHED; PG8_LDA(At, 0, 0); PG8_STAGE(PG8_SA(1, 1), a1 + hstep, voffA);
;             PG8_WAIT_V(8); PG8_WAIT_L(0); PG8_BAR; PG8_MMA(0, 0, At, B0); PG8_MMA(0, 1, At, B1); PG8_BAR; PG8_SCHED;
;             PG8_LDA(At, 0, 1); PG8_STAGE(PG8_SB(0, 0), b2, voffB); PG8_STAGE(PG8_SB(0, 1), b2 + hstep, voffB); PG8_STAGE(PG8_SA(0, 0), a2, voffA);
;             PG8_WAIT_V(8); PG8_WAIT_L(0); PG8_BAR; PG8_MMA(1, 0, At, B0); PG8_MMA(1, 1, At, B1); PG8_BAR; PG8_SCHED;
.Lsgi_peel:
	ds_read_b128 v[140:143], v254
	ds_read_b128 v[162:165], v254 offset:1024
	ds_read_b128 v[166:169], v254 offset:2048
	ds_read_b128 v[170:173], v254 offset:3072
	ds_read_b128 v[180:183], v254 offset:16384
	ds_read_b128 v[184:187], v254 offset:17408
	ds_read_b128 v[188:191], v254 offset:18432
	ds_read_b128 v[244:247], v254 offset:19456
	s_add_u32 s2, s0, 0xfffc0080
	s_addc_u32 s3, s1, -1
	s_cmp_eq_u32 s55, 12
	s_cselect_b32 s5, s13, s3
	s_cselect_b32 s4, s25, s2
	s_cselect_b32 s3, s23, s39
	s_cselect_b32 s2, s33, s38
	s_add_i32 m0, s6, 0xc000
	ds_read_b128 v[212:215], v178
	ds_read_b128 v[216:219], v178 offset:1024
	ds_read_b128 v[220:223], v178 offset:2048
	ds_read_b128 v[224:227], v178 offset:3072
	ds_read_b128 v[228:231], v178 offset:4096
	ds_read_b128 v[232:235], v178 offset:5120
	ds_read_b128 v[236:239], v178 offset:6144
	ds_read_b128 v[240:243], v178 offset:7168
	global_load_lds_dwordx4 v136, s[0:1]
	s_add_i32 m0, s6, 0xe000
	s_nop 0
	global_load_lds_dwordx4 v138, s[0:1]
	s_waitcnt vmcnt(8)
	s_waitcnt lgkmcnt(0)
	s_barrier
	s_setprio 1
	v_mfma_f32_16x16x32_bf16 v[124:127], v[140:143], v[212:215], 0
	v_mfma_f32_16x16x32_bf16 v[124:127], v[162:165], v[216:219], v[124:127]
	v_mfma_f32_16x16x32_bf16 v[108:111], v[140:143], v[220:223], 0
	v_mfma_f32_16x16x32_bf16 v[108:111], v[162:165], v[224:227], v[108:111]
	v_mfma_f32_16x16x32_bf16 v[92:95], v[140:143], v[228:231], 0
	v_mfma_f32_16x16x32_bf16 v[92:95], v[162:165], v[232:235], v[92:95]
	v_mfma_f32_16x16x32_bf16 v[76:79], v[140:143], v[236:239], 0
	v_mfma_f32_16x16x32_bf16 v[76:79], v[162:165], v[240:243], v[76:79]
	v_mfma_f32_16x16x32_bf16 v[120:123], v[166:169], v[212:215], 0
	v_mfma_f32_16x16x32_bf16 v[120:123], v[170:173], v[216:219], v[120:123]
	v_mfma_f32_16x16x32_bf16 v[104:107], v[166:169], v[220:223], 0
	v_mfma_f32_16x16x32_bf16 v[104:107], v[170:173], v[224:227], v[104:107]
	v_mfma_f32_16x16x32_bf16 v[88:91], v[166:169], v[228:231], 0
	v_mfma_f32_16x16x32_bf16 v[88:91], v[170:173], v[232:235], v[88:91]
	v_mfma_f32_16x16x32_bf16 v[72:75], v[166:169], v[236:239], 0
	v_mfma_f32_16x16x32_bf16 v[72:75], v[170:173], v[240:243], v[72:75]
	v_mfma_f32_16x16x32_bf16 v[116:119], v[180:183], v[212:215], 0
	v_mfma_f32_16x16x32_bf16 v[116:119], v[184:187], v[216:219], v[116:119]
	v_mfma_f32_16x16x32_bf16 v[100:103], v[180:183], v[220:223], 0
	v_mfma_f32_16x16x32_bf16 v[100:103], v[184:187], v[224:227], v[100:103]
	v_mfma_f32_16x16x32_bf16 v[84:87], v[180:183], v[228:231], 0
	v_mfma_f32_16x16x32_bf16 v[84:87], v[184:187], v[232:235], v[84:87]
	v_mfma_f32_16x16x32_bf16 v[68:71], v[180:183], v[236:239], 0
	v_mfma_f32_16x16x32_bf16 v[68:71], v[184:187], v[240:243], v[68:71]
	v_mfma_f32_16x16x32_bf16 v[112:115], v[188:191], v[212:215], 0
	v_mfma_f32_16x16x32_bf16 v[112:115], v[244:247], v[216:219], v[112:115]
	v_mfma_f32_16x16x32_bf16 v[96:99], v[188:191], v[220:223], 0
	v_mfma_f32_16x16x32_bf16 v[96:99], v[244:247], v[224:227], v[96:99]
	v_mfma_f32_16x16x32_bf16 v[80:83], v[188:191], v[228:231], 0
	v_mfma_f32_16x16x32_bf16 v[80:83], v[244:247], v[232:235], v[80:83]
	v_mfma_f32_16x16x32_bf16 v[64:67], v[188:191], v[236:239], 0
	v_mfma_f32_16x16x32_bf16 v[64:67], v[244:247], v[240:243], v[64:67]
	s_setprio 0
	s_barrier
	s_mov_b32 m0, s31
	s_add_u32 s56, s2, 0x40000
	s_addc_u32 s57, s3, 0
	ds_read_b128 v[212:215], v178 offset:16384
	ds_read_b128 v[216:219], v178 offset:17408
	ds_read_b128 v[220:223], v178 offset:18432
	ds_read_b128 v[224:227], v178 offset:19456
	ds_read_b128 v[228:231], v178 offset:20480
	ds_read_b128 v[232:235], v178 offset:21504
	ds_read_b128 v[236:239], v178 offset:22528
	ds_read_b128 v[240:243], v178 offset:23552
	global_load_lds_dwordx4 v132, s[2:3]
	s_mov_b32 m0, s34
	s_nop 0
	global_load_lds_dwordx4 v128, s[2:3]
	s_mov_b32 m0, s35
	s_nop 0
	global_load_lds_dwordx4 v132, s[56:57]
	s_mov_b32 m0, s40
	s_nop 0
	global_load_lds_dwordx4 v128, s[56:57]
	s_mov_b32 m0, s6
	s_nop 0
	global_load_lds_dwordx4 v134, s[4:5]
	s_mov_b32 m0, s41
	s_nop 0
	global_load_lds_dwordx4 v130, s[4:5]
	s_waitcnt vmcnt(8)
	s_waitcnt lgkmcnt(0)
	s_barrier
	s_setprio 1
	v_mfma_f32_16x16x32_bf16 v[60:63], v[140:143], v[212:215], 0
	v_mfma_f32_16x16x32_bf16 v[60:63], v[162:165], v[216:219], v[60:63]
	v_mfma_f32_16x16x32_bf16 v[44:47], v[140:143], v[220:223], 0
	v_mfma_f32_16x16x32_bf16 v[44:47], v[162:165], v[224:227], v[44:47]
	v_mfma_f32_16x16x32_bf16 v[28:31], v[140:143], v[228:231], 0
	v_mfma_f32_16x16x32_bf16 v[28:31], v[162:165], v[232:235], v[28:31]
	v_mfma_f32_16x16x32_bf16 v[12:15], v[140:143], v[236:239], 0
	v_mfma_f32_16x16x32_bf16 v[12:15], v[162:165], v[240:243], v[12:15]
	v_mfma_f32_16x16x32_bf16 v[56:59], v[166:169], v[212:215], 0
	v_mfma_f32_16x16x32_bf16 v[56:59], v[170:173], v[216:219], v[56:59]
	v_mfma_f32_16x16x32_bf16 v[40:43], v[166:169], v[220:223], 0
	v_mfma_f32_16x16x32_bf16 v[40:43], v[170:173], v[224:227], v[40:43]
	v_mfma_f32_16x16x32_bf16 v[24:27], v[166:169], v[228:231], 0
	v_mfma_f32_16x16x32_bf16 v[24:27], v[170:173], v[232:235], v[24:27]
	v_mfma_f32_16x16x32_bf16 v[8:11], v[166:169], v[236:239], 0
	v_mfma_f32_16x16x32_bf16 v[8:11], v[170:173], v[240:243], v[8:11]
	v_mfma_f32_16x16x32_bf16 v[52:55], v[180:183], v[212:215], 0
	v_mfma_f32_16x16x32_bf16 v[52:55], v[184:187], v[216:219], v[52:55]
	v_mfma_f32_16x16x32_bf16 v[36:39], v[180:183], v[220:223], 0
	v_mfma_f32_16x16x32_bf16 v[36:39], v[184:187], v[224:227], v[36:39]
	v_mfma_f32_16x16x32_bf16 v[20:23], v[180:183], v[228:231], 0
	v_mfma_f32_16x16x32_bf16 v[20:23], v[184:187], v[232:235], v[20:23]
	v_mfma_f32_16x16x32_bf16 v[4:7], v[180:183], v[236:239], 0
	v_mfma_f32_16x16x32_bf16 v[4:7], v[184:187], v[240:243], v[4:7]
	v_mfma_f32_16x16x32_bf16 v[48:51], v[188:191], v[212:215], 0
	v_mfma_f32_16x16x32_bf16 v[48:51], v[244:247], v[216:219], v[48:51]
	v_mfma_f32_16x16x32_bf16 v[32:35], v[188:191], v[220:223], 0
	v_mfma_f32_16x16x32_bf16 v[32:35], v[244:247], v[224:227], v[32:35]
	v_mfma_f32_16x16x32_bf16 v[16:19], v[188:191], v[228:231], 0
	v_mfma_f32_16x16x32_bf16 v[16:19], v[244:247], v[232:235], v[16:19]
	v_mfma_f32_16x16x32_bf16 v[0:3], v[188:191], v[236:239], 0
	v_mfma_f32_16x16x32_bf16 v[0:3], v[244:247], v[240:243], v[0:3]
	s_setprio 0
	s_barrier
; #define PG8_STAGE(bufoff, gbase, voff) do { _Pragma("unroll") for (int _i = 0; _i < 2; ++_i) \
;         __builtin_amdgcn_global_load_lds((const unsigned*)((const char*)(gbase) + (voff)[_i]), (PG8_LAS unsigned*)(lds + (bufoff) + ldsw + _i * 8192), 16, 0, 0); } while (0)
; #define PG8_LDA(dst, b, h) do { _Pragma("unroll") for (int m = 0; m < 4; ++m) _Pragma("unroll") for (int k = 0; k < 2; ++k) dst[m][k] = *(const PG8_LAS bf16x8*)(lds + PG8_SA(b, h) + aoff + m * 2048 + k * 1024); } while (0)
; #define PG8_LDB(dst, b, h) do { _Pragma("unroll") for (int n = 0; n < 2; ++n) _Pragma("unroll") for (int k = 0; k < 2; ++k) dst[n][k] = *(const PG8_LAS bf16x8*)(lds + PG8_SB(b, h) + boff + n * 2048 + k * 1024); } while (0)
; #define PG8_MMA(ai, bj, At, Bt) do { __builtin_amdgcn_s_setprio(1); _Pragma("unroll") for (int m = 0; m < 4; ++m) _Pragma("unroll") for (int n = 0; n < 2; ++n) _Pragma("unroll") for (int k = 0; k < 2; ++k) \
;         acc[ai][bj][m][n] = __builtin_amdgcn_mfma_f32_16x16x32_bf16(Bt[n][k], At[m][k], acc[ai][bj][m][n], 0, 0, 0); __builtin_amdgcn_s_setprio(0); } while (0)
; #define PG8_WAIT_V(n) asm volatile("s_waitcnt vmcnt(" #n ")" ::: "memory")
; #define PG8_WAIT_L(n) asm volatile("s_waitcnt lgkmcnt(" #n ")" ::: "memory")
; #define PG8_BAR __builtin_amdgcn_s_barrier()
; #define PG8_SCHED __builtin_amdgcn_sched_barrier(0)
; template <class Epi, class Sched, bool ALIGN_EPI = false, bool SP2 = false>
; __device__ __forceinline__ void gemm_phase(PG8_LAS unsigned char* lds, const Gemm g, const Sched& S, const Epi& E) {
;     ...
;             PG8_LDB(B0, 1, 0); PG8_LDB(B1, 1, 1); PG8_SCHED; PG8_LDA(At, 1, 0); PG8_STAGE(PG8_SA(0, 1), a2 + hstep, voffA);
;             PG8_WAIT_V(8); PG8_WAIT_L(0); PG8_BAR; PG8_MMA(0, 0, At, B0); PG8_MMA(0, 1, At, B1); PG8_BAR; PG8_SCHED;
;             PG8_LDA(At, 1, 1); PG8_STAGE(PG8_SB(1, 0), b3, voffB); PG8_STAGE(PG8_SB(1, 1), b3 + hstep, voffB); PG8_STAGE(PG8_SA(1, 0), a3, voffA);
;             PG8_WAIT_V(8); PG8_WAIT_L(0); PG8_BAR; PG8_MMA(1, 0, At, B0); PG8_MMA(1, 1, At, B1); PG8_BAR; PG8_SCHED;
	ds_read_b128 v[140:143], v254 offset:32768
	ds_read_b128 v[162:165], v254 offset:33792
	ds_read_b128 v[166:169], v254 offset:34816
	ds_read_b128 v[170:173], v254 offset:35840
	ds_read_b128 v[180:183], v254 offset:49152
	ds_read_b128 v[184:187], v254 offset:50176
	ds_read_b128 v[188:191], v254 offset:51200
	ds_read_b128 v[244:247], v254 offset:52224
	s_add_u32 s4, s4, 0x40000
	s_addc_u32 s5, s5, 0
	s_mov_b32 m0, s42
	ds_read_b128 v[212:215], v178 offset:32768
	ds_read_b128 v[216:219], v178 offset:33792
	ds_read_b128 v[220:223], v178 offset:34816
	ds_read_b128 v[224:227], v178 offset:35840
	ds_read_b128 v[228:231], v178 offset:36864
	ds_read_b128 v[232:235], v178 offset:37888
	ds_read_b128 v[236:239], v178 offset:38912
	ds_read_b128 v[240:243], v178 offset:39936
	global_load_lds_dwordx4 v134, s[4:5]
	s_mov_b32 m0, s43
	s_nop 0
	global_load_lds_dwordx4 v130, s[4:5]
	s_waitcnt vmcnt(8)
	s_waitcnt lgkmcnt(0)
	s_barrier
	s_setprio 1
	v_mfma_f32_16x16x32_bf16 v[124:127], v[140:143], v[212:215], v[124:127]
	v_mfma_f32_16x16x32_bf16 v[124:127], v[162:165], v[216:219], v[124:127]
	v_mfma_f32_16x16x32_bf16 v[108:111], v[140:143], v[220:223], v[108:111]
	v_mfma_f32_16x16x32_bf16 v[108:111], v[162:165], v[224:227], v[108:111]
	v_mfma_f32_16x16x32_bf16 v[92:95], v[140:143], v[228:231], v[92:95]
	v_mfma_f32_16x16x32_bf16 v[92:95], v[162:165], v[232:235], v[92:95]
	v_mfma_f32_16x16x32_bf16 v[76:79], v[140:143], v[236:239], v[76:79]
	v_mfma_f32_16x16x32_bf16 v[76:79], v[162:165], v[240:243], v[76:79]
	v_mfma_f32_16x16x32_bf16 v[120:123], v[166:169], v[212:215], v[120:123]
	v_mfma_f32_16x16x32_bf16 v[120:123], v[170:173], v[216:219], v[120:123]
	v_mfma_f32_16x16x32_bf16 v[104:107], v[166:169], v[220:223], v[104:107]
	v_mfma_f32_16x16x32_bf16 v[104:107], v[170:173], v[224:227], v[104:107]
	v_mfma_f32_16x16x32_bf16 v[88:91], v[166:169], v[228:231], v[88:91]
	v_mfma_f32_16x16x32_bf16 v[88:91], v[170:173], v[232:235], v[88:91]
	v_mfma_f32_16x16x32_bf16 v[72:75], v[166:169], v[236:239], v[72:75]
	v_mfma_f32_16x16x32_bf16 v[72:75], v[170:173], v[240:243], v[72:75]
	v_mfma_f32_16x16x32_bf16 v[116:119], v[180:183], v[212:215], v[116:119]
	v_mfma_f32_16x16x32_bf16 v[116:119], v[184:187], v[216:219], v[116:119]
	v_mfma_f32_16x16x32_bf16 v[100:103], v[180:183], v[220:223], v[100:103]
	v_mfma_f32_16x16x32_bf16 v[100:103], v[184:187], v[224:227], v[100:103]
	v_mfma_f32_16x16x32_bf16 v[84:87], v[180:183], v[228:231], v[84:87]
	v_mfma_f32_16x16x32_bf16 v[84:87], v[184:187], v[232:235], v[84:87]
	v_mfma_f32_16x16x32_bf16 v[68:71], v[180:183], v[236:239], v[68:71]
	v_mfma_f32_16x16x32_bf16 v[68:71], v[184:187], v[240:243], v[68:71]
	v_mfma_f32_16x16x32_bf16 v[112:115], v[188:191], v[212:215], v[112:115]
	v_mfma_f32_16x16x32_bf16 v[112:115], v[244:247], v[216:219], v[112:115]
	v_mfma_f32_16x16x32_bf16 v[96:99], v[188:191], v[220:223], v[96:99]
	v_mfma_f32_16x16x32_bf16 v[96:99], v[244:247], v[224:227], v[96:99]
	v_mfma_f32_16x16x32_bf16 v[80:83], v[188:191], v[228:231], v[80:83]
	v_mfma_f32_16x16x32_bf16 v[80:83], v[244:247], v[232:235], v[80:83]
	v_mfma_f32_16x16x32_bf16 v[64:67], v[188:191], v[236:239], v[64:67]
	v_mfma_f32_16x16x32_bf16 v[64:67], v[244:247], v[240:243], v[64:67]
	s_setprio 0
	s_barrier
	s_mov_b32 m0, s48
	s_add_u32 s2, s2, 0x40080
	s_addc_u32 s3, s3, 0
	ds_read_b128 v[212:215], v178 offset:49152
	ds_read_b128 v[216:219], v178 offset:50176
	ds_read_b128 v[220:223], v178 offset:51200
	ds_read_b128 v[224:227], v178 offset:52224
	ds_read_b128 v[228:231], v178 offset:53248
	ds_read_b128 v[232:235], v178 offset:54272
	ds_read_b128 v[236:239], v178 offset:55296
	ds_read_b128 v[240:243], v178 offset:56320
	s_add_u32 s98, s2, 0xfffc0000
	s_addc_u32 s99, s3, -1
	global_load_lds_dwordx4 v132, s[98:99]
	s_mov_b32 m0, s49
	s_nop 0
	global_load_lds_dwordx4 v128, s[98:99]
	s_mov_b32 m0, s52
	s_nop 0
	global_load_lds_dwordx4 v132, s[2:3]
	s_mov_b32 m0, s53
	s_nop 0
	global_load_lds_dwordx4 v128, s[2:3]
	s_mov_b32 m0, s50
	s_nop 0
	s_add_u32 s100, s4, 0xfffc0080
	s_addc_u32 s101, s5, -1
	global_load_lds_dwordx4 v134, s[100:101]
	s_mov_b32 m0, s51
	s_nop 0
	global_load_lds_dwordx4 v130, s[100:101]
	s_waitcnt vmcnt(8)
	s_waitcnt lgkmcnt(0)
	s_barrier
	s_setprio 1
	v_mfma_f32_16x16x32_bf16 v[60:63], v[140:143], v[212:215], v[60:63]
	v_mfma_f32_16x16x32_bf16 v[60:63], v[162:165], v[216:219], v[60:63]
	v_mfma_f32_16x16x32_bf16 v[44:47], v[140:143], v[220:223], v[44:47]
	v_mfma_f32_16x16x32_bf16 v[44:47], v[162:165], v[224:227], v[44:47]
	v_mfma_f32_16x16x32_bf16 v[28:31], v[140:143], v[228:231], v[28:31]
	v_mfma_f32_16x16x32_bf16 v[28:31], v[162:165], v[232:235], v[28:31]
	v_mfma_f32_16x16x32_bf16 v[12:15], v[140:143], v[236:239], v[12:15]
	v_mfma_f32_16x16x32_bf16 v[12:15], v[162:165], v[240:243], v[12:15]
	v_mfma_f32_16x16x32_bf16 v[56:59], v[166:169], v[212:215], v[56:59]
	v_mfma_f32_16x16x32_bf16 v[56:59], v[170:173], v[216:219], v[56:59]
	v_mfma_f32_16x16x32_bf16 v[40:43], v[166:169], v[220:223], v[40:43]
	v_mfma_f32_16x16x32_bf16 v[40:43], v[170:173], v[224:227], v[40:43]
	v_mfma_f32_16x16x32_bf16 v[24:27], v[166:169], v[228:231], v[24:27]
	v_mfma_f32_16x16x32_bf16 v[24:27], v[170:173], v[232:235], v[24:27]
	v_mfma_f32_16x16x32_bf16 v[8:11], v[166:169], v[236:239], v[8:11]
	v_mfma_f32_16x16x32_bf16 v[8:11], v[170:173], v[240:243], v[8:11]
	v_mfma_f32_16x16x32_bf16 v[52:55], v[180:183], v[212:215], v[52:55]
	v_mfma_f32_16x16x32_bf16 v[52:55], v[184:187], v[216:219], v[52:55]
	v_mfma_f32_16x16x32_bf16 v[36:39], v[180:183], v[220:223], v[36:39]
	v_mfma_f32_16x16x32_bf16 v[36:39], v[184:187], v[224:227], v[36:39]
	v_mfma_f32_16x16x32_bf16 v[20:23], v[180:183], v[228:231], v[20:23]
	v_mfma_f32_16x16x32_bf16 v[20:23], v[184:187], v[232:235], v[20:23]
	v_mfma_f32_16x16x32_bf16 v[4:7], v[180:183], v[236:239], v[4:7]
	v_mfma_f32_16x16x32_bf16 v[4:7], v[184:187], v[240:243], v[4:7]
	v_mfma_f32_16x16x32_bf16 v[48:51], v[188:191], v[212:215], v[48:51]
	v_mfma_f32_16x16x32_bf16 v[48:51], v[244:247], v[216:219], v[48:51]
	v_mfma_f32_16x16x32_bf16 v[32:35], v[188:191], v[220:223], v[32:35]
	v_mfma_f32_16x16x32_bf16 v[32:35], v[244:247], v[224:227], v[32:35]
	v_mfma_f32_16x16x32_bf16 v[16:19], v[188:191], v[228:231], v[16:19]
	v_mfma_f32_16x16x32_bf16 v[16:19], v[244:247], v[232:235], v[16:19]
	v_mfma_f32_16x16x32_bf16 v[0:3], v[188:191], v[236:239], v[0:3]
	v_mfma_f32_16x16x32_bf16 v[0:3], v[244:247], v[240:243], v[0:3]
	s_setprio 0
	s_barrier
	s_add_i32 s55, s55, 2
	s_add_u32 s0, s0, 0x100
	s_addc_u32 s1, s1, 0
	s_add_u32 s38, s38, 0x100
	s_addc_u32 s39, s39, 0
	s_cmp_gt_u32 s55, 13
; #define PG8_STAGE(bufoff, gbase, voff) do { _Pragma("unroll") for (int _i = 0; _i < 2; ++_i) \
;         __builtin_amdgcn_global_load_lds((const unsigned*)((const char*)(gbase) + (voff)[_i]), (PG8_LAS unsigned*)(lds + (bufoff) + ldsw + _i * 8192), 16, 0, 0); } while (0)
; #define PG8_LDA(dst, b, h) do { _Pragma("unroll") for (int m = 0; m < 4; ++m) _Pragma("unroll") for (int k = 0; k < 2; ++k) dst[m][k] = *(const PG8_LAS bf16x8*)(lds + PG8_SA(b, h) + aoff + m * 2048 + k * 1024); } while (0)
; #define PG8_LDB(dst, b, h) do { _Pragma("unroll") for (int n = 0; n < 2; ++n) _Pragma("unroll") for (int k = 0; k < 2; ++k) dst[n][k] = *(const PG8_LAS bf16x8*)(lds + PG8_SB(b, h) + boff + n * 2048 + k * 1024); } while (0)
; #define PG8_MMA(ai, bj, At, Bt) do { __builtin_amdgcn_s_setprio(1); _Pragma("unroll") for (int m = 0; m < 4; ++m) _Pragma("unroll") for (int n = 0; n < 2; ++n) _Pragma("unroll") for (int k = 0; k < 2; ++k) \
;         acc[ai][bj][m][n] = __builtin_amdgcn_mfma_f32_16x16x32_bf16(Bt[n][k], At[m][k], acc[ai][bj][m][n], 0, 0, 0); __builtin_amdgcn_s_setprio(0); } while (0)
; #define PG8_WAIT_V(n) asm volatile("s_waitcnt vmcnt(" #n ")" ::: "memory")
; #define PG8_WAIT_L(n) asm volatile("s_waitcnt lgkmcnt(" #n ")" ::: "memory")
; #define PG8_BAR __builtin_amdgcn_s_barrier()
; #define PG8_SCHED __builtin_amdgcn_sched_barrier(0)
; template <class Epi, class Sched, bool ALIGN_EPI = false, bool SP2 = false>
; __device__ __forceinline__ void gemm_phase(PG8_LAS unsigned char* lds, const Gemm g, const Sched& S, const Epi& E) {
;     ...
;             PG8_LDB(B0, 0, 0); PG8_LDB(B1, 0, 1); PG8_SCHED; PG8_LDA(At, 0, 0); PG8_STAGE(PG8_SA(1, 1), a1 + hstep, voffA);
;             PG8_WAIT_V(8); PG8_WAIT_L(0); PG8_BAR; PG8_MMA(0, 0, At, B0); PG8_MMA(0, 1, At, B1); PG8_BAR; PG8_SCHED;
;             PG8_LDA(At, 0, 1); PG8_STAGE(PG8_SB(0, 0), b2, voffB); PG8_STAGE(PG8_SB(0, 1), b2 + hstep, voffB); PG8_STAGE(PG8_SA(0, 0), a2, voffA);
;             PG8_WAIT_V(8); PG8_WAIT_L(0); PG8_BAR; PG8_MMA(1, 0, At, B0); PG8_MMA(1, 1, At, B1); PG8_BAR; PG8_SCHED;
.LBB0_749:
	ds_read_b128 v[140:143], v254
	ds_read_b128 v[162:165], v254 offset:1024
	ds_read_b128 v[166:169], v254 offset:2048
	ds_read_b128 v[170:173], v254 offset:3072
	ds_read_b128 v[180:183], v254 offset:16384
	ds_read_b128 v[184:187], v254 offset:17408
	ds_read_b128 v[188:191], v254 offset:18432
	ds_read_b128 v[244:247], v254 offset:19456
	s_add_u32 s2, s0, 0xfffc0080
	s_addc_u32 s3, s1, -1
	s_cmp_eq_u32 s55, 12
	s_cselect_b32 s5, s13, s3
	s_cselect_b32 s4, s25, s2
	s_cselect_b32 s3, s23, s39
	s_cselect_b32 s2, s33, s38
	s_add_i32 m0, s6, 0xc000
	ds_read_b128 v[212:215], v178
	ds_read_b128 v[216:219], v178 offset:1024
	ds_read_b128 v[220:223], v178 offset:2048
	ds_read_b128 v[224:227], v178 offset:3072
	ds_read_b128 v[228:231], v178 offset:4096
	ds_read_b128 v[232:235], v178 offset:5120
	ds_read_b128 v[236:239], v178 offset:6144
	ds_read_b128 v[240:243], v178 offset:7168
	global_load_lds_dwordx4 v136, s[0:1]
	s_add_i32 m0, s6, 0xe000
	s_nop 0
	global_load_lds_dwordx4 v138, s[0:1]
	s_waitcnt vmcnt(8)
	s_waitcnt lgkmcnt(0)
	s_barrier
	s_setprio 1
	v_mfma_f32_16x16x32_bf16 v[124:127], v[140:143], v[212:215], v[124:127]
	v_mfma_f32_16x16x32_bf16 v[124:127], v[162:165], v[216:219], v[124:127]
	v_mfma_f32_16x16x32_bf16 v[108:111], v[140:143], v[220:223], v[108:111]
	v_mfma_f32_16x16x32_bf16 v[108:111], v[162:165], v[224:227], v[108:111]
	v_mfma_f32_16x16x32_bf16 v[92:95], v[140:143], v[228:231], v[92:95]
	v_mfma_f32_16x16x32_bf16 v[92:95], v[162:165], v[232:235], v[92:95]
	v_mfma_f32_16x16x32_bf16 v[76:79], v[140:143], v[236:239], v[76:79]
	v_mfma_f32_16x16x32_bf16 v[76:79], v[162:165], v[240:243], v[76:79]
	v_mfma_f32_16x16x32_bf16 v[120:123], v[166:169], v[212:215], v[120:123]
	v_mfma_f32_16x16x32_bf16 v[120:123], v[170:173], v[216:219], v[120:123]
	v_mfma_f32_16x16x32_bf16 v[104:107], v[166:169], v[220:223], v[104:107]
	v_mfma_f32_16x16x32_bf16 v[104:107], v[170:173], v[224:227], v[104:107]
	v_mfma_f32_16x16x32_bf16 v[88:91], v[166:169], v[228:231], v[88:91]
	v_mfma_f32_16x16x32_bf16 v[88:91], v[170:173], v[232:235], v[88:91]
	v_mfma_f32_16x16x32_bf16 v[72:75], v[166:169], v[236:239], v[72:75]
	v_mfma_f32_16x16x32_bf16 v[72:75], v[170:173], v[240:243], v[72:75]
	v_mfma_f32_16x16x32_bf16 v[116:119], v[180:183], v[212:215], v[116:119]
	v_mfma_f32_16x16x32_bf16 v[116:119], v[184:187], v[216:219], v[116:119]
	v_mfma_f32_16x16x32_bf16 v[100:103], v[180:183], v[220:223], v[100:103]
	v_mfma_f32_16x16x32_bf16 v[100:103], v[184:187], v[224:227], v[100:103]
	v_mfma_f32_16x16x32_bf16 v[84:87], v[180:183], v[228:231], v[84:87]
	v_mfma_f32_16x16x32_bf16 v[84:87], v[184:187], v[232:235], v[84:87]
	v_mfma_f32_16x16x32_bf16 v[68:71], v[180:183], v[236:239], v[68:71]
	v_mfma_f32_16x16x32_bf16 v[68:71], v[184:187], v[240:243], v[68:71]
	v_mfma_f32_16x16x32_bf16 v[112:115], v[188:191], v[212:215], v[112:115]
	v_mfma_f32_16x16x32_bf16 v[112:115], v[244:247], v[216:219], v[112:115]
	v_mfma_f32_16x16x32_bf16 v[96:99], v[188:191], v[220:223], v[96:99]
	v_mfma_f32_16x16x32_bf16 v[96:99], v[244:247], v[224:227], v[96:99]
	v_mfma_f32_16x16x32_bf16 v[80:83], v[188:191], v[228:231], v[80:83]
	v_mfma_f32_16x16x32_bf16 v[80:83], v[244:247], v[232:235], v[80:83]
	v_mfma_f32_16x16x32_bf16 v[64:67], v[188:191], v[236:239], v[64:67]
	v_mfma_f32_16x16x32_bf16 v[64:67], v[244:247], v[240:243], v[64:67]
	s_setprio 0
	s_barrier
	s_mov_b32 m0, s31
	s_add_u32 s56, s2, 0x40000
	s_addc_u32 s57, s3, 0
	ds_read_b128 v[212:215], v178 offset:16384
	ds_read_b128 v[216:219], v178 offset:17408
	ds_read_b128 v[220:223], v178 offset:18432
	ds_read_b128 v[224:227], v178 offset:19456
	ds_read_b128 v[228:231], v178 offset:20480
	ds_read_b128 v[232:235], v178 offset:21504
	ds_read_b128 v[236:239], v178 offset:22528
	ds_read_b128 v[240:243], v178 offset:23552
	global_load_lds_dwordx4 v132, s[2:3]
	s_mov_b32 m0, s34
	s_nop 0
	global_load_lds_dwordx4 v128, s[2:3]
	s_mov_b32 m0, s35
	s_nop 0
	global_load_lds_dwordx4 v132, s[56:57]
	s_mov_b32 m0, s40
	s_nop 0
	global_load_lds_dwordx4 v128, s[56:57]
	s_mov_b32 m0, s6
	s_nop 0
	global_load_lds_dwordx4 v134, s[4:5]
	s_mov_b32 m0, s41
	s_nop 0
	global_load_lds_dwordx4 v130, s[4:5]
	s_waitcnt vmcnt(8)
	s_waitcnt lgkmcnt(0)
	s_barrier
	s_setprio 1
	v_mfma_f32_16x16x32_bf16 v[60:63], v[140:143], v[212:215], v[60:63]
	v_mfma_f32_16x16x32_bf16 v[60:63], v[162:165], v[216:219], v[60:63]
	v_mfma_f32_16x16x32_bf16 v[44:47], v[140:143], v[220:223], v[44:47]
	v_mfma_f32_16x16x32_bf16 v[44:47], v[162:165], v[224:227], v[44:47]
	v_mfma_f32_16x16x32_bf16 v[28:31], v[140:143], v[228:231], v[28:31]
	v_mfma_f32_16x16x32_bf16 v[28:31], v[162:165], v[232:235], v[28:31]
	v_mfma_f32_16x16x32_bf16 v[12:15], v[140:143], v[236:239], v[12:15]
	v_mfma_f32_16x16x32_bf16 v[12:15], v[162:165], v[240:243], v[12:15]
	v_mfma_f32_16x16x32_bf16 v[56:59], v[166:169], v[212:215], v[56:59]
	v_mfma_f32_16x16x32_bf16 v[56:59], v[170:173], v[216:219], v[56:59]
	v_mfma_f32_16x16x32_bf16 v[40:43], v[166:169], v[220:223], v[40:43]
	v_mfma_f32_16x16x32_bf16 v[40:43], v[170:173], v[224:227], v[40:43]
	v_mfma_f32_16x16x32_bf16 v[24:27], v[166:169], v[228:231], v[24:27]
	v_mfma_f32_16x16x32_bf16 v[24:27], v[170:173], v[232:235], v[24:27]
	v_mfma_f32_16x16x32_bf16 v[8:11], v[166:169], v[236:239], v[8:11]
	v_mfma_f32_16x16x32_bf16 v[8:11], v[170:173], v[240:243], v[8:11]
	v_mfma_f32_16x16x32_bf16 v[52:55], v[180:183], v[212:215], v[52:55]
	v_mfma_f32_16x16x32_bf16 v[52:55], v[184:187], v[216:219], v[52:55]
	v_mfma_f32_16x16x32_bf16 v[36:39], v[180:183], v[220:223], v[36:39]
	v_mfma_f32_16x16x32_bf16 v[36:39], v[184:187], v[224:227], v[36:39]
	v_mfma_f32_16x16x32_bf16 v[20:23], v[180:183], v[228:231], v[20:23]
	v_mfma_f32_16x16x32_bf16 v[20:23], v[184:187], v[232:235], v[20:23]
	v_mfma_f32_16x16x32_bf16 v[4:7], v[180:183], v[236:239], v[4:7]
	v_mfma_f32_16x16x32_bf16 v[4:7], v[184:187], v[240:243], v[4:7]
	v_mfma_f32_16x16x32_bf16 v[48:51], v[188:191], v[212:215], v[48:51]
	v_mfma_f32_16x16x32_bf16 v[48:51], v[244:247], v[216:219], v[48:51]
	v_mfma_f32_16x16x32_bf16 v[32:35], v[188:191], v[220:223], v[32:35]
	v_mfma_f32_16x16x32_bf16 v[32:35], v[244:247], v[224:227], v[32:35]
	v_mfma_f32_16x16x32_bf16 v[16:19], v[188:191], v[228:231], v[16:19]
	v_mfma_f32_16x16x32_bf16 v[16:19], v[244:247], v[232:235], v[16:19]
	v_mfma_f32_16x16x32_bf16 v[0:3], v[188:191], v[236:239], v[0:3]
	v_mfma_f32_16x16x32_bf16 v[0:3], v[244:247], v[240:243], v[0:3]
	s_setprio 0
	s_barrier
; #define PG8_STAGE(bufoff, gbase, voff) do { _Pragma("unroll") for (int _i = 0; _i < 2; ++_i) \
;         __builtin_amdgcn_global_load_lds((const unsigned*)((const char*)(gbase) + (voff)[_i]), (PG8_LAS unsigned*)(lds + (bufoff) + ldsw + _i * 8192), 16, 0, 0); } while (0)
; #define PG8_LDA(dst, b, h) do { _Pragma("unroll") for (int m = 0; m < 4; ++m) _Pragma("unroll") for (int k = 0; k < 2; ++k) dst[m][k] = *(const PG8_LAS bf16x8*)(lds + PG8_SA(b, h) + aoff + m * 2048 + k * 1024); } while (0)
; #define PG8_LDB(dst, b, h) do { _Pragma("unroll") for (int n = 0; n < 2; ++n) _Pragma("unroll") for (int k = 0; k < 2; ++k) dst[n][k] = *(const PG8_LAS bf16x8*)(lds + PG8_SB(b, h) + boff + n * 2048 + k * 1024); } while (0)
; #define PG8_MMA(ai, bj, At, Bt) do { __builtin_amdgcn_s_setprio(1); _Pragma("unroll") for (int m = 0; m < 4; ++m) _Pragma("unroll") for (int n = 0; n < 2; ++n) _Pragma("unroll") for (int k = 0; k < 2; ++k) \
;         acc[ai][bj][m][n] = __builtin_amdgcn_mfma_f32_16x16x32_bf16(Bt[n][k], At[m][k], acc[ai][bj][m][n], 0, 0, 0); __builtin_amdgcn_s_setprio(0); } while (0)
; #define PG8_WAIT_V(n) asm volatile("s_waitcnt vmcnt(" #n ")" ::: "memory")
; #define PG8_WAIT_L(n) asm volatile("s_waitcnt lgkmcnt(" #n ")" ::: "memory")
; #define PG8_BAR __builtin_amdgcn_s_barrier()
; #define PG8_SCHED __builtin_amdgcn_sched_barrier(0)
; template <class Epi, class Sched, bool ALIGN_EPI = false, bool SP2 = false>
; __device__ __forceinline__ void gemm_phase(PG8_LAS unsigned char* lds, const Gemm g, const Sched& S, const Epi& E) {
;     ...
;         for (int t = 0; t < nt; t += 2) {
;     ...
;             PG8_LDB(B0, 1, 0); PG8_LDB(B1, 1, 1); PG8_SCHED; PG8_LDA(At, 1, 0); PG8_STAGE(PG8_SA(0, 1), a2 + hstep, voffA);
;             PG8_WAIT_V(8); PG8_WAIT_L(0); PG8_BAR; PG8_MMA(0, 0, At, B0); PG8_MMA(0, 1, At, B1); PG8_BAR; PG8_SCHED;
;             PG8_LDA(At, 1, 1); PG8_STAGE(PG8_SB(1, 0), b3, voffB); PG8_STAGE(PG8_SB(1, 1), b3 + hstep, voffB); PG8_STAGE(PG8_SA(1, 0), a3, voffA);
;             PG8_WAIT_V(8); PG8_WAIT_L(0); PG8_BAR; PG8_MMA(1, 0, At, B0); PG8_MMA(1, 1, At, B1); PG8_BAR; PG8_SCHED;
	ds_read_b128 v[140:143], v254 offset:32768
	ds_read_b128 v[162:165], v254 offset:33792
	ds_read_b128 v[166:169], v254 offset:34816
	ds_read_b128 v[170:173], v254 offset:35840
	ds_read_b128 v[180:183], v254 offset:49152
	ds_read_b128 v[184:187], v254 offset:50176
	ds_read_b128 v[188:191], v254 offset:51200
	ds_read_b128 v[244:247], v254 offset:52224
	s_add_u32 s4, s4, 0x40000
	s_addc_u32 s5, s5, 0
	s_mov_b32 m0, s42
	ds_read_b128 v[212:215], v178 offset:32768
	ds_read_b128 v[216:219], v178 offset:33792
	ds_read_b128 v[220:223], v178 offset:34816
	ds_read_b128 v[224:227], v178 offset:35840
	ds_read_b128 v[228:231], v178 offset:36864
	ds_read_b128 v[232:235], v178 offset:37888
	ds_read_b128 v[236:239], v178 offset:38912
	ds_read_b128 v[240:243], v178 offset:39936
	global_load_lds_dwordx4 v134, s[4:5]
	s_mov_b32 m0, s43
	s_nop 0
	global_load_lds_dwordx4 v130, s[4:5]
	s_waitcnt vmcnt(8)
	s_waitcnt lgkmcnt(0)
	s_barrier
	s_setprio 1
	v_mfma_f32_16x16x32_bf16 v[124:127], v[140:143], v[212:215], v[124:127]
	v_mfma_f32_16x16x32_bf16 v[124:127], v[162:165], v[216:219], v[124:127]
	v_mfma_f32_16x16x32_bf16 v[108:111], v[140:143], v[220:223], v[108:111]
	v_mfma_f32_16x16x32_bf16 v[108:111], v[162:165], v[224:227], v[108:111]
	v_mfma_f32_16x16x32_bf16 v[92:95], v[140:143], v[228:231], v[92:95]
	v_mfma_f32_16x16x32_bf16 v[92:95], v[162:165], v[232:235], v[92:95]
	v_mfma_f32_16x16x32_bf16 v[76:79], v[140:143], v[236:239], v[76:79]
	v_mfma_f32_16x16x32_bf16 v[76:79], v[162:165], v[240:243], v[76:79]
	v_mfma_f32_16x16x32_bf16 v[120:123], v[166:169], v[212:215], v[120:123]
	v_mfma_f32_16x16x32_bf16 v[120:123], v[170:173], v[216:219], v[120:123]
	v_mfma_f32_16x16x32_bf16 v[104:107], v[166:169], v[220:223], v[104:107]
	v_mfma_f32_16x16x32_bf16 v[104:107], v[170:173], v[224:227], v[104:107]
	v_mfma_f32_16x16x32_bf16 v[88:91], v[166:169], v[228:231], v[88:91]
	v_mfma_f32_16x16x32_bf16 v[88:91], v[170:173], v[232:235], v[88:91]
	v_mfma_f32_16x16x32_bf16 v[72:75], v[166:169], v[236:239], v[72:75]
	v_mfma_f32_16x16x32_bf16 v[72:75], v[170:173], v[240:243], v[72:75]
	v_mfma_f32_16x16x32_bf16 v[116:119], v[180:183], v[212:215], v[116:119]
	v_mfma_f32_16x16x32_bf16 v[116:119], v[184:187], v[216:219], v[116:119]
	v_mfma_f32_16x16x32_bf16 v[100:103], v[180:183], v[220:223], v[100:103]
	v_mfma_f32_16x16x32_bf16 v[100:103], v[184:187], v[224:227], v[100:103]
	v_mfma_f32_16x16x32_bf16 v[84:87], v[180:183], v[228:231], v[84:87]
	v_mfma_f32_16x16x32_bf16 v[84:87], v[184:187], v[232:235], v[84:87]
	v_mfma_f32_16x16x32_bf16 v[68:71], v[180:183], v[236:239], v[68:71]
	v_mfma_f32_16x16x32_bf16 v[68:71], v[184:187], v[240:243], v[68:71]
	v_mfma_f32_16x16x32_bf16 v[112:115], v[188:191], v[212:215], v[112:115]
	v_mfma_f32_16x16x32_bf16 v[112:115], v[244:247], v[216:219], v[112:115]
	v_mfma_f32_16x16x32_bf16 v[96:99], v[188:191], v[220:223], v[96:99]
	v_mfma_f32_16x16x32_bf16 v[96:99], v[244:247], v[224:227], v[96:99]
	v_mfma_f32_16x16x32_bf16 v[80:83], v[188:191], v[228:231], v[80:83]
	v_mfma_f32_16x16x32_bf16 v[80:83], v[244:247], v[232:235], v[80:83]
	v_mfma_f32_16x16x32_bf16 v[64:67], v[188:191], v[236:239], v[64:67]
	v_mfma_f32_16x16x32_bf16 v[64:67], v[244:247], v[240:243], v[64:67]
	s_setprio 0
	s_barrier
	s_mov_b32 m0, s48
	s_add_u32 s2, s2, 0x40080
	s_addc_u32 s3, s3, 0
	ds_read_b128 v[212:215], v178 offset:49152
	ds_read_b128 v[216:219], v178 offset:50176
	ds_read_b128 v[220:223], v178 offset:51200
	ds_read_b128 v[224:227], v178 offset:52224
	ds_read_b128 v[228:231], v178 offset:53248
	ds_read_b128 v[232:235], v178 offset:54272
	ds_read_b128 v[236:239], v178 offset:55296
	ds_read_b128 v[240:243], v178 offset:56320
	s_add_u32 s98, s2, 0xfffc0000
	s_addc_u32 s99, s3, -1
	global_load_lds_dwordx4 v132, s[98:99]
	s_mov_b32 m0, s49
	s_nop 0
	global_load_lds_dwordx4 v128, s[98:99]
	s_mov_b32 m0, s52
	s_nop 0
	global_load_lds_dwordx4 v132, s[2:3]
	s_mov_b32 m0, s53
	s_nop 0
	global_load_lds_dwordx4 v128, s[2:3]
	s_mov_b32 m0, s50
	s_nop 0
	s_add_u32 s100, s4, 0xfffc0080
	s_addc_u32 s101, s5, -1
	global_load_lds_dwordx4 v134, s[100:101]
	s_mov_b32 m0, s51
	s_nop 0
	global_load_lds_dwordx4 v130, s[100:101]
	s_waitcnt vmcnt(8)
	s_waitcnt lgkmcnt(0)
	s_barrier
	s_setprio 1
	v_mfma_f32_16x16x32_bf16 v[60:63], v[140:143], v[212:215], v[60:63]
	v_mfma_f32_16x16x32_bf16 v[60:63], v[162:165], v[216:219], v[60:63]
	v_mfma_f32_16x16x32_bf16 v[44:47], v[140:143], v[220:223], v[44:47]
	v_mfma_f32_16x16x32_bf16 v[44:47], v[162:165], v[224:227], v[44:47]
	v_mfma_f32_16x16x32_bf16 v[28:31], v[140:143], v[228:231], v[28:31]
	v_mfma_f32_16x16x32_bf16 v[28:31], v[162:165], v[232:235], v[28:31]
	v_mfma_f32_16x16x32_bf16 v[12:15], v[140:143], v[236:239], v[12:15]
	v_mfma_f32_16x16x32_bf16 v[12:15], v[162:165], v[240:243], v[12:15]
	v_mfma_f32_16x16x32_bf16 v[56:59], v[166:169], v[212:215], v[56:59]
	v_mfma_f32_16x16x32_bf16 v[56:59], v[170:173], v[216:219], v[56:59]
	v_mfma_f32_16x16x32_bf16 v[40:43], v[166:169], v[220:223], v[40:43]
	v_mfma_f32_16x16x32_bf16 v[40:43], v[170:173], v[224:227], v[40:43]
	v_mfma_f32_16x16x32_bf16 v[24:27], v[166:169], v[228:231], v[24:27]
	v_mfma_f32_16x16x32_bf16 v[24:27], v[170:173], v[232:235], v[24:27]
	v_mfma_f32_16x16x32_bf16 v[8:11], v[166:169], v[236:239], v[8:11]
	v_mfma_f32_16x16x32_bf16 v[8:11], v[170:173], v[240:243], v[8:11]
	v_mfma_f32_16x16x32_bf16 v[52:55], v[180:183], v[212:215], v[52:55]
	v_mfma_f32_16x16x32_bf16 v[52:55], v[184:187], v[216:219], v[52:55]
	v_mfma_f32_16x16x32_bf16 v[36:39], v[180:183], v[220:223], v[36:39]
	v_mfma_f32_16x16x32_bf16 v[36:39], v[184:187], v[224:227], v[36:39]
	v_mfma_f32_16x16x32_bf16 v[20:23], v[180:183], v[228:231], v[20:23]
	v_mfma_f32_16x16x32_bf16 v[20:23], v[184:187], v[232:235], v[20:23]
	v_mfma_f32_16x16x32_bf16 v[4:7], v[180:183], v[236:239], v[4:7]
	v_mfma_f32_16x16x32_bf16 v[4:7], v[184:187], v[240:243], v[4:7]
	v_mfma_f32_16x16x32_bf16 v[48:51], v[188:191], v[212:215], v[48:51]
	v_mfma_f32_16x16x32_bf16 v[48:51], v[244:247], v[216:219], v[48:51]
	v_mfma_f32_16x16x32_bf16 v[32:35], v[188:191], v[220:223], v[32:35]
	v_mfma_f32_16x16x32_bf16 v[32:35], v[244:247], v[224:227], v[32:35]
	v_mfma_f32_16x16x32_bf16 v[16:19], v[188:191], v[228:231], v[16:19]
	v_mfma_f32_16x16x32_bf16 v[16:19], v[244:247], v[232:235], v[16:19]
	v_mfma_f32_16x16x32_bf16 v[0:3], v[188:191], v[236:239], v[0:3]
	v_mfma_f32_16x16x32_bf16 v[0:3], v[244:247], v[240:243], v[0:3]
	s_setprio 0
	s_barrier
	s_add_i32 s55, s55, 2
	s_add_u32 s0, s0, 0x100
	s_addc_u32 s1, s1, 0
	s_add_u32 s38, s38, 0x100
	s_addc_u32 s39, s39, 0
	s_cmp_gt_u32 s55, 13
	s_cbranch_scc0 .LBB0_749
	s_and_b64 vcc, exec, s[18:19]
	s_cbranch_vccz .LBB0_752
	s_barrier

; #define PG8_STAGE(bufoff, gbase, voff) do { _Pragma("unroll") for (int _i = 0; _i < 2; ++_i) \
;         __builtin_amdgcn_global_load_lds((const unsigned*)((const char*)(gbase) + (voff)[_i]), (PG8_LAS unsigned*)(lds + (bufoff) + ldsw + _i * 8192), 16, 0, 0); } while (0)
; #define PG8_LDA(dst, b, h) do { _Pragma("unroll") for (int m = 0; m < 4; ++m) _Pragma("unroll") for (int k = 0; k < 2; ++k) dst[m][k] = *(const PG8_LAS bf16x8*)(lds + PG8_SA(b, h) + aoff + m * 2048 + k * 1024); } while (0)
; #define PG8_LDB(dst, b, h) do { _Pragma("unroll") for (int n = 0; n < 2; ++n) _Pragma("unroll") for (int k = 0; k < 2; ++k) dst[n][k] = *(const PG8_LAS bf16x8*)(lds + PG8_SB(b, h) + boff + n * 2048 + k * 1024); } while (0)
; #define PG8_MMA(ai, bj, At, Bt) do { __builtin_amdgcn_s_setprio(1); _Pragma("unroll") for (int m = 0; m < 4; ++m) _Pragma("unroll") for (int n = 0; n < 2; ++n) _Pragma("unroll") for (int k = 0; k < 2; ++k) \
;         acc[ai][bj][m][n] = __builtin_amdgcn_mfma_f32_16x16x32_bf16(Bt[n][k], At[m][k], acc[ai][bj][m][n], 0, 0, 0); __builtin_amdgcn_s_setprio(0); } while (0)
; #define PG8_WAIT_V(n) asm volatile("s_waitcnt vmcnt(" #n ")" ::: "memory")
; #define PG8_WAIT_L(n) asm volatile("s_waitcnt lgkmcnt(" #n ")" ::: "memory")
; #define PG8_BAR __builtin_amdgcn_s_barrier()
; #define PG8_SCHED __builtin_amdgcn_sched_barrier(0)
; template <class Epi, class Sched, bool ALIGN_EPI = false, bool SP2 = false>
; __device__ __forceinline__ void gemm_phase(PG8_LAS unsigned char* lds, const Gemm g, const Sched& S, const Epi& E) {
;     ...
;             PG8_LDB(B0, 0, 0); PG8_LDB(B1, 0, 1); PG8_SCHED; PG8_LDA(At, 0, 0); PG8_STAGE(PG8_SA(1, 1), a1 + hstep, voffA);
;             PG8_WAIT_V(8); PG8_WAIT_L(0); PG8_BAR; PG8_MMA(0, 0, At, B0); PG8_MMA(0, 1, At, B1); PG8_BAR; PG8_SCHED;
;             PG8_LDA(At, 0, 1); PG8_STAGE(PG8_SB(0, 0), b2, voffB); PG8_STAGE(PG8_SB(0, 1), b2 + hstep, voffB); PG8_STAGE(PG8_SA(0, 0), a2, voffA);
;             PG8_WAIT_V(8); PG8_WAIT_L(0); PG8_BAR; PG8_MMA(1, 0, At, B0); PG8_MMA(1, 1, At, B1); PG8_BAR; PG8_SCHED;
.Labi_peel:
	s_waitcnt lgkmcnt(0)
	ds_read_b128 v[140:143], v254
	ds_read_b128 v[162:165], v254 offset:1024
	ds_read_b128 v[166:169], v254 offset:2048
	ds_read_b128 v[176:179], v254 offset:3072
	ds_read_b128 v[180:183], v254 offset:16384
	ds_read_b128 v[184:187], v254 offset:17408
	ds_read_b128 v[188:191], v254 offset:18432
	ds_read_b128 v[244:247], v254 offset:19456
	s_add_u32 s2, s0, 0xfffc0080
	s_addc_u32 s3, s1, -1
	s_cmp_eq_u32 s52, 12
	s_cselect_b32 s5, s17, s3
	s_cselect_b32 s4, s48, s2
	s_cselect_b32 s3, s15, s51
	s_cselect_b32 s2, s49, s50
	s_add_i32 m0, s6, 0xc000
	ds_read_b128 v[212:215], v173
	ds_read_b128 v[216:219], v173 offset:1024
	ds_read_b128 v[220:223], v173 offset:2048
	ds_read_b128 v[224:227], v173 offset:3072
	ds_read_b128 v[228:231], v173 offset:4096
	ds_read_b128 v[232:235], v173 offset:5120
	ds_read_b128 v[236:239], v173 offset:6144
	ds_read_b128 v[240:243], v173 offset:7168
	global_load_lds_dwordx4 v136, s[0:1]
	s_add_i32 m0, s6, 0xe000
	s_nop 0
	global_load_lds_dwordx4 v138, s[0:1]
	s_waitcnt vmcnt(8)
	s_waitcnt lgkmcnt(0)
	s_barrier
	s_setprio 1
	v_mfma_f32_16x16x32_bf16 v[124:127], v[140:143], v[212:215], 0
	v_mfma_f32_16x16x32_bf16 v[124:127], v[162:165], v[216:219], v[124:127]
	v_mfma_f32_16x16x32_bf16 v[112:115], v[140:143], v[220:223], 0
	v_mfma_f32_16x16x32_bf16 v[112:115], v[162:165], v[224:227], v[112:115]
	v_mfma_f32_16x16x32_bf16 v[96:99], v[140:143], v[228:231], 0
	v_mfma_f32_16x16x32_bf16 v[96:99], v[162:165], v[232:235], v[96:99]
	v_mfma_f32_16x16x32_bf16 v[80:83], v[140:143], v[236:239], 0
	v_mfma_f32_16x16x32_bf16 v[80:83], v[162:165], v[240:243], v[80:83]
	v_mfma_f32_16x16x32_bf16 v[120:123], v[166:169], v[212:215], 0
	v_mfma_f32_16x16x32_bf16 v[120:123], v[176:179], v[216:219], v[120:123]
	v_mfma_f32_16x16x32_bf16 v[104:107], v[166:169], v[220:223], 0
	v_mfma_f32_16x16x32_bf16 v[104:107], v[176:179], v[224:227], v[104:107]
	v_mfma_f32_16x16x32_bf16 v[88:91], v[166:169], v[228:231], 0
	v_mfma_f32_16x16x32_bf16 v[88:91], v[176:179], v[232:235], v[88:91]
	v_mfma_f32_16x16x32_bf16 v[72:75], v[166:169], v[236:239], 0
	v_mfma_f32_16x16x32_bf16 v[72:75], v[176:179], v[240:243], v[72:75]
	v_mfma_f32_16x16x32_bf16 v[116:119], v[180:183], v[212:215], 0
	v_mfma_f32_16x16x32_bf16 v[116:119], v[184:187], v[216:219], v[116:119]
	v_mfma_f32_16x16x32_bf16 v[100:103], v[180:183], v[220:223], 0
	v_mfma_f32_16x16x32_bf16 v[100:103], v[184:187], v[224:227], v[100:103]
	v_mfma_f32_16x16x32_bf16 v[84:87], v[180:183], v[228:231], 0
	v_mfma_f32_16x16x32_bf16 v[84:87], v[184:187], v[232:235], v[84:87]
	v_mfma_f32_16x16x32_bf16 v[68:71], v[180:183], v[236:239], 0
	v_mfma_f32_16x16x32_bf16 v[68:71], v[184:187], v[240:243], v[68:71]
	v_mfma_f32_16x16x32_bf16 v[108:111], v[188:191], v[212:215], 0
	v_mfma_f32_16x16x32_bf16 v[108:111], v[244:247], v[216:219], v[108:111]
	v_mfma_f32_16x16x32_bf16 v[92:95], v[188:191], v[220:223], 0
	v_mfma_f32_16x16x32_bf16 v[92:95], v[244:247], v[224:227], v[92:95]
	v_mfma_f32_16x16x32_bf16 v[76:79], v[188:191], v[228:231], 0
	v_mfma_f32_16x16x32_bf16 v[76:79], v[244:247], v[232:235], v[76:79]
	v_mfma_f32_16x16x32_bf16 v[64:67], v[188:191], v[236:239], 0
	v_mfma_f32_16x16x32_bf16 v[64:67], v[244:247], v[240:243], v[64:67]
	s_setprio 0
	s_barrier
	s_mov_b32 m0, s27
	s_add_u32 s54, s2, 0x40000
	s_addc_u32 s55, s3, 0
	ds_read_b128 v[212:215], v173 offset:16384
	ds_read_b128 v[216:219], v173 offset:17408
	ds_read_b128 v[220:223], v173 offset:18432
	ds_read_b128 v[224:227], v173 offset:19456
	ds_read_b128 v[228:231], v173 offset:20480
	ds_read_b128 v[232:235], v173 offset:21504
	ds_read_b128 v[236:239], v173 offset:22528
	ds_read_b128 v[240:243], v173 offset:23552
	global_load_lds_dwordx4 v132, s[2:3]
	s_mov_b32 m0, s28
	s_nop 0
	global_load_lds_dwordx4 v128, s[2:3]
	s_mov_b32 m0, s29
	s_nop 0
	global_load_lds_dwordx4 v132, s[54:55]
	s_mov_b32 m0, s30
	s_nop 0
	global_load_lds_dwordx4 v128, s[54:55]
	s_mov_b32 m0, s6
	s_nop 0
	global_load_lds_dwordx4 v134, s[4:5]
	s_mov_b32 m0, s31
	s_nop 0
	global_load_lds_dwordx4 v130, s[4:5]
	s_waitcnt vmcnt(8)
	s_waitcnt lgkmcnt(0)
	s_barrier
	s_setprio 1
	v_mfma_f32_16x16x32_bf16 v[60:63], v[140:143], v[212:215], 0
	v_mfma_f32_16x16x32_bf16 v[60:63], v[162:165], v[216:219], v[60:63]
	v_mfma_f32_16x16x32_bf16 v[48:51], v[140:143], v[220:223], 0
	v_mfma_f32_16x16x32_bf16 v[48:51], v[162:165], v[224:227], v[48:51]
	v_mfma_f32_16x16x32_bf16 v[32:35], v[140:143], v[228:231], 0
	v_mfma_f32_16x16x32_bf16 v[32:35], v[162:165], v[232:235], v[32:35]
	v_mfma_f32_16x16x32_bf16 v[16:19], v[140:143], v[236:239], 0
	v_mfma_f32_16x16x32_bf16 v[16:19], v[162:165], v[240:243], v[16:19]
	v_mfma_f32_16x16x32_bf16 v[56:59], v[166:169], v[212:215], 0
	v_mfma_f32_16x16x32_bf16 v[56:59], v[176:179], v[216:219], v[56:59]
	v_mfma_f32_16x16x32_bf16 v[40:43], v[166:169], v[220:223], 0
	v_mfma_f32_16x16x32_bf16 v[40:43], v[176:179], v[224:227], v[40:43]
	v_mfma_f32_16x16x32_bf16 v[24:27], v[166:169], v[228:231], 0
	v_mfma_f32_16x16x32_bf16 v[24:27], v[176:179], v[232:235], v[24:27]
	v_mfma_f32_16x16x32_bf16 v[8:11], v[166:169], v[236:239], 0
	v_mfma_f32_16x16x32_bf16 v[8:11], v[176:179], v[240:243], v[8:11]
	v_mfma_f32_16x16x32_bf16 v[52:55], v[180:183], v[212:215], 0
	v_mfma_f32_16x16x32_bf16 v[52:55], v[184:187], v[216:219], v[52:55]
	v_mfma_f32_16x16x32_bf16 v[36:39], v[180:183], v[220:223], 0
	v_mfma_f32_16x16x32_bf16 v[36:39], v[184:187], v[224:227], v[36:39]
	v_mfma_f32_16x16x32_bf16 v[20:23], v[180:183], v[228:231], 0
	v_mfma_f32_16x16x32_bf16 v[20:23], v[184:187], v[232:235], v[20:23]
	v_mfma_f32_16x16x32_bf16 v[4:7], v[180:183], v[236:239], 0
	v_mfma_f32_16x16x32_bf16 v[4:7], v[184:187], v[240:243], v[4:7]
	v_mfma_f32_16x16x32_bf16 v[44:47], v[188:191], v[212:215], 0
	v_mfma_f32_16x16x32_bf16 v[44:47], v[244:247], v[216:219], v[44:47]
	v_mfma_f32_16x16x32_bf16 v[28:31], v[188:191], v[220:223], 0
	v_mfma_f32_16x16x32_bf16 v[28:31], v[244:247], v[224:227], v[28:31]
	v_mfma_f32_16x16x32_bf16 v[12:15], v[188:191], v[228:231], 0
	v_mfma_f32_16x16x32_bf16 v[12:15], v[244:247], v[232:235], v[12:15]
	v_mfma_f32_16x16x32_bf16 v[0:3], v[188:191], v[236:239], 0
	v_mfma_f32_16x16x32_bf16 v[0:3], v[244:247], v[240:243], v[0:3]
	s_setprio 0
	s_barrier
; #define PG8_STAGE(bufoff, gbase, voff) do { _Pragma("unroll") for (int _i = 0; _i < 2; ++_i) \
;         __builtin_amdgcn_global_load_lds((const unsigned*)((const char*)(gbase) + (voff)[_i]), (PG8_LAS unsigned*)(lds + (bufoff) + ldsw + _i * 8192), 16, 0, 0); } while (0)
; #define PG8_LDA(dst, b, h) do { _Pragma("unroll") for (int m = 0; m < 4; ++m) _Pragma("unroll") for (int k = 0; k < 2; ++k) dst[m][k] = *(const PG8_LAS bf16x8*)(lds + PG8_SA(b, h) + aoff + m * 2048 + k * 1024); } while (0)
; #define PG8_LDB(dst, b, h) do { _Pragma("unroll") for (int n = 0; n < 2; ++n) _Pragma("unroll") for (int k = 0; k < 2; ++k) dst[n][k] = *(const PG8_LAS bf16x8*)(lds + PG8_SB(b, h) + boff + n * 2048 + k * 1024); } while (0)
; #define PG8_MMA(ai, bj, At, Bt) do { __builtin_amdgcn_s_setprio(1); _Pragma("unroll") for (int m = 0; m < 4; ++m) _Pragma("unroll") for (int n = 0; n < 2; ++n) _Pragma("unroll") for (int k = 0; k < 2; ++k) \
;         acc[ai][bj][m][n] = __builtin_amdgcn_mfma_f32_16x16x32_bf16(Bt[n][k], At[m][k], acc[ai][bj][m][n], 0, 0, 0); __builtin_amdgcn_s_setprio(0); } while (0)
; #define PG8_WAIT_V(n) asm volatile("s_waitcnt vmcnt(" #n ")" ::: "memory")
; #define PG8_WAIT_L(n) asm volatile("s_waitcnt lgkmcnt(" #n ")" ::: "memory")
; #define PG8_BAR __builtin_amdgcn_s_barrier()
; #define PG8_SCHED __builtin_amdgcn_sched_barrier(0)
; template <class Epi, class Sched, bool ALIGN_EPI = false, bool SP2 = false>
; __device__ __forceinline__ void gemm_phase(PG8_LAS unsigned char* lds, const Gemm g, const Sched& S, const Epi& E) {
;     ...
;             PG8_LDB(B0, 1, 0); PG8_LDB(B1, 1, 1); PG8_SCHED; PG8_LDA(At, 1, 0); PG8_STAGE(PG8_SA(0, 1), a2 + hstep, voffA);
;             PG8_WAIT_V(8); PG8_WAIT_L(0); PG8_BAR; PG8_MMA(0, 0, At, B0); PG8_MMA(0, 1, At, B1); PG8_BAR; PG8_SCHED;
;             PG8_LDA(At, 1, 1); PG8_STAGE(PG8_SB(1, 0), b3, voffB); PG8_STAGE(PG8_SB(1, 1), b3 + hstep, voffB); PG8_STAGE(PG8_SA(1, 0), a3, voffA);
;             PG8_WAIT_V(8); PG8_WAIT_L(0); PG8_BAR; PG8_MMA(1, 0, At, B0); PG8_MMA(1, 1, At, B1); PG8_BAR; PG8_SCHED;
	ds_read_b128 v[140:143], v254 offset:32768
	ds_read_b128 v[162:165], v254 offset:33792
	ds_read_b128 v[166:169], v254 offset:34816
	ds_read_b128 v[176:179], v254 offset:35840
	ds_read_b128 v[180:183], v254 offset:49152
	ds_read_b128 v[184:187], v254 offset:50176
	ds_read_b128 v[188:191], v254 offset:51200
	ds_read_b128 v[244:247], v254 offset:52224
	s_add_u32 s4, s4, 0x40000
	s_addc_u32 s5, s5, 0
	s_mov_b32 m0, s33
	ds_read_b128 v[212:215], v173 offset:32768
	ds_read_b128 v[216:219], v173 offset:33792
	ds_read_b128 v[220:223], v173 offset:34816
	ds_read_b128 v[224:227], v173 offset:35840
	ds_read_b128 v[228:231], v173 offset:36864
	ds_read_b128 v[232:235], v173 offset:37888
	ds_read_b128 v[236:239], v173 offset:38912
	ds_read_b128 v[240:243], v173 offset:39936
	global_load_lds_dwordx4 v134, s[4:5]
	s_mov_b32 m0, s34
	s_nop 0
	global_load_lds_dwordx4 v130, s[4:5]
	s_waitcnt vmcnt(8)
	s_waitcnt lgkmcnt(0)
	s_barrier
	s_setprio 1
	v_mfma_f32_16x16x32_bf16 v[124:127], v[140:143], v[212:215], v[124:127]
	v_mfma_f32_16x16x32_bf16 v[124:127], v[162:165], v[216:219], v[124:127]
	v_mfma_f32_16x16x32_bf16 v[112:115], v[140:143], v[220:223], v[112:115]
	v_mfma_f32_16x16x32_bf16 v[112:115], v[162:165], v[224:227], v[112:115]
	v_mfma_f32_16x16x32_bf16 v[96:99], v[140:143], v[228:231], v[96:99]
	v_mfma_f32_16x16x32_bf16 v[96:99], v[162:165], v[232:235], v[96:99]
	v_mfma_f32_16x16x32_bf16 v[80:83], v[140:143], v[236:239], v[80:83]
	v_mfma_f32_16x16x32_bf16 v[80:83], v[162:165], v[240:243], v[80:83]
	v_mfma_f32_16x16x32_bf16 v[120:123], v[166:169], v[212:215], v[120:123]
	v_mfma_f32_16x16x32_bf16 v[120:123], v[176:179], v[216:219], v[120:123]
	v_mfma_f32_16x16x32_bf16 v[104:107], v[166:169], v[220:223], v[104:107]
	v_mfma_f32_16x16x32_bf16 v[104:107], v[176:179], v[224:227], v[104:107]
	v_mfma_f32_16x16x32_bf16 v[88:91], v[166:169], v[228:231], v[88:91]
	v_mfma_f32_16x16x32_bf16 v[88:91], v[176:179], v[232:235], v[88:91]
	v_mfma_f32_16x16x32_bf16 v[72:75], v[166:169], v[236:239], v[72:75]
	v_mfma_f32_16x16x32_bf16 v[72:75], v[176:179], v[240:243], v[72:75]
	v_mfma_f32_16x16x32_bf16 v[116:119], v[180:183], v[212:215], v[116:119]
	v_mfma_f32_16x16x32_bf16 v[116:119], v[184:187], v[216:219], v[116:119]
	v_mfma_f32_16x16x32_bf16 v[100:103], v[180:183], v[220:223], v[100:103]
	v_mfma_f32_16x16x32_bf16 v[100:103], v[184:187], v[224:227], v[100:103]
	v_mfma_f32_16x16x32_bf16 v[84:87], v[180:183], v[228:231], v[84:87]
	v_mfma_f32_16x16x32_bf16 v[84:87], v[184:187], v[232:235], v[84:87]
	v_mfma_f32_16x16x32_bf16 v[68:71], v[180:183], v[236:239], v[68:71]
	v_mfma_f32_16x16x32_bf16 v[68:71], v[184:187], v[240:243], v[68:71]
	v_mfma_f32_16x16x32_bf16 v[108:111], v[188:191], v[212:215], v[108:111]
	v_mfma_f32_16x16x32_bf16 v[108:111], v[244:247], v[216:219], v[108:111]
	v_mfma_f32_16x16x32_bf16 v[92:95], v[188:191], v[220:223], v[92:95]
	v_mfma_f32_16x16x32_bf16 v[92:95], v[244:247], v[224:227], v[92:95]
	v_mfma_f32_16x16x32_bf16 v[76:79], v[188:191], v[228:231], v[76:79]
	v_mfma_f32_16x16x32_bf16 v[76:79], v[244:247], v[232:235], v[76:79]
	v_mfma_f32_16x16x32_bf16 v[64:67], v[188:191], v[236:239], v[64:67]
	v_mfma_f32_16x16x32_bf16 v[64:67], v[244:247], v[240:243], v[64:67]
	s_setprio 0
	s_barrier
	s_mov_b32 m0, s37
	s_add_u32 s2, s2, 0x40080
	s_addc_u32 s3, s3, 0
	ds_read_b128 v[212:215], v173 offset:49152
	ds_read_b128 v[216:219], v173 offset:50176
	ds_read_b128 v[220:223], v173 offset:51200
	ds_read_b128 v[224:227], v173 offset:52224
	ds_read_b128 v[228:231], v173 offset:53248
	ds_read_b128 v[232:235], v173 offset:54272
	ds_read_b128 v[236:239], v173 offset:55296
	ds_read_b128 v[240:243], v173 offset:56320
	s_add_u32 s98, s2, 0xfffc0000
	s_addc_u32 s99, s3, -1
	global_load_lds_dwordx4 v132, s[98:99]
	s_mov_b32 m0, s38
	s_nop 0
	global_load_lds_dwordx4 v128, s[98:99]
	s_mov_b32 m0, s41
	s_nop 0
	global_load_lds_dwordx4 v132, s[2:3]
	s_mov_b32 m0, s42
	s_nop 0
	global_load_lds_dwordx4 v128, s[2:3]
	s_mov_b32 m0, s39
	s_nop 0
	s_add_u32 s100, s4, 0xfffc0080
	s_addc_u32 s101, s5, -1
	global_load_lds_dwordx4 v134, s[100:101]
	s_mov_b32 m0, s40
	s_nop 0
	global_load_lds_dwordx4 v130, s[100:101]
	s_waitcnt vmcnt(8)
	s_waitcnt lgkmcnt(0)
	s_barrier
	s_setprio 1
	v_mfma_f32_16x16x32_bf16 v[60:63], v[140:143], v[212:215], v[60:63]
	v_mfma_f32_16x16x32_bf16 v[60:63], v[162:165], v[216:219], v[60:63]
	v_mfma_f32_16x16x32_bf16 v[48:51], v[140:143], v[220:223], v[48:51]
	v_mfma_f32_16x16x32_bf16 v[48:51], v[162:165], v[224:227], v[48:51]
	v_mfma_f32_16x16x32_bf16 v[32:35], v[140:143], v[228:231], v[32:35]
	v_mfma_f32_16x16x32_bf16 v[32:35], v[162:165], v[232:235], v[32:35]
	v_mfma_f32_16x16x32_bf16 v[16:19], v[140:143], v[236:239], v[16:19]
	v_mfma_f32_16x16x32_bf16 v[16:19], v[162:165], v[240:243], v[16:19]
	v_mfma_f32_16x16x32_bf16 v[56:59], v[166:169], v[212:215], v[56:59]
	v_mfma_f32_16x16x32_bf16 v[56:59], v[176:179], v[216:219], v[56:59]
	v_mfma_f32_16x16x32_bf16 v[40:43], v[166:169], v[220:223], v[40:43]
	v_mfma_f32_16x16x32_bf16 v[40:43], v[176:179], v[224:227], v[40:43]
	v_mfma_f32_16x16x32_bf16 v[24:27], v[166:169], v[228:231], v[24:27]
	v_mfma_f32_16x16x32_bf16 v[24:27], v[176:179], v[232:235], v[24:27]
	v_mfma_f32_16x16x32_bf16 v[8:11], v[166:169], v[236:239], v[8:11]
	v_mfma_f32_16x16x32_bf16 v[8:11], v[176:179], v[240:243], v[8:11]
	v_mfma_f32_16x16x32_bf16 v[52:55], v[180:183], v[212:215], v[52:55]
	v_mfma_f32_16x16x32_bf16 v[52:55], v[184:187], v[216:219], v[52:55]
	v_mfma_f32_16x16x32_bf16 v[36:39], v[180:183], v[220:223], v[36:39]
	v_mfma_f32_16x16x32_bf16 v[36:39], v[184:187], v[224:227], v[36:39]
	v_mfma_f32_16x16x32_bf16 v[20:23], v[180:183], v[228:231], v[20:23]
	v_mfma_f32_16x16x32_bf16 v[20:23], v[184:187], v[232:235], v[20:23]
	v_mfma_f32_16x16x32_bf16 v[4:7], v[180:183], v[236:239], v[4:7]
	v_mfma_f32_16x16x32_bf16 v[4:7], v[184:187], v[240:243], v[4:7]
	v_mfma_f32_16x16x32_bf16 v[44:47], v[188:191], v[212:215], v[44:47]
	v_mfma_f32_16x16x32_bf16 v[44:47], v[244:247], v[216:219], v[44:47]
	v_mfma_f32_16x16x32_bf16 v[28:31], v[188:191], v[220:223], v[28:31]
	v_mfma_f32_16x16x32_bf16 v[28:31], v[244:247], v[224:227], v[28:31]
	v_mfma_f32_16x16x32_bf16 v[12:15], v[188:191], v[228:231], v[12:15]
	v_mfma_f32_16x16x32_bf16 v[12:15], v[244:247], v[232:235], v[12:15]
	v_mfma_f32_16x16x32_bf16 v[0:3], v[188:191], v[236:239], v[0:3]
	v_mfma_f32_16x16x32_bf16 v[0:3], v[244:247], v[240:243], v[0:3]
	s_setprio 0
	s_barrier
	s_add_i32 s52, s52, 2
	s_add_u32 s0, s0, 0x100
	s_addc_u32 s1, s1, 0
	s_add_u32 s50, s50, 0x100
	s_addc_u32 s51, s51, 0
	s_cmp_gt_u32 s52, 13
; #define PG8_STAGE(bufoff, gbase, voff) do { _Pragma("unroll") for (int _i = 0; _i < 2; ++_i) \
;         __builtin_amdgcn_global_load_lds((const unsigned*)((const char*)(gbase) + (voff)[_i]), (PG8_LAS unsigned*)(lds + (bufoff) + ldsw + _i * 8192), 16, 0, 0); } while (0)
; #define PG8_LDA(dst, b, h) do { _Pragma("unroll") for (int m = 0; m < 4; ++m) _Pragma("unroll") for (int k = 0; k < 2; ++k) dst[m][k] = *(const PG8_LAS bf16x8*)(lds + PG8_SA(b, h) + aoff + m * 2048 + k * 1024); } while (0)
; #define PG8_LDB(dst, b, h) do { _Pragma("unroll") for (int n = 0; n < 2; ++n) _Pragma("unroll") for (int k = 0; k < 2; ++k) dst[n][k] = *(const PG8_LAS bf16x8*)(lds + PG8_SB(b, h) + boff + n * 2048 + k * 1024); } while (0)
; #define PG8_MMA(ai, bj, At, Bt) do { __builtin_amdgcn_s_setprio(1); _Pragma("unroll") for (int m = 0; m < 4; ++m) _Pragma("unroll") for (int n = 0; n < 2; ++n) _Pragma("unroll") for (int k = 0; k < 2; ++k) \
;         acc[ai][bj][m][n] = __builtin_amdgcn_mfma_f32_16x16x32_bf16(Bt[n][k], At[m][k], acc[ai][bj][m][n], 0, 0, 0); __builtin_amdgcn_s_setprio(0); } while (0)
; #define PG8_WAIT_V(n) asm volatile("s_waitcnt vmcnt(" #n ")" ::: "memory")
; #define PG8_WAIT_L(n) asm volatile("s_waitcnt lgkmcnt(" #n ")" ::: "memory")
; #define PG8_BAR __builtin_amdgcn_s_barrier()
; #define PG8_SCHED __builtin_amdgcn_sched_barrier(0)
; template <class Epi, class Sched, bool ALIGN_EPI = false, bool SP2 = false>
; __device__ __forceinline__ void gemm_phase(PG8_LAS unsigned char* lds, const Gemm g, const Sched& S, const Epi& E) {
;     ...
;             PG8_LDB(B0, 0, 0); PG8_LDB(B1, 0, 1); PG8_SCHED; PG8_LDA(At, 0, 0); PG8_STAGE(PG8_SA(1, 1), a1 + hstep, voffA);
;             PG8_WAIT_V(8); PG8_WAIT_L(0); PG8_BAR; PG8_MMA(0, 0, At, B0); PG8_MMA(0, 1, At, B1); PG8_BAR; PG8_SCHED;
;             PG8_LDA(At, 0, 1); PG8_STAGE(PG8_SB(0, 0), b2, voffB); PG8_STAGE(PG8_SB(0, 1), b2 + hstep, voffB); PG8_STAGE(PG8_SA(0, 0), a2, voffA);
;             PG8_WAIT_V(8); PG8_WAIT_L(0); PG8_BAR; PG8_MMA(1, 0, At, B0); PG8_MMA(1, 1, At, B1); PG8_BAR; PG8_SCHED;
.LBB0_792:
	s_waitcnt lgkmcnt(0)
	ds_read_b128 v[140:143], v254
	ds_read_b128 v[162:165], v254 offset:1024
	ds_read_b128 v[166:169], v254 offset:2048
	ds_read_b128 v[176:179], v254 offset:3072
	ds_read_b128 v[180:183], v254 offset:16384
	ds_read_b128 v[184:187], v254 offset:17408
	ds_read_b128 v[188:191], v254 offset:18432
	ds_read_b128 v[244:247], v254 offset:19456
	s_add_u32 s2, s0, 0xfffc0080
	s_addc_u32 s3, s1, -1
	s_cmp_eq_u32 s52, 12
	s_cselect_b32 s5, s17, s3
	s_cselect_b32 s4, s48, s2
	s_cselect_b32 s3, s15, s51
	s_cselect_b32 s2, s49, s50
	s_add_i32 m0, s6, 0xc000
	ds_read_b128 v[212:215], v173
	ds_read_b128 v[216:219], v173 offset:1024
	ds_read_b128 v[220:223], v173 offset:2048
	ds_read_b128 v[224:227], v173 offset:3072
	ds_read_b128 v[228:231], v173 offset:4096
	ds_read_b128 v[232:235], v173 offset:5120
	ds_read_b128 v[236:239], v173 offset:6144
	ds_read_b128 v[240:243], v173 offset:7168
	global_load_lds_dwordx4 v136, s[0:1]
	s_add_i32 m0, s6, 0xe000
	s_nop 0
	global_load_lds_dwordx4 v138, s[0:1]
	s_waitcnt vmcnt(8)
	s_waitcnt lgkmcnt(0)
	s_barrier
	s_setprio 1
	v_mfma_f32_16x16x32_bf16 v[124:127], v[140:143], v[212:215], v[124:127]
	v_mfma_f32_16x16x32_bf16 v[124:127], v[162:165], v[216:219], v[124:127]
	v_mfma_f32_16x16x32_bf16 v[112:115], v[140:143], v[220:223], v[112:115]
	v_mfma_f32_16x16x32_bf16 v[112:115], v[162:165], v[224:227], v[112:115]
	v_mfma_f32_16x16x32_bf16 v[96:99], v[140:143], v[228:231], v[96:99]
	v_mfma_f32_16x16x32_bf16 v[96:99], v[162:165], v[232:235], v[96:99]
	v_mfma_f32_16x16x32_bf16 v[80:83], v[140:143], v[236:239], v[80:83]
	v_mfma_f32_16x16x32_bf16 v[80:83], v[162:165], v[240:243], v[80:83]
	v_mfma_f32_16x16x32_bf16 v[120:123], v[166:169], v[212:215], v[120:123]
	v_mfma_f32_16x16x32_bf16 v[120:123], v[176:179], v[216:219], v[120:123]
	v_mfma_f32_16x16x32_bf16 v[104:107], v[166:169], v[220:223], v[104:107]
	v_mfma_f32_16x16x32_bf16 v[104:107], v[176:179], v[224:227], v[104:107]
	v_mfma_f32_16x16x32_bf16 v[88:91], v[166:169], v[228:231], v[88:91]
	v_mfma_f32_16x16x32_bf16 v[88:91], v[176:179], v[232:235], v[88:91]
	v_mfma_f32_16x16x32_bf16 v[72:75], v[166:169], v[236:239], v[72:75]
	v_mfma_f32_16x16x32_bf16 v[72:75], v[176:179], v[240:243], v[72:75]
	v_mfma_f32_16x16x32_bf16 v[116:119], v[180:183], v[212:215], v[116:119]
	v_mfma_f32_16x16x32_bf16 v[116:119], v[184:187], v[216:219], v[116:119]
	v_mfma_f32_16x16x32_bf16 v[100:103], v[180:183], v[220:223], v[100:103]
	v_mfma_f32_16x16x32_bf16 v[100:103], v[184:187], v[224:227], v[100:103]
	v_mfma_f32_16x16x32_bf16 v[84:87], v[180:183], v[228:231], v[84:87]
	v_mfma_f32_16x16x32_bf16 v[84:87], v[184:187], v[232:235], v[84:87]
	v_mfma_f32_16x16x32_bf16 v[68:71], v[180:183], v[236:239], v[68:71]
	v_mfma_f32_16x16x32_bf16 v[68:71], v[184:187], v[240:243], v[68:71]
	v_mfma_f32_16x16x32_bf16 v[108:111], v[188:191], v[212:215], v[108:111]
	v_mfma_f32_16x16x32_bf16 v[108:111], v[244:247], v[216:219], v[108:111]
	v_mfma_f32_16x16x32_bf16 v[92:95], v[188:191], v[220:223], v[92:95]
	v_mfma_f32_16x16x32_bf16 v[92:95], v[244:247], v[224:227], v[92:95]
	v_mfma_f32_16x16x32_bf16 v[76:79], v[188:191], v[228:231], v[76:79]
	v_mfma_f32_16x16x32_bf16 v[76:79], v[244:247], v[232:235], v[76:79]
	v_mfma_f32_16x16x32_bf16 v[64:67], v[188:191], v[236:239], v[64:67]
	v_mfma_f32_16x16x32_bf16 v[64:67], v[244:247], v[240:243], v[64:67]
	s_setprio 0
	s_barrier
	s_mov_b32 m0, s27
	s_add_u32 s54, s2, 0x40000
	s_addc_u32 s55, s3, 0
	ds_read_b128 v[212:215], v173 offset:16384
	ds_read_b128 v[216:219], v173 offset:17408
	ds_read_b128 v[220:223], v173 offset:18432
	ds_read_b128 v[224:227], v173 offset:19456
	ds_read_b128 v[228:231], v173 offset:20480
	ds_read_b128 v[232:235], v173 offset:21504
	ds_read_b128 v[236:239], v173 offset:22528
	ds_read_b128 v[240:243], v173 offset:23552
	global_load_lds_dwordx4 v132, s[2:3]
	s_mov_b32 m0, s28
	s_nop 0
	global_load_lds_dwordx4 v128, s[2:3]
	s_mov_b32 m0, s29
	s_nop 0
	global_load_lds_dwordx4 v132, s[54:55]
	s_mov_b32 m0, s30
	s_nop 0
	global_load_lds_dwordx4 v128, s[54:55]
	s_mov_b32 m0, s6
	s_nop 0
	global_load_lds_dwordx4 v134, s[4:5]
	s_mov_b32 m0, s31
	s_nop 0
	global_load_lds_dwordx4 v130, s[4:5]
	s_waitcnt vmcnt(8)
	s_waitcnt lgkmcnt(0)
	s_barrier
	s_setprio 1
	v_mfma_f32_16x16x32_bf16 v[60:63], v[140:143], v[212:215], v[60:63]
	v_mfma_f32_16x16x32_bf16 v[60:63], v[162:165], v[216:219], v[60:63]
	v_mfma_f32_16x16x32_bf16 v[48:51], v[140:143], v[220:223], v[48:51]
	v_mfma_f32_16x16x32_bf16 v[48:51], v[162:165], v[224:227], v[48:51]
	v_mfma_f32_16x16x32_bf16 v[32:35], v[140:143], v[228:231], v[32:35]
	v_mfma_f32_16x16x32_bf16 v[32:35], v[162:165], v[232:235], v[32:35]
	v_mfma_f32_16x16x32_bf16 v[16:19], v[140:143], v[236:239], v[16:19]
	v_mfma_f32_16x16x32_bf16 v[16:19], v[162:165], v[240:243], v[16:19]
	v_mfma_f32_16x16x32_bf16 v[56:59], v[166:169], v[212:215], v[56:59]
	v_mfma_f32_16x16x32_bf16 v[56:59], v[176:179], v[216:219], v[56:59]
	v_mfma_f32_16x16x32_bf16 v[40:43], v[166:169], v[220:223], v[40:43]
	v_mfma_f32_16x16x32_bf16 v[40:43], v[176:179], v[224:227], v[40:43]
	v_mfma_f32_16x16x32_bf16 v[24:27], v[166:169], v[228:231], v[24:27]
	v_mfma_f32_16x16x32_bf16 v[24:27], v[176:179], v[232:235], v[24:27]
	v_mfma_f32_16x16x32_bf16 v[8:11], v[166:169], v[236:239], v[8:11]
	v_mfma_f32_16x16x32_bf16 v[8:11], v[176:179], v[240:243], v[8:11]
	v_mfma_f32_16x16x32_bf16 v[52:55], v[180:183], v[212:215], v[52:55]
	v_mfma_f32_16x16x32_bf16 v[52:55], v[184:187], v[216:219], v[52:55]
	v_mfma_f32_16x16x32_bf16 v[36:39], v[180:183], v[220:223], v[36:39]
	v_mfma_f32_16x16x32_bf16 v[36:39], v[184:187], v[224:227], v[36:39]
	v_mfma_f32_16x16x32_bf16 v[20:23], v[180:183], v[228:231], v[20:23]
	v_mfma_f32_16x16x32_bf16 v[20:23], v[184:187], v[232:235], v[20:23]
	v_mfma_f32_16x16x32_bf16 v[4:7], v[180:183], v[236:239], v[4:7]
	v_mfma_f32_16x16x32_bf16 v[4:7], v[184:187], v[240:243], v[4:7]
	v_mfma_f32_16x16x32_bf16 v[44:47], v[188:191], v[212:215], v[44:47]
	v_mfma_f32_16x16x32_bf16 v[44:47], v[244:247], v[216:219], v[44:47]
	v_mfma_f32_16x16x32_bf16 v[28:31], v[188:191], v[220:223], v[28:31]
	v_mfma_f32_16x16x32_bf16 v[28:31], v[244:247], v[224:227], v[28:31]
	v_mfma_f32_16x16x32_bf16 v[12:15], v[188:191], v[228:231], v[12:15]
	v_mfma_f32_16x16x32_bf16 v[12:15], v[244:247], v[232:235], v[12:15]
	v_mfma_f32_16x16x32_bf16 v[0:3], v[188:191], v[236:239], v[0:3]
	v_mfma_f32_16x16x32_bf16 v[0:3], v[244:247], v[240:243], v[0:3]
	s_setprio 0
	s_barrier
; #define PG8_STAGE(bufoff, gbase, voff) do { _Pragma("unroll") for (int _i = 0; _i < 2; ++_i) \
;         __builtin_amdgcn_global_load_lds((const unsigned*)((const char*)(gbase) + (voff)[_i]), (PG8_LAS unsigned*)(lds + (bufoff) + ldsw + _i * 8192), 16, 0, 0); } while (0)
; #define PG8_LDA(dst, b, h) do { _Pragma("unroll") for (int m = 0; m < 4; ++m) _Pragma("unroll") for (int k = 0; k < 2; ++k) dst[m][k] = *(const PG8_LAS bf16x8*)(lds + PG8_SA(b, h) + aoff + m * 2048 + k * 1024); } while (0)
; #define PG8_LDB(dst, b, h) do { _Pragma("unroll") for (int n = 0; n < 2; ++n) _Pragma("unroll") for (int k = 0; k < 2; ++k) dst[n][k] = *(const PG8_LAS bf16x8*)(lds + PG8_SB(b, h) + boff + n * 2048 + k * 1024); } while (0)
; #define PG8_MMA(ai, bj, At, Bt) do { __builtin_amdgcn_s_setprio(1); _Pragma("unroll") for (int m = 0; m < 4; ++m) _Pragma("unroll") for (int n = 0; n < 2; ++n) _Pragma("unroll") for (int k = 0; k < 2; ++k) \
;         acc[ai][bj][m][n] = __builtin_amdgcn_mfma_f32_16x16x32_bf16(Bt[n][k], At[m][k], acc[ai][bj][m][n], 0, 0, 0); __builtin_amdgcn_s_setprio(0); } while (0)
; #define PG8_WAIT_V(n) asm volatile("s_waitcnt vmcnt(" #n ")" ::: "memory")
; #define PG8_WAIT_L(n) asm volatile("s_waitcnt lgkmcnt(" #n ")" ::: "memory")
; #define PG8_BAR __builtin_amdgcn_s_barrier()
; #define PG8_SCHED __builtin_amdgcn_sched_barrier(0)
; template <class Epi, class Sched, bool ALIGN_EPI = false, bool SP2 = false>
; __device__ __forceinline__ void gemm_phase(PG8_LAS unsigned char* lds, const Gemm g, const Sched& S, const Epi& E) {
;     ...
;         for (int t = 0; t < nt; t += 2) {
;     ...
;             PG8_LDB(B0, 1, 0); PG8_LDB(B1, 1, 1); PG8_SCHED; PG8_LDA(At, 1, 0); PG8_STAGE(PG8_SA(0, 1), a2 + hstep, voffA);
;             PG8_WAIT_V(8); PG8_WAIT_L(0); PG8_BAR; PG8_MMA(0, 0, At, B0); PG8_MMA(0, 1, At, B1); PG8_BAR; PG8_SCHED;
;             PG8_LDA(At, 1, 1); PG8_STAGE(PG8_SB(1, 0), b3, voffB); PG8_STAGE(PG8_SB(1, 1), b3 + hstep, voffB); PG8_STAGE(PG8_SA(1, 0), a3, voffA);
;             PG8_WAIT_V(8); PG8_WAIT_L(0); PG8_BAR; PG8_MMA(1, 0, At, B0); PG8_MMA(1, 1, At, B1); PG8_BAR; PG8_SCHED;
	ds_read_b128 v[140:143], v254 offset:32768
	ds_read_b128 v[162:165], v254 offset:33792
	ds_read_b128 v[166:169], v254 offset:34816
	ds_read_b128 v[176:179], v254 offset:35840
	ds_read_b128 v[180:183], v254 offset:49152
	ds_read_b128 v[184:187], v254 offset:50176
	ds_read_b128 v[188:191], v254 offset:51200
	ds_read_b128 v[244:247], v254 offset:52224
	s_add_u32 s4, s4, 0x40000
	s_addc_u32 s5, s5, 0
	s_mov_b32 m0, s33
	ds_read_b128 v[212:215], v173 offset:32768
	ds_read_b128 v[216:219], v173 offset:33792
	ds_read_b128 v[220:223], v173 offset:34816
	ds_read_b128 v[224:227], v173 offset:35840
	ds_read_b128 v[228:231], v173 offset:36864
	ds_read_b128 v[232:235], v173 offset:37888
	ds_read_b128 v[236:239], v173 offset:38912
	ds_read_b128 v[240:243], v173 offset:39936
	global_load_lds_dwordx4 v134, s[4:5]
	s_mov_b32 m0, s34
	s_nop 0
	global_load_lds_dwordx4 v130, s[4:5]
	s_waitcnt vmcnt(8)
	s_waitcnt lgkmcnt(0)
	s_barrier
	s_setprio 1
	v_mfma_f32_16x16x32_bf16 v[124:127], v[140:143], v[212:215], v[124:127]
	v_mfma_f32_16x16x32_bf16 v[124:127], v[162:165], v[216:219], v[124:127]
	v_mfma_f32_16x16x32_bf16 v[112:115], v[140:143], v[220:223], v[112:115]
	v_mfma_f32_16x16x32_bf16 v[112:115], v[162:165], v[224:227], v[112:115]
	v_mfma_f32_16x16x32_bf16 v[96:99], v[140:143], v[228:231], v[96:99]
	v_mfma_f32_16x16x32_bf16 v[96:99], v[162:165], v[232:235], v[96:99]
	v_mfma_f32_16x16x32_bf16 v[80:83], v[140:143], v[236:239], v[80:83]
	v_mfma_f32_16x16x32_bf16 v[80:83], v[162:165], v[240:243], v[80:83]
	v_mfma_f32_16x16x32_bf16 v[120:123], v[166:169], v[212:215], v[120:123]
	v_mfma_f32_16x16x32_bf16 v[120:123], v[176:179], v[216:219], v[120:123]
	v_mfma_f32_16x16x32_bf16 v[104:107], v[166:169], v[220:223], v[104:107]
	v_mfma_f32_16x16x32_bf16 v[104:107], v[176:179], v[224:227], v[104:107]
	v_mfma_f32_16x16x32_bf16 v[88:91], v[166:169], v[228:231], v[88:91]
	v_mfma_f32_16x16x32_bf16 v[88:91], v[176:179], v[232:235], v[88:91]
	v_mfma_f32_16x16x32_bf16 v[72:75], v[166:169], v[236:239], v[72:75]
	v_mfma_f32_16x16x32_bf16 v[72:75], v[176:179], v[240:243], v[72:75]
	v_mfma_f32_16x16x32_bf16 v[116:119], v[180:183], v[212:215], v[116:119]
	v_mfma_f32_16x16x32_bf16 v[116:119], v[184:187], v[216:219], v[116:119]
	v_mfma_f32_16x16x32_bf16 v[100:103], v[180:183], v[220:223], v[100:103]
	v_mfma_f32_16x16x32_bf16 v[100:103], v[184:187], v[224:227], v[100:103]
	v_mfma_f32_16x16x32_bf16 v[84:87], v[180:183], v[228:231], v[84:87]
	v_mfma_f32_16x16x32_bf16 v[84:87], v[184:187], v[232:235], v[84:87]
	v_mfma_f32_16x16x32_bf16 v[68:71], v[180:183], v[236:239], v[68:71]
	v_mfma_f32_16x16x32_bf16 v[68:71], v[184:187], v[240:243], v[68:71]
	v_mfma_f32_16x16x32_bf16 v[108:111], v[188:191], v[212:215], v[108:111]
	v_mfma_f32_16x16x32_bf16 v[108:111], v[244:247], v[216:219], v[108:111]
	v_mfma_f32_16x16x32_bf16 v[92:95], v[188:191], v[220:223], v[92:95]
	v_mfma_f32_16x16x32_bf16 v[92:95], v[244:247], v[224:227], v[92:95]
	v_mfma_f32_16x16x32_bf16 v[76:79], v[188:191], v[228:231], v[76:79]
	v_mfma_f32_16x16x32_bf16 v[76:79], v[244:247], v[232:235], v[76:79]
	v_mfma_f32_16x16x32_bf16 v[64:67], v[188:191], v[236:239], v[64:67]
	v_mfma_f32_16x16x32_bf16 v[64:67], v[244:247], v[240:243], v[64:67]
	s_setprio 0
	s_barrier
	s_mov_b32 m0, s37
	s_add_u32 s2, s2, 0x40080
	s_addc_u32 s3, s3, 0
	ds_read_b128 v[212:215], v173 offset:49152
	ds_read_b128 v[216:219], v173 offset:50176
	ds_read_b128 v[220:223], v173 offset:51200
	ds_read_b128 v[224:227], v173 offset:52224
	ds_read_b128 v[228:231], v173 offset:53248
	ds_read_b128 v[232:235], v173 offset:54272
	ds_read_b128 v[236:239], v173 offset:55296
	ds_read_b128 v[240:243], v173 offset:56320
	s_add_u32 s98, s2, 0xfffc0000
	s_addc_u32 s99, s3, -1
	global_load_lds_dwordx4 v132, s[98:99]
	s_mov_b32 m0, s38
	s_nop 0
	global_load_lds_dwordx4 v128, s[98:99]
	s_mov_b32 m0, s41
	s_nop 0
	global_load_lds_dwordx4 v132, s[2:3]
	s_mov_b32 m0, s42
	s_nop 0
	global_load_lds_dwordx4 v128, s[2:3]
	s_mov_b32 m0, s39
	s_nop 0
	s_add_u32 s100, s4, 0xfffc0080
	s_addc_u32 s101, s5, -1
	global_load_lds_dwordx4 v134, s[100:101]
	s_mov_b32 m0, s40
	s_nop 0
	global_load_lds_dwordx4 v130, s[100:101]
	s_waitcnt vmcnt(8)
	s_waitcnt lgkmcnt(0)
	s_barrier
	s_setprio 1
	v_mfma_f32_16x16x32_bf16 v[60:63], v[140:143], v[212:215], v[60:63]
	v_mfma_f32_16x16x32_bf16 v[60:63], v[162:165], v[216:219], v[60:63]
	v_mfma_f32_16x16x32_bf16 v[48:51], v[140:143], v[220:223], v[48:51]
	v_mfma_f32_16x16x32_bf16 v[48:51], v[162:165], v[224:227], v[48:51]
	v_mfma_f32_16x16x32_bf16 v[32:35], v[140:143], v[228:231], v[32:35]
	v_mfma_f32_16x16x32_bf16 v[32:35], v[162:165], v[232:235], v[32:35]
	v_mfma_f32_16x16x32_bf16 v[16:19], v[140:143], v[236:239], v[16:19]
	v_mfma_f32_16x16x32_bf16 v[16:19], v[162:165], v[240:243], v[16:19]
	v_mfma_f32_16x16x32_bf16 v[56:59], v[166:169], v[212:215], v[56:59]
	v_mfma_f32_16x16x32_bf16 v[56:59], v[176:179], v[216:219], v[56:59]
	v_mfma_f32_16x16x32_bf16 v[40:43], v[166:169], v[220:223], v[40:43]
	v_mfma_f32_16x16x32_bf16 v[40:43], v[176:179], v[224:227], v[40:43]
	v_mfma_f32_16x16x32_bf16 v[24:27], v[166:169], v[228:231], v[24:27]
	v_mfma_f32_16x16x32_bf16 v[24:27], v[176:179], v[232:235], v[24:27]
	v_mfma_f32_16x16x32_bf16 v[8:11], v[166:169], v[236:239], v[8:11]
	v_mfma_f32_16x16x32_bf16 v[8:11], v[176:179], v[240:243], v[8:11]
	v_mfma_f32_16x16x32_bf16 v[52:55], v[180:183], v[212:215], v[52:55]
	v_mfma_f32_16x16x32_bf16 v[52:55], v[184:187], v[216:219], v[52:55]
	v_mfma_f32_16x16x32_bf16 v[36:39], v[180:183], v[220:223], v[36:39]
	v_mfma_f32_16x16x32_bf16 v[36:39], v[184:187], v[224:227], v[36:39]
	v_mfma_f32_16x16x32_bf16 v[20:23], v[180:183], v[228:231], v[20:23]
	v_mfma_f32_16x16x32_bf16 v[20:23], v[184:187], v[232:235], v[20:23]
	v_mfma_f32_16x16x32_bf16 v[4:7], v[180:183], v[236:239], v[4:7]
	v_mfma_f32_16x16x32_bf16 v[4:7], v[184:187], v[240:243], v[4:7]
	v_mfma_f32_16x16x32_bf16 v[44:47], v[188:191], v[212:215], v[44:47]
	v_mfma_f32_16x16x32_bf16 v[44:47], v[244:247], v[216:219], v[44:47]
	v_mfma_f32_16x16x32_bf16 v[28:31], v[188:191], v[220:223], v[28:31]
	v_mfma_f32_16x16x32_bf16 v[28:31], v[244:247], v[224:227], v[28:31]
	v_mfma_f32_16x16x32_bf16 v[12:15], v[188:191], v[228:231], v[12:15]
	v_mfma_f32_16x16x32_bf16 v[12:15], v[244:247], v[232:235], v[12:15]
	v_mfma_f32_16x16x32_bf16 v[0:3], v[188:191], v[236:239], v[0:3]
	v_mfma_f32_16x16x32_bf16 v[0:3], v[244:247], v[240:243], v[0:3]
	s_setprio 0
	s_barrier
	s_add_i32 s52, s52, 2
	s_add_u32 s0, s0, 0x100
	s_addc_u32 s1, s1, 0
	s_add_u32 s50, s50, 0x100
	s_addc_u32 s51, s51, 0
	s_cmp_gt_u32 s52, 13
	s_cbranch_scc0 .LBB0_792
	s_and_b64 vcc, exec, s[12:13]
	s_cbranch_vccz .LBB0_795
	s_barrier

; #define PG8_STAGE(bufoff, gbase, voff) do { _Pragma("unroll") for (int _i = 0; _i < 2; ++_i) \
;         __builtin_amdgcn_global_load_lds((const unsigned*)((const char*)(gbase) + (voff)[_i]), (PG8_LAS unsigned*)(lds + (bufoff) + ldsw + _i * 8192), 16, 0, 0); } while (0)
; #define PG8_LDA(dst, b, h) do { _Pragma("unroll") for (int m = 0; m < 4; ++m) _Pragma("unroll") for (int k = 0; k < 2; ++k) dst[m][k] = *(const PG8_LAS bf16x8*)(lds + PG8_SA(b, h) + aoff + m * 2048 + k * 1024); } while (0)
; #define PG8_LDB(dst, b, h) do { _Pragma("unroll") for (int n = 0; n < 2; ++n) _Pragma("unroll") for (int k = 0; k < 2; ++k) dst[n][k] = *(const PG8_LAS bf16x8*)(lds + PG8_SB(b, h) + boff + n * 2048 + k * 1024); } while (0)
; #define PG8_MMA(ai, bj, At, Bt) do { __builtin_amdgcn_s_setprio(1); _Pragma("unroll") for (int m = 0; m < 4; ++m) _Pragma("unroll") for (int n = 0; n < 2; ++n) _Pragma("unroll") for (int k = 0; k < 2; ++k) \
;         acc[ai][bj][m][n] = __builtin_amdgcn_mfma_f32_16x16x32_bf16(Bt[n][k], At[m][k], acc[ai][bj][m][n], 0, 0, 0); __builtin_amdgcn_s_setprio(0); } while (0)
; #define PG8_WAIT_V(n) asm volatile("s_waitcnt vmcnt(" #n ")" ::: "memory")
; #define PG8_WAIT_L(n) asm volatile("s_waitcnt lgkmcnt(" #n ")" ::: "memory")
; #define PG8_BAR __builtin_amdgcn_s_barrier()
; #define PG8_SCHED __builtin_amdgcn_sched_barrier(0)
; template <class Epi, class Sched, bool ALIGN_EPI = false, bool SP2 = false>
; __device__ __forceinline__ void gemm_phase(PG8_LAS unsigned char* lds, const Gemm g, const Sched& S, const Epi& E) {
;     ...
;             PG8_LDB(B0, 0, 0); PG8_LDB(B1, 0, 1); PG8_SCHED; PG8_LDA(At, 0, 0); PG8_STAGE(PG8_SA(1, 1), a1 + hstep, voffA);
;             PG8_WAIT_V(8); PG8_WAIT_L(0); PG8_BAR; PG8_MMA(0, 0, At, B0); PG8_MMA(0, 1, At, B1); PG8_BAR; PG8_SCHED;
;             PG8_LDA(At, 0, 1); PG8_STAGE(PG8_SB(0, 0), b2, voffB); PG8_STAGE(PG8_SB(0, 1), b2 + hstep, voffB); PG8_STAGE(PG8_SA(0, 0), a2, voffA);
;             PG8_WAIT_V(8); PG8_WAIT_L(0); PG8_BAR; PG8_MMA(1, 0, At, B0); PG8_MMA(1, 1, At, B1); PG8_BAR; PG8_SCHED;
.Lsgo_peel:
	ds_read_b128 v[140:143], v254
	ds_read_b128 v[166:169], v254 offset:1024
	ds_read_b128 v[170:173], v254 offset:2048
	ds_read_b128 v[174:177], v254 offset:3072
	ds_read_b128 v[178:181], v254 offset:16384
	ds_read_b128 v[182:185], v254 offset:17408
	ds_read_b128 v[186:189], v254 offset:18432
	ds_read_b128 v[244:247], v254 offset:19456
	s_add_u32 s2, s0, 0xfffc0080
	s_addc_u32 s3, s1, -1
	s_cmp_eq_u32 s55, 12
	s_cselect_b32 s5, s23, s3
	s_cselect_b32 s4, s51, s2
	s_cselect_b32 s3, s21, s54
	s_cselect_b32 s2, s52, s53
	s_add_i32 m0, s31, 0xc000
	ds_read_b128 v[212:215], v163
	ds_read_b128 v[216:219], v163 offset:1024
	ds_read_b128 v[220:223], v163 offset:2048
	ds_read_b128 v[224:227], v163 offset:3072
	ds_read_b128 v[228:231], v163 offset:4096
	ds_read_b128 v[232:235], v163 offset:5120
	ds_read_b128 v[236:239], v163 offset:6144
	ds_read_b128 v[240:243], v163 offset:7168
	global_load_lds_dwordx4 v136, s[0:1]
	s_add_i32 m0, s31, 0xe000
	s_nop 0
	global_load_lds_dwordx4 v138, s[0:1]
	s_waitcnt vmcnt(8)
	s_waitcnt lgkmcnt(0)
	s_barrier
	s_setprio 1
	v_mfma_f32_16x16x32_bf16 v[124:127], v[140:143], v[212:215], 0
	v_mfma_f32_16x16x32_bf16 v[124:127], v[166:169], v[216:219], v[124:127]
	v_mfma_f32_16x16x32_bf16 v[108:111], v[140:143], v[220:223], 0
	v_mfma_f32_16x16x32_bf16 v[108:111], v[166:169], v[224:227], v[108:111]
	v_mfma_f32_16x16x32_bf16 v[92:95], v[140:143], v[228:231], 0
	v_mfma_f32_16x16x32_bf16 v[92:95], v[166:169], v[232:235], v[92:95]
	v_mfma_f32_16x16x32_bf16 v[76:79], v[140:143], v[236:239], 0
	v_mfma_f32_16x16x32_bf16 v[76:79], v[166:169], v[240:243], v[76:79]
	v_mfma_f32_16x16x32_bf16 v[120:123], v[170:173], v[212:215], 0
	v_mfma_f32_16x16x32_bf16 v[120:123], v[174:177], v[216:219], v[120:123]
	v_mfma_f32_16x16x32_bf16 v[104:107], v[170:173], v[220:223], 0
	v_mfma_f32_16x16x32_bf16 v[104:107], v[174:177], v[224:227], v[104:107]
	v_mfma_f32_16x16x32_bf16 v[88:91], v[170:173], v[228:231], 0
	v_mfma_f32_16x16x32_bf16 v[88:91], v[174:177], v[232:235], v[88:91]
	v_mfma_f32_16x16x32_bf16 v[72:75], v[170:173], v[236:239], 0
	v_mfma_f32_16x16x32_bf16 v[72:75], v[174:177], v[240:243], v[72:75]
	v_mfma_f32_16x16x32_bf16 v[116:119], v[178:181], v[212:215], 0
	v_mfma_f32_16x16x32_bf16 v[116:119], v[182:185], v[216:219], v[116:119]
	v_mfma_f32_16x16x32_bf16 v[100:103], v[178:181], v[220:223], 0
	v_mfma_f32_16x16x32_bf16 v[100:103], v[182:185], v[224:227], v[100:103]
	v_mfma_f32_16x16x32_bf16 v[84:87], v[178:181], v[228:231], 0
	v_mfma_f32_16x16x32_bf16 v[84:87], v[182:185], v[232:235], v[84:87]
	v_mfma_f32_16x16x32_bf16 v[68:71], v[178:181], v[236:239], 0
	v_mfma_f32_16x16x32_bf16 v[68:71], v[182:185], v[240:243], v[68:71]
	v_mfma_f32_16x16x32_bf16 v[112:115], v[186:189], v[212:215], 0
	v_mfma_f32_16x16x32_bf16 v[112:115], v[244:247], v[216:219], v[112:115]
	v_mfma_f32_16x16x32_bf16 v[96:99], v[186:189], v[220:223], 0
	v_mfma_f32_16x16x32_bf16 v[96:99], v[244:247], v[224:227], v[96:99]
	v_mfma_f32_16x16x32_bf16 v[80:83], v[186:189], v[228:231], 0
	v_mfma_f32_16x16x32_bf16 v[80:83], v[244:247], v[232:235], v[80:83]
	v_mfma_f32_16x16x32_bf16 v[64:67], v[186:189], v[236:239], 0
	v_mfma_f32_16x16x32_bf16 v[64:67], v[244:247], v[240:243], v[64:67]
	s_setprio 0
	s_barrier
	s_mov_b32 m0, s33
	s_add_u32 s56, s2, 0x40000
	s_addc_u32 s57, s3, 0
	ds_read_b128 v[212:215], v163 offset:16384
	ds_read_b128 v[216:219], v163 offset:17408
	ds_read_b128 v[220:223], v163 offset:18432
	ds_read_b128 v[224:227], v163 offset:19456
	ds_read_b128 v[228:231], v163 offset:20480
	ds_read_b128 v[232:235], v163 offset:21504
	ds_read_b128 v[236:239], v163 offset:22528
	ds_read_b128 v[240:243], v163 offset:23552
	global_load_lds_dwordx4 v132, s[2:3]
	s_mov_b32 m0, s34
	s_nop 0
	global_load_lds_dwordx4 v128, s[2:3]
	s_mov_b32 m0, s35
	s_nop 0
	global_load_lds_dwordx4 v132, s[56:57]
	s_mov_b32 m0, s36
	s_nop 0
	global_load_lds_dwordx4 v128, s[56:57]
	s_mov_b32 m0, s31
	s_nop 0
	global_load_lds_dwordx4 v134, s[4:5]
	s_mov_b32 m0, s37
	s_nop 0
	global_load_lds_dwordx4 v130, s[4:5]
	s_waitcnt vmcnt(8)
	s_waitcnt lgkmcnt(0)
	s_barrier
	s_setprio 1
	v_mfma_f32_16x16x32_bf16 v[60:63], v[140:143], v[212:215], 0
	v_mfma_f32_16x16x32_bf16 v[60:63], v[166:169], v[216:219], v[60:63]
	v_mfma_f32_16x16x32_bf16 v[44:47], v[140:143], v[220:223], 0
	v_mfma_f32_16x16x32_bf16 v[44:47], v[166:169], v[224:227], v[44:47]
	v_mfma_f32_16x16x32_bf16 v[28:31], v[140:143], v[228:231], 0
	v_mfma_f32_16x16x32_bf16 v[28:31], v[166:169], v[232:235], v[28:31]
	v_mfma_f32_16x16x32_bf16 v[12:15], v[140:143], v[236:239], 0
	v_mfma_f32_16x16x32_bf16 v[12:15], v[166:169], v[240:243], v[12:15]
	v_mfma_f32_16x16x32_bf16 v[56:59], v[170:173], v[212:215], 0
	v_mfma_f32_16x16x32_bf16 v[56:59], v[174:177], v[216:219], v[56:59]
	v_mfma_f32_16x16x32_bf16 v[40:43], v[170:173], v[220:223], 0
	v_mfma_f32_16x16x32_bf16 v[40:43], v[174:177], v[224:227], v[40:43]
	v_mfma_f32_16x16x32_bf16 v[24:27], v[170:173], v[228:231], 0
	v_mfma_f32_16x16x32_bf16 v[24:27], v[174:177], v[232:235], v[24:27]
	v_mfma_f32_16x16x32_bf16 v[8:11], v[170:173], v[236:239], 0
	v_mfma_f32_16x16x32_bf16 v[8:11], v[174:177], v[240:243], v[8:11]
	v_mfma_f32_16x16x32_bf16 v[52:55], v[178:181], v[212:215], 0
	v_mfma_f32_16x16x32_bf16 v[52:55], v[182:185], v[216:219], v[52:55]
	v_mfma_f32_16x16x32_bf16 v[36:39], v[178:181], v[220:223], 0
	v_mfma_f32_16x16x32_bf16 v[36:39], v[182:185], v[224:227], v[36:39]
	v_mfma_f32_16x16x32_bf16 v[20:23], v[178:181], v[228:231], 0
	v_mfma_f32_16x16x32_bf16 v[20:23], v[182:185], v[232:235], v[20:23]
	v_mfma_f32_16x16x32_bf16 v[4:7], v[178:181], v[236:239], 0
	v_mfma_f32_16x16x32_bf16 v[4:7], v[182:185], v[240:243], v[4:7]
	v_mfma_f32_16x16x32_bf16 v[48:51], v[186:189], v[212:215], 0
	v_mfma_f32_16x16x32_bf16 v[48:51], v[244:247], v[216:219], v[48:51]
	v_mfma_f32_16x16x32_bf16 v[32:35], v[186:189], v[220:223], 0
	v_mfma_f32_16x16x32_bf16 v[32:35], v[244:247], v[224:227], v[32:35]
	v_mfma_f32_16x16x32_bf16 v[16:19], v[186:189], v[228:231], 0
	v_mfma_f32_16x16x32_bf16 v[16:19], v[244:247], v[232:235], v[16:19]
	v_mfma_f32_16x16x32_bf16 v[0:3], v[186:189], v[236:239], 0
	v_mfma_f32_16x16x32_bf16 v[0:3], v[244:247], v[240:243], v[0:3]
	s_setprio 0
	s_barrier
; #define PG8_STAGE(bufoff, gbase, voff) do { _Pragma("unroll") for (int _i = 0; _i < 2; ++_i) \
;         __builtin_amdgcn_global_load_lds((const unsigned*)((const char*)(gbase) + (voff)[_i]), (PG8_LAS unsigned*)(lds + (bufoff) + ldsw + _i * 8192), 16, 0, 0); } while (0)
; #define PG8_LDA(dst, b, h) do { _Pragma("unroll") for (int m = 0; m < 4; ++m) _Pragma("unroll") for (int k = 0; k < 2; ++k) dst[m][k] = *(const PG8_LAS bf16x8*)(lds + PG8_SA(b, h) + aoff + m * 2048 + k * 1024); } while (0)
; #define PG8_LDB(dst, b, h) do { _Pragma("unroll") for (int n = 0; n < 2; ++n) _Pragma("unroll") for (int k = 0; k < 2; ++k) dst[n][k] = *(const PG8_LAS bf16x8*)(lds + PG8_SB(b, h) + boff + n * 2048 + k * 1024); } while (0)
; #define PG8_MMA(ai, bj, At, Bt) do { __builtin_amdgcn_s_setprio(1); _Pragma("unroll") for (int m = 0; m < 4; ++m) _Pragma("unroll") for (int n = 0; n < 2; ++n) _Pragma("unroll") for (int k = 0; k < 2; ++k) \
;         acc[ai][bj][m][n] = __builtin_amdgcn_mfma_f32_16x16x32_bf16(Bt[n][k], At[m][k], acc[ai][bj][m][n], 0, 0, 0); __builtin_amdgcn_s_setprio(0); } while (0)
; #define PG8_WAIT_V(n) asm volatile("s_waitcnt vmcnt(" #n ")" ::: "memory")
; #define PG8_WAIT_L(n) asm volatile("s_waitcnt lgkmcnt(" #n ")" ::: "memory")
; #define PG8_BAR __builtin_amdgcn_s_barrier()
; #define PG8_SCHED __builtin_amdgcn_sched_barrier(0)
; template <class Epi, class Sched, bool ALIGN_EPI = false, bool SP2 = false>
; __device__ __forceinline__ void gemm_phase(PG8_LAS unsigned char* lds, const Gemm g, const Sched& S, const Epi& E) {
;     ...
;             PG8_LDB(B0, 1, 0); PG8_LDB(B1, 1, 1); PG8_SCHED; PG8_LDA(At, 1, 0); PG8_STAGE(PG8_SA(0, 1), a2 + hstep, voffA);
;             PG8_WAIT_V(8); PG8_WAIT_L(0); PG8_BAR; PG8_MMA(0, 0, At, B0); PG8_MMA(0, 1, At, B1); PG8_BAR; PG8_SCHED;
;             PG8_LDA(At, 1, 1); PG8_STAGE(PG8_SB(1, 0), b3, voffB); PG8_STAGE(PG8_SB(1, 1), b3 + hstep, voffB); PG8_STAGE(PG8_SA(1, 0), a3, voffA);
;             PG8_WAIT_V(8); PG8_WAIT_L(0); PG8_BAR; PG8_MMA(1, 0, At, B0); PG8_MMA(1, 1, At, B1); PG8_BAR; PG8_SCHED;
	ds_read_b128 v[140:143], v254 offset:32768
	ds_read_b128 v[166:169], v254 offset:33792
	ds_read_b128 v[170:173], v254 offset:34816
	ds_read_b128 v[174:177], v254 offset:35840
	ds_read_b128 v[178:181], v254 offset:49152
	ds_read_b128 v[182:185], v254 offset:50176
	ds_read_b128 v[186:189], v254 offset:51200
	ds_read_b128 v[244:247], v254 offset:52224
	s_add_u32 s4, s4, 0x40000
	s_addc_u32 s5, s5, 0
	s_mov_b32 m0, s38
	ds_read_b128 v[212:215], v163 offset:32768
	ds_read_b128 v[216:219], v163 offset:33792
	ds_read_b128 v[220:223], v163 offset:34816
	ds_read_b128 v[224:227], v163 offset:35840
	ds_read_b128 v[228:231], v163 offset:36864
	ds_read_b128 v[232:235], v163 offset:37888
	ds_read_b128 v[236:239], v163 offset:38912
	ds_read_b128 v[240:243], v163 offset:39936
	global_load_lds_dwordx4 v134, s[4:5]
	s_mov_b32 m0, s39
	s_nop 0
	global_load_lds_dwordx4 v130, s[4:5]
	s_waitcnt vmcnt(8)
	s_waitcnt lgkmcnt(0)
	s_barrier
	s_setprio 1
	v_mfma_f32_16x16x32_bf16 v[124:127], v[140:143], v[212:215], v[124:127]
	v_mfma_f32_16x16x32_bf16 v[124:127], v[166:169], v[216:219], v[124:127]
	v_mfma_f32_16x16x32_bf16 v[108:111], v[140:143], v[220:223], v[108:111]
	v_mfma_f32_16x16x32_bf16 v[108:111], v[166:169], v[224:227], v[108:111]
	v_mfma_f32_16x16x32_bf16 v[92:95], v[140:143], v[228:231], v[92:95]
	v_mfma_f32_16x16x32_bf16 v[92:95], v[166:169], v[232:235], v[92:95]
	v_mfma_f32_16x16x32_bf16 v[76:79], v[140:143], v[236:239], v[76:79]
	v_mfma_f32_16x16x32_bf16 v[76:79], v[166:169], v[240:243], v[76:79]
	v_mfma_f32_16x16x32_bf16 v[120:123], v[170:173], v[212:215], v[120:123]
	v_mfma_f32_16x16x32_bf16 v[120:123], v[174:177], v[216:219], v[120:123]
	v_mfma_f32_16x16x32_bf16 v[104:107], v[170:173], v[220:223], v[104:107]
	v_mfma_f32_16x16x32_bf16 v[104:107], v[174:177], v[224:227], v[104:107]
	v_mfma_f32_16x16x32_bf16 v[88:91], v[170:173], v[228:231], v[88:91]
	v_mfma_f32_16x16x32_bf16 v[88:91], v[174:177], v[232:235], v[88:91]
	v_mfma_f32_16x16x32_bf16 v[72:75], v[170:173], v[236:239], v[72:75]
	v_mfma_f32_16x16x32_bf16 v[72:75], v[174:177], v[240:243], v[72:75]
	v_mfma_f32_16x16x32_bf16 v[116:119], v[178:181], v[212:215], v[116:119]
	v_mfma_f32_16x16x32_bf16 v[116:119], v[182:185], v[216:219], v[116:119]
	v_mfma_f32_16x16x32_bf16 v[100:103], v[178:181], v[220:223], v[100:103]
	v_mfma_f32_16x16x32_bf16 v[100:103], v[182:185], v[224:227], v[100:103]
	v_mfma_f32_16x16x32_bf16 v[84:87], v[178:181], v[228:231], v[84:87]
	v_mfma_f32_16x16x32_bf16 v[84:87], v[182:185], v[232:235], v[84:87]
	v_mfma_f32_16x16x32_bf16 v[68:71], v[178:181], v[236:239], v[68:71]
	v_mfma_f32_16x16x32_bf16 v[68:71], v[182:185], v[240:243], v[68:71]
	v_mfma_f32_16x16x32_bf16 v[112:115], v[186:189], v[212:215], v[112:115]
	v_mfma_f32_16x16x32_bf16 v[112:115], v[244:247], v[216:219], v[112:115]
	v_mfma_f32_16x16x32_bf16 v[96:99], v[186:189], v[220:223], v[96:99]
	v_mfma_f32_16x16x32_bf16 v[96:99], v[244:247], v[224:227], v[96:99]
	v_mfma_f32_16x16x32_bf16 v[80:83], v[186:189], v[228:231], v[80:83]
	v_mfma_f32_16x16x32_bf16 v[80:83], v[244:247], v[232:235], v[80:83]
	v_mfma_f32_16x16x32_bf16 v[64:67], v[186:189], v[236:239], v[64:67]
	v_mfma_f32_16x16x32_bf16 v[64:67], v[244:247], v[240:243], v[64:67]
	s_setprio 0
	s_barrier
	s_mov_b32 m0, s43
	s_add_u32 s2, s2, 0x40080
	s_addc_u32 s3, s3, 0
	ds_read_b128 v[212:215], v163 offset:49152
	ds_read_b128 v[216:219], v163 offset:50176
	ds_read_b128 v[220:223], v163 offset:51200
	ds_read_b128 v[224:227], v163 offset:52224
	ds_read_b128 v[228:231], v163 offset:53248
	ds_read_b128 v[232:235], v163 offset:54272
	ds_read_b128 v[236:239], v163 offset:55296
	ds_read_b128 v[240:243], v163 offset:56320
	s_add_u32 s98, s2, 0xfffc0000
	s_addc_u32 s99, s3, -1
	global_load_lds_dwordx4 v132, s[98:99]
	s_mov_b32 m0, s44
	s_nop 0
	global_load_lds_dwordx4 v128, s[98:99]
	s_mov_b32 m0, s48
	s_nop 0
	global_load_lds_dwordx4 v132, s[2:3]
	s_mov_b32 m0, s49
	s_nop 0
	global_load_lds_dwordx4 v128, s[2:3]
	s_mov_b32 m0, s45
	s_nop 0
	s_add_u32 s100, s4, 0xfffc0080
	s_addc_u32 s101, s5, -1
	global_load_lds_dwordx4 v134, s[100:101]
	s_mov_b32 m0, s47
	s_nop 0
	global_load_lds_dwordx4 v130, s[100:101]
	s_waitcnt vmcnt(8)
	s_waitcnt lgkmcnt(0)
	s_barrier
	s_setprio 1
	v_mfma_f32_16x16x32_bf16 v[60:63], v[140:143], v[212:215], v[60:63]
	v_mfma_f32_16x16x32_bf16 v[60:63], v[166:169], v[216:219], v[60:63]
	v_mfma_f32_16x16x32_bf16 v[44:47], v[140:143], v[220:223], v[44:47]
	v_mfma_f32_16x16x32_bf16 v[44:47], v[166:169], v[224:227], v[44:47]
	v_mfma_f32_16x16x32_bf16 v[28:31], v[140:143], v[228:231], v[28:31]
	v_mfma_f32_16x16x32_bf16 v[28:31], v[166:169], v[232:235], v[28:31]
	v_mfma_f32_16x16x32_bf16 v[12:15], v[140:143], v[236:239], v[12:15]
	v_mfma_f32_16x16x32_bf16 v[12:15], v[166:169], v[240:243], v[12:15]
	v_mfma_f32_16x16x32_bf16 v[56:59], v[170:173], v[212:215], v[56:59]
	v_mfma_f32_16x16x32_bf16 v[56:59], v[174:177], v[216:219], v[56:59]
	v_mfma_f32_16x16x32_bf16 v[40:43], v[170:173], v[220:223], v[40:43]
	v_mfma_f32_16x16x32_bf16 v[40:43], v[174:177], v[224:227], v[40:43]
	v_mfma_f32_16x16x32_bf16 v[24:27], v[170:173], v[228:231], v[24:27]
	v_mfma_f32_16x16x32_bf16 v[24:27], v[174:177], v[232:235], v[24:27]
	v_mfma_f32_16x16x32_bf16 v[8:11], v[170:173], v[236:239], v[8:11]
	v_mfma_f32_16x16x32_bf16 v[8:11], v[174:177], v[240:243], v[8:11]
	v_mfma_f32_16x16x32_bf16 v[52:55], v[178:181], v[212:215], v[52:55]
	v_mfma_f32_16x16x32_bf16 v[52:55], v[182:185], v[216:219], v[52:55]
	v_mfma_f32_16x16x32_bf16 v[36:39], v[178:181], v[220:223], v[36:39]
	v_mfma_f32_16x16x32_bf16 v[36:39], v[182:185], v[224:227], v[36:39]
	v_mfma_f32_16x16x32_bf16 v[20:23], v[178:181], v[228:231], v[20:23]
	v_mfma_f32_16x16x32_bf16 v[20:23], v[182:185], v[232:235], v[20:23]
	v_mfma_f32_16x16x32_bf16 v[4:7], v[178:181], v[236:239], v[4:7]
	v_mfma_f32_16x16x32_bf16 v[4:7], v[182:185], v[240:243], v[4:7]
	v_mfma_f32_16x16x32_bf16 v[48:51], v[186:189], v[212:215], v[48:51]
	v_mfma_f32_16x16x32_bf16 v[48:51], v[244:247], v[216:219], v[48:51]
	v_mfma_f32_16x16x32_bf16 v[32:35], v[186:189], v[220:223], v[32:35]
	v_mfma_f32_16x16x32_bf16 v[32:35], v[244:247], v[224:227], v[32:35]
	v_mfma_f32_16x16x32_bf16 v[16:19], v[186:189], v[228:231], v[16:19]
	v_mfma_f32_16x16x32_bf16 v[16:19], v[244:247], v[232:235], v[16:19]
	v_mfma_f32_16x16x32_bf16 v[0:3], v[186:189], v[236:239], v[0:3]
	v_mfma_f32_16x16x32_bf16 v[0:3], v[244:247], v[240:243], v[0:3]
	s_setprio 0
	s_barrier
	s_add_i32 s55, s55, 2
	s_add_u32 s0, s0, 0x100
	s_addc_u32 s1, s1, 0
	s_add_u32 s53, s53, 0x100
	s_addc_u32 s54, s54, 0
	s_cmp_gt_u32 s55, 13
; #define PG8_STAGE(bufoff, gbase, voff) do { _Pragma("unroll") for (int _i = 0; _i < 2; ++_i) \
;         __builtin_amdgcn_global_load_lds((const unsigned*)((const char*)(gbase) + (voff)[_i]), (PG8_LAS unsigned*)(lds + (bufoff) + ldsw + _i * 8192), 16, 0, 0); } while (0)
; #define PG8_LDA(dst, b, h) do { _Pragma("unroll") for (int m = 0; m < 4; ++m) _Pragma("unroll") for (int k = 0; k < 2; ++k) dst[m][k] = *(const PG8_LAS bf16x8*)(lds + PG8_SA(b, h) + aoff + m * 2048 + k * 1024); } while (0)
; #define PG8_LDB(dst, b, h) do { _Pragma("unroll") for (int n = 0; n < 2; ++n) _Pragma("unroll") for (int k = 0; k < 2; ++k) dst[n][k] = *(const PG8_LAS bf16x8*)(lds + PG8_SB(b, h) + boff + n * 2048 + k * 1024); } while (0)
; #define PG8_MMA(ai, bj, At, Bt) do { __builtin_amdgcn_s_setprio(1); _Pragma("unroll") for (int m = 0; m < 4; ++m) _Pragma("unroll") for (int n = 0; n < 2; ++n) _Pragma("unroll") for (int k = 0; k < 2; ++k) \
;         acc[ai][bj][m][n] = __builtin_amdgcn_mfma_f32_16x16x32_bf16(Bt[n][k], At[m][k], acc[ai][bj][m][n], 0, 0, 0); __builtin_amdgcn_s_setprio(0); } while (0)
; #define PG8_WAIT_V(n) asm volatile("s_waitcnt vmcnt(" #n ")" ::: "memory")
; #define PG8_BAR __builtin_amdgcn_s_barrier()
; template <class Epi, class Sched, bool ALIGN_EPI = false, bool SP2 = false>
; __device__ __forceinline__ void gemm_phase(PG8_LAS unsigned char* lds, const Gemm g, const Sched& S, const Epi& E) {
;     ...
;         for (int t = 0; t < nt; t += 2) {
;             const bool last = (t == nt - 2);
;             const char* a1 = cA + (size_t)(t + 1) * kstep;
;             const char* a2 = last ? nA : cA + (size_t)(t + 2) * kstep; const char* b2 = last ? nB : cB + (size_t)(t + 2) * kstep;
;             const char* a3 = a2 + kstep; const char* b3 = b2 + kstep;
;             if (last && has_next) S.a_ready(nxt);
;             if constexpr (SP2) {
;             PG8_LDB(B0, 0, 0); PG8_LDB(B1, 0, 1); PG8_SCHED; PG8_LDA(At, 0, 0); PG8_STAGE(PG8_SA(1, 1), a1 + hstep, voffA);
;             PG8_WAIT_V(8); PG8_WAIT_L(0); PG8_BAR; PG8_MMA(0, 0, At, B0); PG8_MMA(0, 1, At, B1); PG8_BAR; PG8_SCHED;
;             PG8_LDA(At, 0, 1); PG8_STAGE(PG8_SB(0, 0), b2, voffB); PG8_STAGE(PG8_SB(0, 1), b2 + hstep, voffB); PG8_STAGE(PG8_SA(0, 0), a2, voffA);
;             PG8_WAIT_V(8); PG8_WAIT_L(0); PG8_BAR; PG8_MMA(1, 0, At, B0); PG8_MMA(1, 1, At, B1); PG8_BAR; PG8_SCHED;
.LBB0_1042:
	ds_read_b128 v[140:143], v254
	ds_read_b128 v[166:169], v254 offset:1024
	ds_read_b128 v[170:173], v254 offset:2048
	ds_read_b128 v[174:177], v254 offset:3072
	ds_read_b128 v[178:181], v254 offset:16384
	ds_read_b128 v[182:185], v254 offset:17408
	ds_read_b128 v[186:189], v254 offset:18432
	ds_read_b128 v[244:247], v254 offset:19456
	s_add_u32 s2, s0, 0xfffc0080
	s_addc_u32 s3, s1, -1
	s_cmp_eq_u32 s55, 12
	s_cselect_b32 s5, s23, s3
	s_cselect_b32 s4, s51, s2
	s_cselect_b32 s3, s21, s54
	s_cselect_b32 s2, s52, s53
	s_add_i32 m0, s31, 0xc000
	ds_read_b128 v[212:215], v163
	ds_read_b128 v[216:219], v163 offset:1024
	ds_read_b128 v[220:223], v163 offset:2048
	ds_read_b128 v[224:227], v163 offset:3072
	ds_read_b128 v[228:231], v163 offset:4096
	ds_read_b128 v[232:235], v163 offset:5120
	ds_read_b128 v[236:239], v163 offset:6144
	ds_read_b128 v[240:243], v163 offset:7168
	global_load_lds_dwordx4 v136, s[0:1]
	s_add_i32 m0, s31, 0xe000
	s_nop 0
	global_load_lds_dwordx4 v138, s[0:1]
	s_waitcnt vmcnt(8)
	s_waitcnt lgkmcnt(0)
	s_barrier
	s_setprio 1
	v_mfma_f32_16x16x32_bf16 v[124:127], v[140:143], v[212:215], v[124:127]
	v_mfma_f32_16x16x32_bf16 v[124:127], v[166:169], v[216:219], v[124:127]
	v_mfma_f32_16x16x32_bf16 v[108:111], v[140:143], v[220:223], v[108:111]
	v_mfma_f32_16x16x32_bf16 v[108:111], v[166:169], v[224:227], v[108:111]
	v_mfma_f32_16x16x32_bf16 v[92:95], v[140:143], v[228:231], v[92:95]
	v_mfma_f32_16x16x32_bf16 v[92:95], v[166:169], v[232:235], v[92:95]
	v_mfma_f32_16x16x32_bf16 v[76:79], v[140:143], v[236:239], v[76:79]
	v_mfma_f32_16x16x32_bf16 v[76:79], v[166:169], v[240:243], v[76:79]
	v_mfma_f32_16x16x32_bf16 v[120:123], v[170:173], v[212:215], v[120:123]
	v_mfma_f32_16x16x32_bf16 v[120:123], v[174:177], v[216:219], v[120:123]
	v_mfma_f32_16x16x32_bf16 v[104:107], v[170:173], v[220:223], v[104:107]
	v_mfma_f32_16x16x32_bf16 v[104:107], v[174:177], v[224:227], v[104:107]
	v_mfma_f32_16x16x32_bf16 v[88:91], v[170:173], v[228:231], v[88:91]
	v_mfma_f32_16x16x32_bf16 v[88:91], v[174:177], v[232:235], v[88:91]
	v_mfma_f32_16x16x32_bf16 v[72:75], v[170:173], v[236:239], v[72:75]
	v_mfma_f32_16x16x32_bf16 v[72:75], v[174:177], v[240:243], v[72:75]
	v_mfma_f32_16x16x32_bf16 v[116:119], v[178:181], v[212:215], v[116:119]
	v_mfma_f32_16x16x32_bf16 v[116:119], v[182:185], v[216:219], v[116:119]
	v_mfma_f32_16x16x32_bf16 v[100:103], v[178:181], v[220:223], v[100:103]
	v_mfma_f32_16x16x32_bf16 v[100:103], v[182:185], v[224:227], v[100:103]
	v_mfma_f32_16x16x32_bf16 v[84:87], v[178:181], v[228:231], v[84:87]
	v_mfma_f32_16x16x32_bf16 v[84:87], v[182:185], v[232:235], v[84:87]
	v_mfma_f32_16x16x32_bf16 v[68:71], v[178:181], v[236:239], v[68:71]
	v_mfma_f32_16x16x32_bf16 v[68:71], v[182:185], v[240:243], v[68:71]
	v_mfma_f32_16x16x32_bf16 v[112:115], v[186:189], v[212:215], v[112:115]
	v_mfma_f32_16x16x32_bf16 v[112:115], v[244:247], v[216:219], v[112:115]
	v_mfma_f32_16x16x32_bf16 v[96:99], v[186:189], v[220:223], v[96:99]
	v_mfma_f32_16x16x32_bf16 v[96:99], v[244:247], v[224:227], v[96:99]
	v_mfma_f32_16x16x32_bf16 v[80:83], v[186:189], v[228:231], v[80:83]
	v_mfma_f32_16x16x32_bf16 v[80:83], v[244:247], v[232:235], v[80:83]
	v_mfma_f32_16x16x32_bf16 v[64:67], v[186:189], v[236:239], v[64:67]
	v_mfma_f32_16x16x32_bf16 v[64:67], v[244:247], v[240:243], v[64:67]
	s_setprio 0
	s_barrier
	s_mov_b32 m0, s33
	s_add_u32 s56, s2, 0x40000
	s_addc_u32 s57, s3, 0
	ds_read_b128 v[212:215], v163 offset:16384
	ds_read_b128 v[216:219], v163 offset:17408
	ds_read_b128 v[220:223], v163 offset:18432
	ds_read_b128 v[224:227], v163 offset:19456
	ds_read_b128 v[228:231], v163 offset:20480
	ds_read_b128 v[232:235], v163 offset:21504
	ds_read_b128 v[236:239], v163 offset:22528
	ds_read_b128 v[240:243], v163 offset:23552
	global_load_lds_dwordx4 v132, s[2:3]
	s_mov_b32 m0, s34
	s_nop 0
	global_load_lds_dwordx4 v128, s[2:3]
	s_mov_b32 m0, s35
	s_nop 0
	global_load_lds_dwordx4 v132, s[56:57]
	s_mov_b32 m0, s36
	s_nop 0
	global_load_lds_dwordx4 v128, s[56:57]
	s_mov_b32 m0, s31
	s_nop 0
	global_load_lds_dwordx4 v134, s[4:5]
	s_mov_b32 m0, s37
	s_nop 0
	global_load_lds_dwordx4 v130, s[4:5]
	s_waitcnt vmcnt(8)
	s_waitcnt lgkmcnt(0)
	s_barrier
	s_setprio 1
	v_mfma_f32_16x16x32_bf16 v[60:63], v[140:143], v[212:215], v[60:63]
	v_mfma_f32_16x16x32_bf16 v[60:63], v[166:169], v[216:219], v[60:63]
	v_mfma_f32_16x16x32_bf16 v[44:47], v[140:143], v[220:223], v[44:47]
	v_mfma_f32_16x16x32_bf16 v[44:47], v[166:169], v[224:227], v[44:47]
	v_mfma_f32_16x16x32_bf16 v[28:31], v[140:143], v[228:231], v[28:31]
	v_mfma_f32_16x16x32_bf16 v[28:31], v[166:169], v[232:235], v[28:31]
	v_mfma_f32_16x16x32_bf16 v[12:15], v[140:143], v[236:239], v[12:15]
	v_mfma_f32_16x16x32_bf16 v[12:15], v[166:169], v[240:243], v[12:15]
	v_mfma_f32_16x16x32_bf16 v[56:59], v[170:173], v[212:215], v[56:59]
	v_mfma_f32_16x16x32_bf16 v[56:59], v[174:177], v[216:219], v[56:59]
	v_mfma_f32_16x16x32_bf16 v[40:43], v[170:173], v[220:223], v[40:43]
	v_mfma_f32_16x16x32_bf16 v[40:43], v[174:177], v[224:227], v[40:43]
	v_mfma_f32_16x16x32_bf16 v[24:27], v[170:173], v[228:231], v[24:27]
	v_mfma_f32_16x16x32_bf16 v[24:27], v[174:177], v[232:235], v[24:27]
	v_mfma_f32_16x16x32_bf16 v[8:11], v[170:173], v[236:239], v[8:11]
	v_mfma_f32_16x16x32_bf16 v[8:11], v[174:177], v[240:243], v[8:11]
	v_mfma_f32_16x16x32_bf16 v[52:55], v[178:181], v[212:215], v[52:55]
	v_mfma_f32_16x16x32_bf16 v[52:55], v[182:185], v[216:219], v[52:55]
	v_mfma_f32_16x16x32_bf16 v[36:39], v[178:181], v[220:223], v[36:39]
	v_mfma_f32_16x16x32_bf16 v[36:39], v[182:185], v[224:227], v[36:39]
	v_mfma_f32_16x16x32_bf16 v[20:23], v[178:181], v[228:231], v[20:23]
	v_mfma_f32_16x16x32_bf16 v[20:23], v[182:185], v[232:235], v[20:23]
	v_mfma_f32_16x16x32_bf16 v[4:7], v[178:181], v[236:239], v[4:7]
	v_mfma_f32_16x16x32_bf16 v[4:7], v[182:185], v[240:243], v[4:7]
	v_mfma_f32_16x16x32_bf16 v[48:51], v[186:189], v[212:215], v[48:51]
	v_mfma_f32_16x16x32_bf16 v[48:51], v[244:247], v[216:219], v[48:51]
	v_mfma_f32_16x16x32_bf16 v[32:35], v[186:189], v[220:223], v[32:35]
	v_mfma_f32_16x16x32_bf16 v[32:35], v[244:247], v[224:227], v[32:35]
	v_mfma_f32_16x16x32_bf16 v[16:19], v[186:189], v[228:231], v[16:19]
	v_mfma_f32_16x16x32_bf16 v[16:19], v[244:247], v[232:235], v[16:19]
	v_mfma_f32_16x16x32_bf16 v[0:3], v[186:189], v[236:239], v[0:3]
	v_mfma_f32_16x16x32_bf16 v[0:3], v[244:247], v[240:243], v[0:3]
	s_setprio 0
	s_barrier
; #define PG8_STAGE(bufoff, gbase, voff) do { _Pragma("unroll") for (int _i = 0; _i < 2; ++_i) \
;         __builtin_amdgcn_global_load_lds((const unsigned*)((const char*)(gbase) + (voff)[_i]), (PG8_LAS unsigned*)(lds + (bufoff) + ldsw + _i * 8192), 16, 0, 0); } while (0)
; #define PG8_LDA(dst, b, h) do { _Pragma("unroll") for (int m = 0; m < 4; ++m) _Pragma("unroll") for (int k = 0; k < 2; ++k) dst[m][k] = *(const PG8_LAS bf16x8*)(lds + PG8_SA(b, h) + aoff + m * 2048 + k * 1024); } while (0)
; #define PG8_LDB(dst, b, h) do { _Pragma("unroll") for (int n = 0; n < 2; ++n) _Pragma("unroll") for (int k = 0; k < 2; ++k) dst[n][k] = *(const PG8_LAS bf16x8*)(lds + PG8_SB(b, h) + boff + n * 2048 + k * 1024); } while (0)
; #define PG8_MMA(ai, bj, At, Bt) do { __builtin_amdgcn_s_setprio(1); _Pragma("unroll") for (int m = 0; m < 4; ++m) _Pragma("unroll") for (int n = 0; n < 2; ++n) _Pragma("unroll") for (int k = 0; k < 2; ++k) \
;         acc[ai][bj][m][n] = __builtin_amdgcn_mfma_f32_16x16x32_bf16(Bt[n][k], At[m][k], acc[ai][bj][m][n], 0, 0, 0); __builtin_amdgcn_s_setprio(0); } while (0)
; #define PG8_WAIT_V(n) asm volatile("s_waitcnt vmcnt(" #n ")" ::: "memory")
; #define PG8_WAIT_L(n) asm volatile("s_waitcnt lgkmcnt(" #n ")" ::: "memory")
; #define PG8_BAR __builtin_amdgcn_s_barrier()
; #define PG8_SCHED __builtin_amdgcn_sched_barrier(0)
; template <class Epi, class Sched, bool ALIGN_EPI = false, bool SP2 = false>
; __device__ __forceinline__ void gemm_phase(PG8_LAS unsigned char* lds, const Gemm g, const Sched& S, const Epi& E) {
;     ...
;             PG8_LDB(B0, 1, 0); PG8_LDB(B1, 1, 1); PG8_SCHED; PG8_LDA(At, 1, 0); PG8_STAGE(PG8_SA(0, 1), a2 + hstep, voffA);
;             PG8_WAIT_V(8); PG8_WAIT_L(0); PG8_BAR; PG8_MMA(0, 0, At, B0); PG8_MMA(0, 1, At, B1); PG8_BAR; PG8_SCHED;
;             PG8_LDA(At, 1, 1); PG8_STAGE(PG8_SB(1, 0), b3, voffB); PG8_STAGE(PG8_SB(1, 1), b3 + hstep, voffB); PG8_STAGE(PG8_SA(1, 0), a3, voffA);
;             PG8_WAIT_V(8); PG8_WAIT_L(0); PG8_BAR; PG8_MMA(1, 0, At, B0); PG8_MMA(1, 1, At, B1); PG8_BAR; PG8_SCHED;
;     ...
;         if constexpr (ALIGN_EPI) { if (wr == 0) PG8_BAR; }
	ds_read_b128 v[140:143], v254 offset:32768
	ds_read_b128 v[166:169], v254 offset:33792
	ds_read_b128 v[170:173], v254 offset:34816
	ds_read_b128 v[174:177], v254 offset:35840
	ds_read_b128 v[178:181], v254 offset:49152
	ds_read_b128 v[182:185], v254 offset:50176
	ds_read_b128 v[186:189], v254 offset:51200
	ds_read_b128 v[244:247], v254 offset:52224
	s_add_u32 s4, s4, 0x40000
	s_addc_u32 s5, s5, 0
	s_mov_b32 m0, s38
	ds_read_b128 v[212:215], v163 offset:32768
	ds_read_b128 v[216:219], v163 offset:33792
	ds_read_b128 v[220:223], v163 offset:34816
	ds_read_b128 v[224:227], v163 offset:35840
	ds_read_b128 v[228:231], v163 offset:36864
	ds_read_b128 v[232:235], v163 offset:37888
	ds_read_b128 v[236:239], v163 offset:38912
	ds_read_b128 v[240:243], v163 offset:39936
	global_load_lds_dwordx4 v134, s[4:5]
	s_mov_b32 m0, s39
	s_nop 0
	global_load_lds_dwordx4 v130, s[4:5]
	s_waitcnt vmcnt(8)
	s_waitcnt lgkmcnt(0)
	s_barrier
	s_setprio 1
	v_mfma_f32_16x16x32_bf16 v[124:127], v[140:143], v[212:215], v[124:127]
	v_mfma_f32_16x16x32_bf16 v[124:127], v[166:169], v[216:219], v[124:127]
	v_mfma_f32_16x16x32_bf16 v[108:111], v[140:143], v[220:223], v[108:111]
	v_mfma_f32_16x16x32_bf16 v[108:111], v[166:169], v[224:227], v[108:111]
	v_mfma_f32_16x16x32_bf16 v[92:95], v[140:143], v[228:231], v[92:95]
	v_mfma_f32_16x16x32_bf16 v[92:95], v[166:169], v[232:235], v[92:95]
	v_mfma_f32_16x16x32_bf16 v[76:79], v[140:143], v[236:239], v[76:79]
	v_mfma_f32_16x16x32_bf16 v[76:79], v[166:169], v[240:243], v[76:79]
	v_mfma_f32_16x16x32_bf16 v[120:123], v[170:173], v[212:215], v[120:123]
	v_mfma_f32_16x16x32_bf16 v[120:123], v[174:177], v[216:219], v[120:123]
	v_mfma_f32_16x16x32_bf16 v[104:107], v[170:173], v[220:223], v[104:107]
	v_mfma_f32_16x16x32_bf16 v[104:107], v[174:177], v[224:227], v[104:107]
	v_mfma_f32_16x16x32_bf16 v[88:91], v[170:173], v[228:231], v[88:91]
	v_mfma_f32_16x16x32_bf16 v[88:91], v[174:177], v[232:235], v[88:91]
	v_mfma_f32_16x16x32_bf16 v[72:75], v[170:173], v[236:239], v[72:75]
	v_mfma_f32_16x16x32_bf16 v[72:75], v[174:177], v[240:243], v[72:75]
	v_mfma_f32_16x16x32_bf16 v[116:119], v[178:181], v[212:215], v[116:119]
	v_mfma_f32_16x16x32_bf16 v[116:119], v[182:185], v[216:219], v[116:119]
	v_mfma_f32_16x16x32_bf16 v[100:103], v[178:181], v[220:223], v[100:103]
	v_mfma_f32_16x16x32_bf16 v[100:103], v[182:185], v[224:227], v[100:103]
	v_mfma_f32_16x16x32_bf16 v[84:87], v[178:181], v[228:231], v[84:87]
	v_mfma_f32_16x16x32_bf16 v[84:87], v[182:185], v[232:235], v[84:87]
	v_mfma_f32_16x16x32_bf16 v[68:71], v[178:181], v[236:239], v[68:71]
	v_mfma_f32_16x16x32_bf16 v[68:71], v[182:185], v[240:243], v[68:71]
	v_mfma_f32_16x16x32_bf16 v[112:115], v[186:189], v[212:215], v[112:115]
	v_mfma_f32_16x16x32_bf16 v[112:115], v[244:247], v[216:219], v[112:115]
	v_mfma_f32_16x16x32_bf16 v[96:99], v[186:189], v[220:223], v[96:99]
	v_mfma_f32_16x16x32_bf16 v[96:99], v[244:247], v[224:227], v[96:99]
	v_mfma_f32_16x16x32_bf16 v[80:83], v[186:189], v[228:231], v[80:83]
	v_mfma_f32_16x16x32_bf16 v[80:83], v[244:247], v[232:235], v[80:83]
	v_mfma_f32_16x16x32_bf16 v[64:67], v[186:189], v[236:239], v[64:67]
	v_mfma_f32_16x16x32_bf16 v[64:67], v[244:247], v[240:243], v[64:67]
	s_setprio 0
	s_barrier
	s_mov_b32 m0, s43
	s_add_u32 s2, s2, 0x40080
	s_addc_u32 s3, s3, 0
	ds_read_b128 v[212:215], v163 offset:49152
	ds_read_b128 v[216:219], v163 offset:50176
	ds_read_b128 v[220:223], v163 offset:51200
	ds_read_b128 v[224:227], v163 offset:52224
	ds_read_b128 v[228:231], v163 offset:53248
	ds_read_b128 v[232:235], v163 offset:54272
	ds_read_b128 v[236:239], v163 offset:55296
	ds_read_b128 v[240:243], v163 offset:56320
	s_add_u32 s98, s2, 0xfffc0000
	s_addc_u32 s99, s3, -1
	global_load_lds_dwordx4 v132, s[98:99]
	s_mov_b32 m0, s44
	s_nop 0
	global_load_lds_dwordx4 v128, s[98:99]
	s_mov_b32 m0, s48
	s_nop 0
	global_load_lds_dwordx4 v132, s[2:3]
	s_mov_b32 m0, s49
	s_nop 0
	global_load_lds_dwordx4 v128, s[2:3]
	s_mov_b32 m0, s45
	s_nop 0
	s_add_u32 s100, s4, 0xfffc0080
	s_addc_u32 s101, s5, -1
	global_load_lds_dwordx4 v134, s[100:101]
	s_mov_b32 m0, s47
	s_nop 0
	global_load_lds_dwordx4 v130, s[100:101]
	s_waitcnt vmcnt(8)
	s_waitcnt lgkmcnt(0)
	s_barrier
	s_setprio 1
	v_mfma_f32_16x16x32_bf16 v[60:63], v[140:143], v[212:215], v[60:63]
	v_mfma_f32_16x16x32_bf16 v[60:63], v[166:169], v[216:219], v[60:63]
	v_mfma_f32_16x16x32_bf16 v[44:47], v[140:143], v[220:223], v[44:47]
	v_mfma_f32_16x16x32_bf16 v[44:47], v[166:169], v[224:227], v[44:47]
	v_mfma_f32_16x16x32_bf16 v[28:31], v[140:143], v[228:231], v[28:31]
	v_mfma_f32_16x16x32_bf16 v[28:31], v[166:169], v[232:235], v[28:31]
	v_mfma_f32_16x16x32_bf16 v[12:15], v[140:143], v[236:239], v[12:15]
	v_mfma_f32_16x16x32_bf16 v[12:15], v[166:169], v[240:243], v[12:15]
	v_mfma_f32_16x16x32_bf16 v[56:59], v[170:173], v[212:215], v[56:59]
	v_mfma_f32_16x16x32_bf16 v[56:59], v[174:177], v[216:219], v[56:59]
	v_mfma_f32_16x16x32_bf16 v[40:43], v[170:173], v[220:223], v[40:43]
	v_mfma_f32_16x16x32_bf16 v[40:43], v[174:177], v[224:227], v[40:43]
	v_mfma_f32_16x16x32_bf16 v[24:27], v[170:173], v[228:231], v[24:27]
	v_mfma_f32_16x16x32_bf16 v[24:27], v[174:177], v[232:235], v[24:27]
	v_mfma_f32_16x16x32_bf16 v[8:11], v[170:173], v[236:239], v[8:11]
	v_mfma_f32_16x16x32_bf16 v[8:11], v[174:177], v[240:243], v[8:11]
	v_mfma_f32_16x16x32_bf16 v[52:55], v[178:181], v[212:215], v[52:55]
	v_mfma_f32_16x16x32_bf16 v[52:55], v[182:185], v[216:219], v[52:55]
	v_mfma_f32_16x16x32_bf16 v[36:39], v[178:181], v[220:223], v[36:39]
	v_mfma_f32_16x16x32_bf16 v[36:39], v[182:185], v[224:227], v[36:39]
	v_mfma_f32_16x16x32_bf16 v[20:23], v[178:181], v[228:231], v[20:23]
	v_mfma_f32_16x16x32_bf16 v[20:23], v[182:185], v[232:235], v[20:23]
	v_mfma_f32_16x16x32_bf16 v[4:7], v[178:181], v[236:239], v[4:7]
	v_mfma_f32_16x16x32_bf16 v[4:7], v[182:185], v[240:243], v[4:7]
	v_mfma_f32_16x16x32_bf16 v[48:51], v[186:189], v[212:215], v[48:51]
	v_mfma_f32_16x16x32_bf16 v[48:51], v[244:247], v[216:219], v[48:51]
	v_mfma_f32_16x16x32_bf16 v[32:35], v[186:189], v[220:223], v[32:35]
	v_mfma_f32_16x16x32_bf16 v[32:35], v[244:247], v[224:227], v[32:35]
	v_mfma_f32_16x16x32_bf16 v[16:19], v[186:189], v[228:231], v[16:19]
	v_mfma_f32_16x16x32_bf16 v[16:19], v[244:247], v[232:235], v[16:19]
	v_mfma_f32_16x16x32_bf16 v[0:3], v[186:189], v[236:239], v[0:3]
	v_mfma_f32_16x16x32_bf16 v[0:3], v[244:247], v[240:243], v[0:3]
	s_setprio 0
	s_barrier
	s_add_i32 s55, s55, 2
	s_add_u32 s0, s0, 0x100
	s_addc_u32 s1, s1, 0
	s_add_u32 s53, s53, 0x100
	s_addc_u32 s54, s54, 0
	s_cmp_gt_u32 s55, 13
	s_cbranch_scc0 .LBB0_1042
	s_and_b64 vcc, exec, s[18:19]
	s_cbranch_vccz .LBB0_1045
	s_barrier
